# EpiConv VALU trim: sample-only context-load address math sunk into the load path, G-store row-group addresses by base+K*pitch instead of mad_i64, GELU constant pair hoisted to v[246:247]
# speedup vs baseline: 1.0007x; 1.0007x over previous
; template <int N> __device__ __forceinline__ float dpp_ror(float v) { const int i = __builtin_bit_cast(int, v); return __builtin_bit_cast(float, __builtin_amdgcn_update_dpp(i, i, 0x120 + N, 0xF, 0xF, false)); }
;     __device__ __forceinline__ void operator()(const f32x4 (&acc)[2][2][4][2], const pg8::Unit& u, int wr, int wc, int fr, int fq, PG8_LAS unsigned char* xl) const {
;     ...
;                 for (int m = 0; m < 4; ++m) {
;                     const int row = pm * 256 + ai * 128 + wr * 64 + m * 16 + fr;
;                     f32x4 cc[2];
; #pragma unroll
;                     for (int bj = 0; bj < 2; ++bj) {
;                         const f32x4 cur = acc[ai][bj][m][n]; f32x4 p1, p2;
;                         if (!sample) { const f32x4 prv = (m == 0) ? hb[bj] : acc[ai][bj][m == 0 ? 0 : m - 1][n];
; #pragma unroll
;                             for (int j = 0; j < 4; ++j) { const float s1 = fr == 15 ? prv[j] : cur[j], s2 = fr >= 14 ? prv[j] : cur[j]; p1[j] = dpp_ror<1>(s1); p2[j] = dpp_ror<2>(s2); }
;                         } else { const int t = fr & 3, b = (row - MP) >> 2;
; #pragma unroll
;                             for (int j = 0; j < 4; ++j) { p1[j] = dpp_ror<1>(cur[j]); p2[j] = dpp_ror<2>(cur[j]); }
;                             const f32x4 c1 = *(const f32x4*)(ctx_s + (size_t)(b * 2 + 1) * FF2 + bj * FF + jc0 + 4 * n), c0 = *(const f32x4*)(ctx_s + (size_t)(b * 2) * FF2 + bj * FF + jc0 + 4 * n);
; #pragma unroll
;                             for (int j = 0; j < 4; ++j) { p2[j] = t == 0 ? c0[j] : (t == 1 ? c1[j] : p2[j]); p1[j] = t == 0 ? c1[j] : p1[j]; }
;                         }
.LBB0_557:
	s_or_b64 exec, exec, s[6:7]
	v_lshl_add_u32 v225, s42, 8, v212
	v_add_u32_e32 v164, 0xffffc000, v225
	v_ashrrev_i32_e32 v164, 1, v164
	v_and_b32_e32 v224, 0xffffffe6, v164
	s_mov_b64 s[6:7], -1
	s_and_b64 vcc, exec, s[34:35]
	s_cbranch_vccz .LBB0_559
	v_or_b32_e32 v166, 1, v164
	v_mov_b64_e32 v[164:165], s[40:41]
	v_mad_i64_i32 v[166:167], vcc, v166, s36, v[164:165]
	v_mad_i64_i32 v[164:165], vcc, v224, s36, v[164:165]
	v_lshl_add_u64 v[202:203], v[166:167], 0, v[198:199]
	v_lshl_add_u64 v[200:201], v[164:165], 0, v[198:199]
	global_load_dwordx4 v[164:167], v[202:203], off
	global_load_dwordx4 v[168:171], v[200:201], off
	v_mov_b32_e32 v176, v156
	v_mov_b32_e32 v177, v156
	v_mov_b32_e32 v178, v157
	v_mov_b32_e32 v179, v157
	v_mov_b32_e32 v227, v158
	v_mov_b32_e32 v229, v159
	v_mov_b32_e32 v226, v158
	v_mov_b32_e32 v228, v159
	v_mov_b32_dpp v176, v176 row_ror:1 row_mask:0xf bank_mask:0xf
	v_mov_b32_dpp v177, v177 row_ror:2 row_mask:0xf bank_mask:0xf
	v_mov_b32_dpp v178, v178 row_ror:1 row_mask:0xf bank_mask:0xf
	v_mov_b32_dpp v179, v179 row_ror:2 row_mask:0xf bank_mask:0xf
	v_mov_b32_dpp v227, v227 row_ror:2 row_mask:0xf bank_mask:0xf
	v_mov_b32_dpp v229, v229 row_ror:2 row_mask:0xf bank_mask:0xf
	v_mov_b32_dpp v226, v226 row_ror:1 row_mask:0xf bank_mask:0xf
	v_mov_b32_dpp v228, v228 row_ror:1 row_mask:0xf bank_mask:0xf
	s_mov_b64 s[6:7], 0
	s_waitcnt vmcnt(0)
	v_cndmask_b32_e64 v177, v177, v164, s[14:15]
	v_cndmask_b32_e64 v164, v176, v164, s[12:13]
	v_cndmask_b32_e64 v176, v179, v165, s[14:15]
	v_cndmask_b32_e64 v165, v178, v165, s[12:13]
	v_cndmask_b32_e64 v178, v227, v166, s[14:15]
	v_cndmask_b32_e64 v179, v229, v167, s[14:15]
	v_cndmask_b32_e64 v166, v226, v166, s[12:13]
	v_cndmask_b32_e64 v167, v228, v167, s[12:13]
	v_cndmask_b32_e64 v168, v177, v168, s[12:13]
	v_cndmask_b32_e64 v169, v176, v169, s[12:13]
	v_cndmask_b32_e64 v170, v178, v170, s[12:13]
	v_cndmask_b32_e64 v171, v179, v171, s[12:13]

; __device__ __forceinline__ unsigned pk2(float lo, float hi) { const f32x2 v = {lo, hi}; const bf16x2_t b = __builtin_convertvector(v, bf16x2_t); return __builtin_bit_cast(unsigned, b); }
; __device__ __forceinline__ f32x4 gelu_mul4(f32x4 x, f32x4 v) {
;     const f32x4 t = x * x;
;     const f32x4 u = t * (-2.0f * 0.7978845608028654f * 0.044715f * 1.4426950408889634f) + (-2.0f * 0.7978845608028654f * 1.4426950408889634f);
;     const f32x4 z = x * u;
;     f32x4 d; d[0] = __builtin_amdgcn_exp2f(z[0]); d[1] = __builtin_amdgcn_exp2f(z[1]); d[2] = __builtin_amdgcn_exp2f(z[2]); d[3] = __builtin_amdgcn_exp2f(z[3]);
;     d = d + 1.0f;
;     f32x4 r; r[0] = __builtin_amdgcn_rcpf(d[0]); r[1] = __builtin_amdgcn_rcpf(d[1]); r[2] = __builtin_amdgcn_rcpf(d[2]); r[3] = __builtin_amdgcn_rcpf(d[3]);
;     return (x * v) * r;
; }
;     __device__ __forceinline__ void operator()(const f32x4 (&acc)[2][2][4][2], const pg8::Unit& u, int wr, int wc, int fr, int fq, PG8_LAS unsigned char* xl) const {
;     ...
;                         cc[bj] = bb[bj] + w0[bj] * p2 + w1[bj] * p1 + w2[bj] * cur;
;                     }
;                     const f32x4 gv = gelu_mul4(cc[0], cc[1]);
;                     u32x2 w; w.x = pk2(gv[0], gv[1]); w.y = pk2(gv[2], gv[3]);
;                     *(u32x2*)(G + (size_t)row * FF + jc0 + 4 * n) = w;
;                     if (!sample && ai == 0 && wr == 0 && m == 0 && fr < 2 && (pm & 7) != 0) {
; #pragma unroll
;                         for (int bj = 0; bj < 2; ++bj) *(f32x4*)(PH + (size_t)(pm * 2 + fr) * FF2 + bj * FF + jc0 + 4 * n) = cc[bj];
;                     }
;                     if (sample && (fr & 3) >= 2) { const int b = (row - MP) >> 2, t = fr & 3;
; #pragma unroll
;                         for (int bj = 0; bj < 2; ++bj) *(f32x4*)(nf_s + (size_t)(b * 2 + t - 2) * FF2 + bj * FF + jc0 + 4 * n) = acc[ai][bj][m][n];
.LBB0_565:
	s_and_b32 s73, s42, 7
	s_waitcnt vmcnt(0)
	v_pk_fma_f32 v[160:161], v[114:115], v[170:171], v[118:119]
	v_pk_fma_f32 v[162:163], v[112:113], v[168:169], v[116:117]
	s_cmp_lg_u32 s73, 0
	v_pk_fma_f32 v[160:161], v[110:111], v[166:167], v[160:161]
	v_pk_fma_f32 v[164:165], v[108:109], v[164:165], v[162:163]
	s_cselect_b64 s[6:7], -1, 0
	s_lshl_b32 s87, s42, 1
	v_pk_fma_f32 v[162:163], v[158:159], v[98:99], v[160:161]
	v_pk_fma_f32 v[160:161], v[156:157], v[96:97], v[164:165]
	v_add_u32_e32 v164, s87, v211
	v_mad_i64_i32 v[168:169], s[34:35], v164, s36, 0
	v_pk_fma_f32 v[164:165], v[106:107], v[178:179], v[122:123]
	v_pk_fma_f32 v[166:167], v[104:105], v[176:177], v[120:121]
	v_pk_fma_f32 v[164:165], v[102:103], v[174:175], v[164:165]
	v_pk_fma_f32 v[170:171], v[100:101], v[172:173], v[166:167]
	v_pk_mul_f32 v[166:167], v[162:163], v[162:163]
	v_pk_mul_f32 v[172:173], v[160:161], v[160:161]
	v_mov_b64_e32 v[246:247], s[82:83]
	v_pk_fma_f32 v[166:167], v[166:167], s[84:85], v[246:247] op_sel_hi:[1,0,0]
	v_pk_fma_f32 v[172:173], v[172:173], s[84:85], v[246:247] op_sel_hi:[1,0,0]
	v_pk_mul_f32 v[166:167], v[162:163], v[166:167]
	v_pk_mul_f32 v[172:173], v[160:161], v[172:173]
	v_exp_f32_e32 v174, v166
	v_exp_f32_e32 v172, v172
	v_exp_f32_e32 v175, v167
	v_exp_f32_e32 v173, v173
	v_pk_fma_f32 v[166:167], v[154:155], v[94:95], v[164:165]
	v_pk_fma_f32 v[164:165], v[152:153], v[92:93], v[170:171]
	v_pk_add_f32 v[170:171], v[174:175], 1.0 op_sel_hi:[1,0]
	v_pk_add_f32 v[172:173], v[172:173], 1.0 op_sel_hi:[1,0]
	v_rcp_f32_e32 v170, v170
	v_rcp_f32_e32 v172, v172
	v_rcp_f32_e32 v171, v171
	v_rcp_f32_e32 v173, v173
	v_pk_mul_f32 v[174:175], v[162:163], v[166:167]
	v_pk_mul_f32 v[176:177], v[160:161], v[164:165]
	v_pk_mul_f32 v[170:171], v[174:175], v[170:171]
	v_pk_mul_f32 v[172:173], v[176:177], v[172:173]
	v_lshl_add_u64 v[168:169], s[50:51], 0, v[168:169]
	v_cvt_pk_bf16_f32 v172, v172, v173
	v_cvt_pk_bf16_f32 v173, v170, v171
	v_mov_b64_e32 v[170:171], s[46:47]
	v_mad_i64_i32 v[170:171], s[34:35], v225, s37, v[170:171]
	s_and_b64 s[34:35], s[66:67], s[96:97]
	s_xor_b64 s[34:35], s[34:35], -1
	s_nor_b64 s[34:35], s[34:35], s[18:19]
	v_lshl_add_u64 v[178:179], v[196:197], 1, v[170:171]
	s_mov_b32 s101, 0
	s_and_b64 s[6:7], s[6:7], s[34:35]
	v_lshl_add_u64 v[176:177], v[196:197], 2, v[168:169]
	ds_bpermute_b32 v236, v244, v178
	ds_bpermute_b32 v237, v244, v179
	ds_bpermute_b32 v238, v244, v172
	ds_bpermute_b32 v239, v244, v173
	s_waitcnt lgkmcnt(0)
	global_store_dwordx2 v[236:237], v[238:239], off
	s_and_saveexec_b64 s[34:35], s[6:7]
	s_cbranch_execz .LBB0_567
	global_store_dwordx4 v[176:177], v[160:163], off
	s_nop 1
	v_add_co_u32_e32 v160, vcc, 0x2000, v176
	s_nop 1
	v_addc_co_u32_e32 v161, vcc, 0, v177, vcc
	global_store_dwordx4 v[160:161], v[164:167], off offset:3072

; template <int N> __device__ __forceinline__ float dpp_ror(float v) { const int i = __builtin_bit_cast(int, v); return __builtin_bit_cast(float, __builtin_amdgcn_update_dpp(i, i, 0x120 + N, 0xF, 0xF, false)); }
;     __device__ __forceinline__ void operator()(const f32x4 (&acc)[2][2][4][2], const pg8::Unit& u, int wr, int wc, int fr, int fq, PG8_LAS unsigned char* xl) const {
;     ...
;                 for (int m = 0; m < 4; ++m) {
;                     const int row = pm * 256 + ai * 128 + wr * 64 + m * 16 + fr;
;                     f32x4 cc[2];
; #pragma unroll
;                     for (int bj = 0; bj < 2; ++bj) {
;                         const f32x4 cur = acc[ai][bj][m][n]; f32x4 p1, p2;
;                         if (!sample) { const f32x4 prv = (m == 0) ? hb[bj] : acc[ai][bj][m == 0 ? 0 : m - 1][n];
; #pragma unroll
;                             for (int j = 0; j < 4; ++j) { const float s1 = fr == 15 ? prv[j] : cur[j], s2 = fr >= 14 ? prv[j] : cur[j]; p1[j] = dpp_ror<1>(s1); p2[j] = dpp_ror<2>(s2); }
;                         } else { const int t = fr & 3, b = (row - MP) >> 2;
; #pragma unroll
;                             for (int j = 0; j < 4; ++j) { p1[j] = dpp_ror<1>(cur[j]); p2[j] = dpp_ror<2>(cur[j]); }
;                             const f32x4 c1 = *(const f32x4*)(ctx_s + (size_t)(b * 2 + 1) * FF2 + bj * FF + jc0 + 4 * n), c0 = *(const f32x4*)(ctx_s + (size_t)(b * 2) * FF2 + bj * FF + jc0 + 4 * n);
; #pragma unroll
;                             for (int j = 0; j < 4; ++j) { p2[j] = t == 0 ? c0[j] : (t == 1 ? c1[j] : p2[j]); p1[j] = t == 0 ? c1[j] : p1[j]; }
;                         }
.LBB0_569:
	s_or_b64 exec, exec, s[78:79]
	v_add_u32_e32 v160, 0xffffc010, v225
	v_ashrrev_i32_e32 v160, 1, v160
	v_and_b32_e32 v226, 0xffffffee, v160
	s_and_b64 vcc, exec, s[22:23]
	s_mov_b64 s[78:79], -1
	s_cbranch_vccnz .LBB0_571
	v_or_b32_e32 v162, 1, v160
	v_mov_b64_e32 v[160:161], s[40:41]
	v_mad_i64_i32 v[162:163], vcc, v162, s36, v[160:161]
	v_mad_i64_i32 v[160:161], vcc, v226, s36, v[160:161]
	v_lshl_add_u64 v[174:175], v[162:163], 0, v[198:199]
	v_lshl_add_u64 v[172:173], v[160:161], 0, v[198:199]
	global_load_dwordx4 v[160:163], v[174:175], off
	global_load_dwordx4 v[164:167], v[172:173], off
	v_mov_b32_e32 v168, v148
	v_mov_b32_e32 v169, v148
	v_mov_b32_e32 v170, v149
	v_mov_b32_e32 v171, v149
	v_mov_b32_e32 v228, v150
	v_mov_b32_e32 v230, v151
	v_mov_b32_e32 v227, v150
	v_mov_b32_e32 v229, v151
	v_mov_b32_dpp v168, v168 row_ror:1 row_mask:0xf bank_mask:0xf
	v_mov_b32_dpp v169, v169 row_ror:2 row_mask:0xf bank_mask:0xf
	v_mov_b32_dpp v170, v170 row_ror:1 row_mask:0xf bank_mask:0xf
	v_mov_b32_dpp v171, v171 row_ror:2 row_mask:0xf bank_mask:0xf
	v_mov_b32_dpp v228, v228 row_ror:2 row_mask:0xf bank_mask:0xf
	v_mov_b32_dpp v230, v230 row_ror:2 row_mask:0xf bank_mask:0xf
	v_mov_b32_dpp v227, v227 row_ror:1 row_mask:0xf bank_mask:0xf
	v_mov_b32_dpp v229, v229 row_ror:1 row_mask:0xf bank_mask:0xf
	s_waitcnt vmcnt(1)
	v_cndmask_b32_e64 v169, v169, v160, s[14:15]
	v_cndmask_b32_e64 v160, v168, v160, s[12:13]
	v_cndmask_b32_e64 v168, v171, v161, s[14:15]
	v_cndmask_b32_e64 v161, v170, v161, s[12:13]
	v_cndmask_b32_e64 v170, v228, v162, s[14:15]
	v_cndmask_b32_e64 v171, v230, v163, s[14:15]
	v_cndmask_b32_e64 v162, v227, v162, s[12:13]
	v_cndmask_b32_e64 v163, v229, v163, s[12:13]
	s_waitcnt vmcnt(0)
	v_cndmask_b32_e64 v164, v169, v164, s[12:13]
	v_cndmask_b32_e64 v165, v168, v165, s[12:13]
	v_cndmask_b32_e64 v166, v170, v166, s[12:13]
	v_cndmask_b32_e64 v167, v171, v167, s[12:13]
	s_cbranch_execnz .LBB0_573
	s_branch .LBB0_572

; __device__ __forceinline__ f32x4 gelu_mul4(f32x4 x, f32x4 v) {
;     const f32x4 t = x * x;
;     const f32x4 u = t * (-2.0f * 0.7978845608028654f * 0.044715f * 1.4426950408889634f) + (-2.0f * 0.7978845608028654f * 1.4426950408889634f);
;     const f32x4 z = x * u;
;     __device__ __forceinline__ void operator()(const f32x4 (&acc)[2][2][4][2], const pg8::Unit& u, int wr, int wc, int fr, int fq, PG8_LAS unsigned char* xl) const {
;     ...
;                         const f32x4 cur = acc[ai][bj][m][n]; f32x4 p1, p2;
;                         if (!sample) { const f32x4 prv = (m == 0) ? hb[bj] : acc[ai][bj][m == 0 ? 0 : m - 1][n];
; #pragma unroll
;                             for (int j = 0; j < 4; ++j) { const float s1 = fr == 15 ? prv[j] : cur[j], s2 = fr >= 14 ? prv[j] : cur[j]; p1[j] = dpp_ror<1>(s1); p2[j] = dpp_ror<2>(s2); }
;                         } else { const int t = fr & 3, b = (row - MP) >> 2;
; #pragma unroll
;                             for (int j = 0; j < 4; ++j) { p1[j] = dpp_ror<1>(cur[j]); p2[j] = dpp_ror<2>(cur[j]); }
;                             const f32x4 c1 = *(const f32x4*)(ctx_s + (size_t)(b * 2 + 1) * FF2 + bj * FF + jc0 + 4 * n), c0 = *(const f32x4*)(ctx_s + (size_t)(b * 2) * FF2 + bj * FF + jc0 + 4 * n);
; #pragma unroll
;                             for (int j = 0; j < 4; ++j) { p2[j] = t == 0 ? c0[j] : (t == 1 ? c1[j] : p2[j]); p1[j] = t == 0 ? c1[j] : p1[j]; }
;                         }
;                         cc[bj] = bb[bj] + w0[bj] * p2 + w1[bj] * p1 + w2[bj] * cur;
;                     }
;                     const f32x4 gv = gelu_mul4(cc[0], cc[1]);
;                     u32x2 w; w.x = pk2(gv[0], gv[1]); w.y = pk2(gv[2], gv[3]);
;                     *(u32x2*)(G + (size_t)row * FF + jc0 + 4 * n) = w;
;                     if (!sample && ai == 0 && wr == 0 && m == 0 && fr < 2 && (pm & 7) != 0) {
; #pragma unroll
;                         for (int bj = 0; bj < 2; ++bj) *(f32x4*)(PH + (size_t)(pm * 2 + fr) * FF2 + bj * FF + jc0 + 4 * n) = cc[bj];
;                     }
;                     if (sample && (fr & 3) >= 2) { const int b = (row - MP) >> 2, t = fr & 3;
; #pragma unroll
;                         for (int bj = 0; bj < 2; ++bj) *(f32x4*)(nf_s + (size_t)(b * 2 + t - 2) * FF2 + bj * FF + jc0 + 4 * n) = acc[ai][bj][m][n];
.LBB0_577:
	v_pk_fma_f32 v[152:153], v[114:115], v[166:167], v[118:119]
	v_pk_fma_f32 v[154:155], v[112:113], v[164:165], v[116:117]
	v_pk_fma_f32 v[152:153], v[110:111], v[162:163], v[152:153]
	v_pk_fma_f32 v[154:155], v[108:109], v[160:161], v[154:155]
	v_pk_fma_f32 v[152:153], v[150:151], v[98:99], v[152:153]
	v_pk_fma_f32 v[154:155], v[148:149], v[96:97], v[154:155]
	v_pk_fma_f32 v[160:161], v[106:107], v[170:171], v[122:123]
	v_pk_fma_f32 v[162:163], v[104:105], v[168:169], v[120:121]
	v_pk_fma_f32 v[158:159], v[102:103], v[158:159], v[160:161]
	v_pk_fma_f32 v[156:157], v[100:101], v[156:157], v[162:163]
	v_pk_mul_f32 v[160:161], v[152:153], v[152:153]
	v_pk_mul_f32 v[162:163], v[154:155], v[154:155]
	v_pk_fma_f32 v[160:161], v[160:161], s[84:85], v[246:247] op_sel_hi:[1,0,0]
	v_pk_fma_f32 v[162:163], v[162:163], s[84:85], v[246:247] op_sel_hi:[1,0,0]
	v_pk_mul_f32 v[160:161], v[152:153], v[160:161]
	v_pk_mul_f32 v[162:163], v[154:155], v[162:163]
	v_exp_f32_e32 v160, v160
	v_exp_f32_e32 v162, v162
	v_exp_f32_e32 v161, v161
	v_exp_f32_e32 v163, v163
	v_pk_fma_f32 v[158:159], v[146:147], v[94:95], v[158:159]
	v_pk_fma_f32 v[156:157], v[144:145], v[92:93], v[156:157]
	v_pk_add_f32 v[160:161], v[160:161], 1.0 op_sel_hi:[1,0]
	v_pk_add_f32 v[162:163], v[162:163], 1.0 op_sel_hi:[1,0]
	v_rcp_f32_e32 v160, v160
	v_rcp_f32_e32 v162, v162
	v_rcp_f32_e32 v161, v161
	v_rcp_f32_e32 v163, v163
	v_pk_mul_f32 v[152:153], v[152:153], v[158:159]
	v_pk_mul_f32 v[154:155], v[154:155], v[156:157]
	v_pk_mul_f32 v[152:153], v[152:153], v[160:161]
	v_pk_mul_f32 v[154:155], v[154:155], v[162:163]
	v_cvt_pk_bf16_f32 v154, v154, v155
	v_cvt_pk_bf16_f32 v155, v152, v153
	s_mul_i32 s100, s37, 16
	v_lshl_add_u64 v[168:169], v[178:179], 0, s[100:101]
	v_add_u32_e32 v170, v226, v215
	ds_bpermute_b32 v236, v244, v168
	ds_bpermute_b32 v237, v244, v169
	ds_bpermute_b32 v238, v244, v154
	ds_bpermute_b32 v239, v244, v155
	s_waitcnt lgkmcnt(0)
	global_store_dwordx2 v[236:237], v[238:239], off
	s_and_saveexec_b64 s[78:79], s[34:35]
	s_cbranch_execz .LBB0_579
	v_mov_b64_e32 v[152:153], s[24:25]
	v_mad_i64_i32 v[152:153], vcc, v170, s36, v[152:153]
	v_lshl_add_u64 v[152:153], v[196:197], 2, v[152:153]
	global_store_dwordx4 v[152:153], v[148:151], off
	v_add_co_u32_e32 v152, vcc, 0x2000, v152
	s_nop 1
	v_addc_co_u32_e32 v153, vcc, 0, v153, vcc
	global_store_dwordx4 v[152:153], v[144:147], off offset:3072
.LBB0_579:
	s_or_b64 exec, exec, s[78:79]
	v_add_u32_e32 v152, 0xffffc020, v225
	v_ashrrev_i32_e32 v152, 1, v152
	v_and_b32_e32 v171, -10, v152
	s_and_b64 vcc, exec, s[22:23]
	s_mov_b64 s[78:79], -1
	s_cbranch_vccnz .LBB0_581
	v_or_b32_e32 v154, 1, v152
	v_mov_b64_e32 v[152:153], s[40:41]
	v_mad_i64_i32 v[154:155], vcc, v154, s36, v[152:153]
	v_mad_i64_i32 v[152:153], vcc, v171, s36, v[152:153]
	v_lshl_add_u64 v[166:167], v[154:155], 0, v[198:199]
	v_lshl_add_u64 v[164:165], v[152:153], 0, v[198:199]
	global_load_dwordx4 v[152:155], v[166:167], off
	global_load_dwordx4 v[156:159], v[164:165], off
	v_mov_b32_e32 v160, v140
	v_mov_b32_e32 v161, v140
	v_mov_b32_e32 v162, v141
	v_mov_b32_e32 v163, v141
	v_mov_b32_e32 v227, v142
	v_mov_b32_e32 v229, v143
	v_mov_b32_e32 v226, v142
	v_mov_b32_e32 v228, v143
	v_mov_b32_dpp v160, v160 row_ror:1 row_mask:0xf bank_mask:0xf
	v_mov_b32_dpp v161, v161 row_ror:2 row_mask:0xf bank_mask:0xf
	v_mov_b32_dpp v162, v162 row_ror:1 row_mask:0xf bank_mask:0xf
	v_mov_b32_dpp v163, v163 row_ror:2 row_mask:0xf bank_mask:0xf
	v_mov_b32_dpp v227, v227 row_ror:2 row_mask:0xf bank_mask:0xf
	v_mov_b32_dpp v229, v229 row_ror:2 row_mask:0xf bank_mask:0xf
	v_mov_b32_dpp v226, v226 row_ror:1 row_mask:0xf bank_mask:0xf
	v_mov_b32_dpp v228, v228 row_ror:1 row_mask:0xf bank_mask:0xf
	s_waitcnt vmcnt(1)
	v_cndmask_b32_e64 v161, v161, v152, s[14:15]
	v_cndmask_b32_e64 v152, v160, v152, s[12:13]
	v_cndmask_b32_e64 v160, v163, v153, s[14:15]
	v_cndmask_b32_e64 v153, v162, v153, s[12:13]
	v_cndmask_b32_e64 v162, v227, v154, s[14:15]
	v_cndmask_b32_e64 v163, v229, v155, s[14:15]
	v_cndmask_b32_e64 v154, v226, v154, s[12:13]
	v_cndmask_b32_e64 v155, v228, v155, s[12:13]
	s_waitcnt vmcnt(0)
	v_cndmask_b32_e64 v156, v161, v156, s[12:13]
	v_cndmask_b32_e64 v157, v160, v157, s[12:13]
	v_cndmask_b32_e64 v158, v162, v158, s[12:13]
	v_cndmask_b32_e64 v159, v163, v159, s[12:13]
	s_cbranch_execnz .LBB0_583
	s_branch .LBB0_582

; __device__ __forceinline__ f32x4 gelu_mul4(f32x4 x, f32x4 v) {
;     const f32x4 t = x * x;
;     const f32x4 u = t * (-2.0f * 0.7978845608028654f * 0.044715f * 1.4426950408889634f) + (-2.0f * 0.7978845608028654f * 1.4426950408889634f);
;     const f32x4 z = x * u;
;     __device__ __forceinline__ void operator()(const f32x4 (&acc)[2][2][4][2], const pg8::Unit& u, int wr, int wc, int fr, int fq, PG8_LAS unsigned char* xl) const {
;     ...
;                         const f32x4 cur = acc[ai][bj][m][n]; f32x4 p1, p2;
;                         if (!sample) { const f32x4 prv = (m == 0) ? hb[bj] : acc[ai][bj][m == 0 ? 0 : m - 1][n];
; #pragma unroll
;                             for (int j = 0; j < 4; ++j) { const float s1 = fr == 15 ? prv[j] : cur[j], s2 = fr >= 14 ? prv[j] : cur[j]; p1[j] = dpp_ror<1>(s1); p2[j] = dpp_ror<2>(s2); }
;                         } else { const int t = fr & 3, b = (row - MP) >> 2;
; #pragma unroll
;                             for (int j = 0; j < 4; ++j) { p1[j] = dpp_ror<1>(cur[j]); p2[j] = dpp_ror<2>(cur[j]); }
;                             const f32x4 c1 = *(const f32x4*)(ctx_s + (size_t)(b * 2 + 1) * FF2 + bj * FF + jc0 + 4 * n), c0 = *(const f32x4*)(ctx_s + (size_t)(b * 2) * FF2 + bj * FF + jc0 + 4 * n);
; #pragma unroll
;                             for (int j = 0; j < 4; ++j) { p2[j] = t == 0 ? c0[j] : (t == 1 ? c1[j] : p2[j]); p1[j] = t == 0 ? c1[j] : p1[j]; }
;                         }
;                         cc[bj] = bb[bj] + w0[bj] * p2 + w1[bj] * p1 + w2[bj] * cur;
;                     }
;                     const f32x4 gv = gelu_mul4(cc[0], cc[1]);
;                     u32x2 w; w.x = pk2(gv[0], gv[1]); w.y = pk2(gv[2], gv[3]);
;                     *(u32x2*)(G + (size_t)row * FF + jc0 + 4 * n) = w;
;                     if (!sample && ai == 0 && wr == 0 && m == 0 && fr < 2 && (pm & 7) != 0) {
; #pragma unroll
;                         for (int bj = 0; bj < 2; ++bj) *(f32x4*)(PH + (size_t)(pm * 2 + fr) * FF2 + bj * FF + jc0 + 4 * n) = cc[bj];
;                     }
;                     if (sample && (fr & 3) >= 2) { const int b = (row - MP) >> 2, t = fr & 3;
; #pragma unroll
;                         for (int bj = 0; bj < 2; ++bj) *(f32x4*)(nf_s + (size_t)(b * 2 + t - 2) * FF2 + bj * FF + jc0 + 4 * n) = acc[ai][bj][m][n];
.LBB0_587:
	v_pk_fma_f32 v[144:145], v[114:115], v[158:159], v[118:119]
	v_pk_fma_f32 v[146:147], v[112:113], v[156:157], v[116:117]
	v_pk_fma_f32 v[144:145], v[110:111], v[154:155], v[144:145]
	v_pk_fma_f32 v[146:147], v[108:109], v[152:153], v[146:147]
	v_pk_fma_f32 v[144:145], v[142:143], v[98:99], v[144:145]
	v_pk_fma_f32 v[146:147], v[140:141], v[96:97], v[146:147]
	v_pk_fma_f32 v[152:153], v[106:107], v[162:163], v[122:123]
	v_pk_fma_f32 v[154:155], v[104:105], v[160:161], v[120:121]
	v_pk_fma_f32 v[150:151], v[102:103], v[150:151], v[152:153]
	v_pk_fma_f32 v[148:149], v[100:101], v[148:149], v[154:155]
	v_pk_mul_f32 v[152:153], v[144:145], v[144:145]
	v_pk_mul_f32 v[154:155], v[146:147], v[146:147]
	v_pk_fma_f32 v[152:153], v[152:153], s[84:85], v[246:247] op_sel_hi:[1,0,0]
	v_pk_fma_f32 v[154:155], v[154:155], s[84:85], v[246:247] op_sel_hi:[1,0,0]
	v_pk_mul_f32 v[152:153], v[144:145], v[152:153]
	v_pk_mul_f32 v[154:155], v[146:147], v[154:155]
	v_exp_f32_e32 v152, v152
	v_exp_f32_e32 v154, v154
	v_exp_f32_e32 v153, v153
	v_exp_f32_e32 v155, v155
	v_pk_fma_f32 v[150:151], v[138:139], v[94:95], v[150:151]
	v_pk_fma_f32 v[148:149], v[136:137], v[92:93], v[148:149]
	v_pk_add_f32 v[152:153], v[152:153], 1.0 op_sel_hi:[1,0]
	v_pk_add_f32 v[154:155], v[154:155], 1.0 op_sel_hi:[1,0]
	v_rcp_f32_e32 v152, v152
	v_rcp_f32_e32 v154, v154
	v_rcp_f32_e32 v153, v153
	v_rcp_f32_e32 v155, v155
	v_pk_mul_f32 v[144:145], v[144:145], v[150:151]
	v_pk_mul_f32 v[146:147], v[146:147], v[148:149]
	v_pk_mul_f32 v[144:145], v[144:145], v[152:153]
	v_pk_mul_f32 v[146:147], v[146:147], v[154:155]
	v_cvt_pk_bf16_f32 v146, v146, v147
	v_cvt_pk_bf16_f32 v147, v144, v145
	s_mul_i32 s100, s37, 32
	v_lshl_add_u64 v[160:161], v[178:179], 0, s[100:101]
	v_add_u32_e32 v162, v171, v215
	ds_bpermute_b32 v236, v244, v160
	ds_bpermute_b32 v237, v244, v161
	ds_bpermute_b32 v238, v244, v146
	ds_bpermute_b32 v239, v244, v147
	s_waitcnt lgkmcnt(0)
	global_store_dwordx2 v[236:237], v[238:239], off
	s_and_saveexec_b64 s[78:79], s[34:35]
	s_cbranch_execz .LBB0_589
	v_mov_b64_e32 v[144:145], s[24:25]
	v_mad_i64_i32 v[144:145], vcc, v162, s36, v[144:145]
	v_lshl_add_u64 v[144:145], v[196:197], 2, v[144:145]
	global_store_dwordx4 v[144:145], v[140:143], off
	v_add_co_u32_e32 v144, vcc, 0x2000, v144
	s_nop 1
	v_addc_co_u32_e32 v145, vcc, 0, v145, vcc
	global_store_dwordx4 v[144:145], v[136:139], off offset:3072
.LBB0_589:
	s_or_b64 exec, exec, s[78:79]
	v_add_u32_e32 v144, 0xffffc030, v225
	v_ashrrev_i32_e32 v144, 1, v144
	v_and_b32_e32 v163, -2, v144
	s_and_b64 vcc, exec, s[22:23]
	s_mov_b64 s[78:79], -1
	s_cbranch_vccnz .LBB0_591
	v_or_b32_e32 v146, 1, v144
	v_mov_b64_e32 v[144:145], s[40:41]
	v_mad_i64_i32 v[146:147], vcc, v146, s36, v[144:145]
	v_mad_i64_i32 v[144:145], vcc, v163, s36, v[144:145]
	v_lshl_add_u64 v[158:159], v[146:147], 0, v[198:199]
	v_lshl_add_u64 v[156:157], v[144:145], 0, v[198:199]
	global_load_dwordx4 v[144:147], v[158:159], off
	global_load_dwordx4 v[148:151], v[156:157], off
	v_mov_b32_e32 v152, v132
	v_mov_b32_e32 v153, v132
	v_mov_b32_e32 v154, v133
	v_mov_b32_e32 v155, v133
	v_mov_b32_e32 v226, v134
	v_mov_b32_e32 v228, v135
	v_mov_b32_e32 v171, v134
	v_mov_b32_e32 v227, v135
	v_mov_b32_dpp v152, v152 row_ror:1 row_mask:0xf bank_mask:0xf
	v_mov_b32_dpp v153, v153 row_ror:2 row_mask:0xf bank_mask:0xf
	v_mov_b32_dpp v154, v154 row_ror:1 row_mask:0xf bank_mask:0xf
	v_mov_b32_dpp v155, v155 row_ror:2 row_mask:0xf bank_mask:0xf
	v_mov_b32_dpp v226, v226 row_ror:2 row_mask:0xf bank_mask:0xf
	v_mov_b32_dpp v228, v228 row_ror:2 row_mask:0xf bank_mask:0xf
	v_mov_b32_dpp v171, v171 row_ror:1 row_mask:0xf bank_mask:0xf
	v_mov_b32_dpp v227, v227 row_ror:1 row_mask:0xf bank_mask:0xf
	s_waitcnt vmcnt(1)
	v_cndmask_b32_e64 v153, v153, v144, s[14:15]
	v_cndmask_b32_e64 v144, v152, v144, s[12:13]
	v_cndmask_b32_e64 v152, v155, v145, s[14:15]
	v_cndmask_b32_e64 v145, v154, v145, s[12:13]
	v_cndmask_b32_e64 v154, v226, v146, s[14:15]
	v_cndmask_b32_e64 v155, v228, v147, s[14:15]
	v_cndmask_b32_e64 v146, v171, v146, s[12:13]
	v_cndmask_b32_e64 v147, v227, v147, s[12:13]
	s_waitcnt vmcnt(0)
	v_cndmask_b32_e64 v148, v153, v148, s[12:13]
	v_cndmask_b32_e64 v149, v152, v149, s[12:13]
	v_cndmask_b32_e64 v150, v154, v150, s[12:13]
	v_cndmask_b32_e64 v151, v155, v151, s[12:13]
	s_cbranch_execnz .LBB0_593
	s_branch .LBB0_592

; __device__ __forceinline__ unsigned pk2(float lo, float hi) { const f32x2 v = {lo, hi}; const bf16x2_t b = __builtin_convertvector(v, bf16x2_t); return __builtin_bit_cast(unsigned, b); }
; __device__ __forceinline__ f32x4 gelu_mul4(f32x4 x, f32x4 v) {
;     const f32x4 t = x * x;
;     const f32x4 u = t * (-2.0f * 0.7978845608028654f * 0.044715f * 1.4426950408889634f) + (-2.0f * 0.7978845608028654f * 1.4426950408889634f);
;     const f32x4 z = x * u;
;     f32x4 d; d[0] = __builtin_amdgcn_exp2f(z[0]); d[1] = __builtin_amdgcn_exp2f(z[1]); d[2] = __builtin_amdgcn_exp2f(z[2]); d[3] = __builtin_amdgcn_exp2f(z[3]);
;     d = d + 1.0f;
;     f32x4 r; r[0] = __builtin_amdgcn_rcpf(d[0]); r[1] = __builtin_amdgcn_rcpf(d[1]); r[2] = __builtin_amdgcn_rcpf(d[2]); r[3] = __builtin_amdgcn_rcpf(d[3]);
;     return (x * v) * r;
; }
;     __device__ __forceinline__ void operator()(const f32x4 (&acc)[2][2][4][2], const pg8::Unit& u, int wr, int wc, int fr, int fq, PG8_LAS unsigned char* xl) const {
;     ...
;                         cc[bj] = bb[bj] + w0[bj] * p2 + w1[bj] * p1 + w2[bj] * cur;
;                     }
;                     const f32x4 gv = gelu_mul4(cc[0], cc[1]);
;                     u32x2 w; w.x = pk2(gv[0], gv[1]); w.y = pk2(gv[2], gv[3]);
;                     *(u32x2*)(G + (size_t)row * FF + jc0 + 4 * n) = w;
;                     if (!sample && ai == 0 && wr == 0 && m == 0 && fr < 2 && (pm & 7) != 0) {
; #pragma unroll
;                         for (int bj = 0; bj < 2; ++bj) *(f32x4*)(PH + (size_t)(pm * 2 + fr) * FF2 + bj * FF + jc0 + 4 * n) = cc[bj];
;                     }
;                     if (sample && (fr & 3) >= 2) { const int b = (row - MP) >> 2, t = fr & 3;
; #pragma unroll
;                         for (int bj = 0; bj < 2; ++bj) *(f32x4*)(nf_s + (size_t)(b * 2 + t - 2) * FF2 + bj * FF + jc0 + 4 * n) = acc[ai][bj][m][n];
.LBB0_597:
	v_pk_fma_f32 v[136:137], v[114:115], v[150:151], v[118:119]
	v_pk_fma_f32 v[138:139], v[112:113], v[148:149], v[116:117]
	v_pk_fma_f32 v[136:137], v[110:111], v[146:147], v[136:137]
	v_pk_fma_f32 v[138:139], v[108:109], v[144:145], v[138:139]
	v_pk_fma_f32 v[136:137], v[134:135], v[98:99], v[136:137]
	v_pk_fma_f32 v[138:139], v[132:133], v[96:97], v[138:139]
	v_pk_fma_f32 v[144:145], v[106:107], v[154:155], v[122:123]
	v_pk_fma_f32 v[146:147], v[104:105], v[152:153], v[120:121]
	v_pk_fma_f32 v[142:143], v[102:103], v[142:143], v[144:145]
	v_pk_fma_f32 v[140:141], v[100:101], v[140:141], v[146:147]
	v_pk_mul_f32 v[144:145], v[136:137], v[136:137]
	v_pk_mul_f32 v[146:147], v[138:139], v[138:139]
	v_pk_fma_f32 v[144:145], v[144:145], s[84:85], v[246:247] op_sel_hi:[1,0,0]
	v_pk_fma_f32 v[146:147], v[146:147], s[84:85], v[246:247] op_sel_hi:[1,0,0]
	v_pk_mul_f32 v[144:145], v[136:137], v[144:145]
	v_pk_mul_f32 v[146:147], v[138:139], v[146:147]
	v_exp_f32_e32 v144, v144
	v_exp_f32_e32 v146, v146
	v_exp_f32_e32 v145, v145
	v_exp_f32_e32 v147, v147
	v_pk_fma_f32 v[142:143], v[130:131], v[94:95], v[142:143]
	v_pk_fma_f32 v[140:141], v[128:129], v[92:93], v[140:141]
	v_pk_add_f32 v[144:145], v[144:145], 1.0 op_sel_hi:[1,0]
	v_pk_add_f32 v[146:147], v[146:147], 1.0 op_sel_hi:[1,0]
	v_rcp_f32_e32 v144, v144
	v_rcp_f32_e32 v146, v146
	v_rcp_f32_e32 v145, v145
	v_rcp_f32_e32 v147, v147
	v_pk_mul_f32 v[136:137], v[136:137], v[142:143]
	v_pk_mul_f32 v[138:139], v[138:139], v[140:141]
	v_pk_mul_f32 v[136:137], v[136:137], v[144:145]
	v_pk_mul_f32 v[138:139], v[138:139], v[146:147]
	v_cvt_pk_bf16_f32 v138, v138, v139
	v_cvt_pk_bf16_f32 v139, v136, v137
	s_mul_i32 s100, s37, 48
	v_lshl_add_u64 v[152:153], v[178:179], 0, s[100:101]
	v_add_u32_e32 v154, v163, v215
	ds_bpermute_b32 v236, v244, v152
	ds_bpermute_b32 v237, v244, v153
	ds_bpermute_b32 v238, v244, v138
	ds_bpermute_b32 v239, v244, v139
	s_waitcnt lgkmcnt(0)
	global_store_dwordx2 v[236:237], v[238:239], off
	s_and_saveexec_b64 s[78:79], s[34:35]
	s_cbranch_execz .LBB0_599
	v_mov_b64_e32 v[136:137], s[24:25]
	v_mad_i64_i32 v[136:137], vcc, v154, s36, v[136:137]
	v_lshl_add_u64 v[136:137], v[196:197], 2, v[136:137]
	global_store_dwordx4 v[136:137], v[132:135], off
	s_nop 1
	v_add_co_u32_e32 v132, vcc, 0x2000, v136
	s_nop 1
	v_addc_co_u32_e32 v133, vcc, 0, v137, vcc
	global_store_dwordx4 v[132:133], v[128:131], off offset:3072

; template <int N> __device__ __forceinline__ float dpp_ror(float v) { const int i = __builtin_bit_cast(int, v); return __builtin_bit_cast(float, __builtin_amdgcn_update_dpp(i, i, 0x120 + N, 0xF, 0xF, false)); }
;     __device__ __forceinline__ void operator()(const f32x4 (&acc)[2][2][4][2], const pg8::Unit& u, int wr, int wc, int fr, int fq, PG8_LAS unsigned char* xl) const {
;     ...
;                 for (int m = 0; m < 4; ++m) {
;                     const int row = pm * 256 + ai * 128 + wr * 64 + m * 16 + fr;
;                     f32x4 cc[2];
; #pragma unroll
;                     for (int bj = 0; bj < 2; ++bj) {
;                         const f32x4 cur = acc[ai][bj][m][n]; f32x4 p1, p2;
;                         if (!sample) { const f32x4 prv = (m == 0) ? hb[bj] : acc[ai][bj][m == 0 ? 0 : m - 1][n];
; #pragma unroll
;                             for (int j = 0; j < 4; ++j) { const float s1 = fr == 15 ? prv[j] : cur[j], s2 = fr >= 14 ? prv[j] : cur[j]; p1[j] = dpp_ror<1>(s1); p2[j] = dpp_ror<2>(s2); }
;                         } else { const int t = fr & 3, b = (row - MP) >> 2;
; #pragma unroll
;                             for (int j = 0; j < 4; ++j) { p1[j] = dpp_ror<1>(cur[j]); p2[j] = dpp_ror<2>(cur[j]); }
;                             const f32x4 c1 = *(const f32x4*)(ctx_s + (size_t)(b * 2 + 1) * FF2 + bj * FF + jc0 + 4 * n), c0 = *(const f32x4*)(ctx_s + (size_t)(b * 2) * FF2 + bj * FF + jc0 + 4 * n);
; #pragma unroll
;                             for (int j = 0; j < 4; ++j) { p2[j] = t == 0 ? c0[j] : (t == 1 ? c1[j] : p2[j]); p1[j] = t == 0 ? c1[j] : p1[j]; }
;                         }
.LBB0_601:
	s_or_b64 exec, exec, vcc
	v_add_u32_e32 v132, 0xffffc080, v225
	v_ashrrev_i32_e32 v132, 1, v132
	v_and_b32_e32 v155, 0xffffffe6, v132
	s_and_b64 vcc, exec, s[22:23]
	s_mov_b64 s[78:79], -1
	s_cbranch_vccnz .LBB0_603
	v_or_b32_e32 v134, 1, v132
	v_mov_b64_e32 v[132:133], s[40:41]
	v_mad_i64_i32 v[134:135], vcc, v134, s36, v[132:133]
	v_mad_i64_i32 v[132:133], vcc, v155, s36, v[132:133]
	v_lshl_add_u64 v[150:151], v[134:135], 0, v[198:199]
	v_lshl_add_u64 v[148:149], v[132:133], 0, v[198:199]
	global_load_dwordx4 v[132:135], v[150:151], off
	global_load_dwordx4 v[136:139], v[148:149], off
	v_mov_b32_e32 v144, v124
	v_mov_b32_e32 v145, v124
	v_mov_b32_e32 v146, v125
	v_mov_b32_e32 v147, v125
	v_mov_b32_e32 v171, v126
	v_mov_b32_e32 v227, v127
	v_mov_b32_e32 v163, v126
	v_mov_b32_e32 v226, v127
	v_mov_b32_dpp v144, v144 row_ror:1 row_mask:0xf bank_mask:0xf
	v_mov_b32_dpp v145, v145 row_ror:2 row_mask:0xf bank_mask:0xf
	v_mov_b32_dpp v146, v146 row_ror:1 row_mask:0xf bank_mask:0xf
	v_mov_b32_dpp v147, v147 row_ror:2 row_mask:0xf bank_mask:0xf
	v_mov_b32_dpp v171, v171 row_ror:2 row_mask:0xf bank_mask:0xf
	v_mov_b32_dpp v227, v227 row_ror:2 row_mask:0xf bank_mask:0xf
	v_mov_b32_dpp v163, v163 row_ror:1 row_mask:0xf bank_mask:0xf
	v_mov_b32_dpp v226, v226 row_ror:1 row_mask:0xf bank_mask:0xf
	s_waitcnt vmcnt(1)
	v_cndmask_b32_e64 v145, v145, v132, s[14:15]
	v_cndmask_b32_e64 v132, v144, v132, s[12:13]
	v_cndmask_b32_e64 v144, v147, v133, s[14:15]
	v_cndmask_b32_e64 v133, v146, v133, s[12:13]
	v_cndmask_b32_e64 v146, v171, v134, s[14:15]
	v_cndmask_b32_e64 v147, v227, v135, s[14:15]
	v_cndmask_b32_e64 v134, v163, v134, s[12:13]
	v_cndmask_b32_e64 v135, v226, v135, s[12:13]
	s_waitcnt vmcnt(0)
	v_cndmask_b32_e64 v136, v145, v136, s[12:13]
	v_cndmask_b32_e64 v137, v144, v137, s[12:13]
	v_cndmask_b32_e64 v138, v146, v138, s[12:13]
	v_cndmask_b32_e64 v139, v147, v139, s[12:13]
	s_cbranch_execnz .LBB0_605
	s_branch .LBB0_604

; __device__ __forceinline__ f32x4 gelu_mul4(f32x4 x, f32x4 v) {
;     const f32x4 t = x * x;
;     const f32x4 u = t * (-2.0f * 0.7978845608028654f * 0.044715f * 1.4426950408889634f) + (-2.0f * 0.7978845608028654f * 1.4426950408889634f);
;     const f32x4 z = x * u;
;     __device__ __forceinline__ void operator()(const f32x4 (&acc)[2][2][4][2], const pg8::Unit& u, int wr, int wc, int fr, int fq, PG8_LAS unsigned char* xl) const {
;     ...
;                         const f32x4 cur = acc[ai][bj][m][n]; f32x4 p1, p2;
;                         if (!sample) { const f32x4 prv = (m == 0) ? hb[bj] : acc[ai][bj][m == 0 ? 0 : m - 1][n];
; #pragma unroll
;                             for (int j = 0; j < 4; ++j) { const float s1 = fr == 15 ? prv[j] : cur[j], s2 = fr >= 14 ? prv[j] : cur[j]; p1[j] = dpp_ror<1>(s1); p2[j] = dpp_ror<2>(s2); }
;                         } else { const int t = fr & 3, b = (row - MP) >> 2;
; #pragma unroll
;                             for (int j = 0; j < 4; ++j) { p1[j] = dpp_ror<1>(cur[j]); p2[j] = dpp_ror<2>(cur[j]); }
;                             const f32x4 c1 = *(const f32x4*)(ctx_s + (size_t)(b * 2 + 1) * FF2 + bj * FF + jc0 + 4 * n), c0 = *(const f32x4*)(ctx_s + (size_t)(b * 2) * FF2 + bj * FF + jc0 + 4 * n);
; #pragma unroll
;                             for (int j = 0; j < 4; ++j) { p2[j] = t == 0 ? c0[j] : (t == 1 ? c1[j] : p2[j]); p1[j] = t == 0 ? c1[j] : p1[j]; }
;                         }
;                         cc[bj] = bb[bj] + w0[bj] * p2 + w1[bj] * p1 + w2[bj] * cur;
;                     }
;                     const f32x4 gv = gelu_mul4(cc[0], cc[1]);
;                     u32x2 w; w.x = pk2(gv[0], gv[1]); w.y = pk2(gv[2], gv[3]);
;                     *(u32x2*)(G + (size_t)row * FF + jc0 + 4 * n) = w;
;                     if (!sample && ai == 0 && wr == 0 && m == 0 && fr < 2 && (pm & 7) != 0) {
; #pragma unroll
;                         for (int bj = 0; bj < 2; ++bj) *(f32x4*)(PH + (size_t)(pm * 2 + fr) * FF2 + bj * FF + jc0 + 4 * n) = cc[bj];
;                     }
;                     if (sample && (fr & 3) >= 2) { const int b = (row - MP) >> 2, t = fr & 3;
; #pragma unroll
;                         for (int bj = 0; bj < 2; ++bj) *(f32x4*)(nf_s + (size_t)(b * 2 + t - 2) * FF2 + bj * FF + jc0 + 4 * n) = acc[ai][bj][m][n];
.LBB0_609:
	s_waitcnt lgkmcnt(0)
	v_pk_fma_f32 v[128:129], v[114:115], v[138:139], v[118:119]
	v_pk_fma_f32 v[130:131], v[112:113], v[136:137], v[116:117]
	v_pk_fma_f32 v[128:129], v[110:111], v[134:135], v[128:129]
	v_pk_fma_f32 v[130:131], v[108:109], v[132:133], v[130:131]
	v_pk_fma_f32 v[128:129], v[126:127], v[98:99], v[128:129]
	v_pk_fma_f32 v[130:131], v[124:125], v[96:97], v[130:131]
	v_pk_fma_f32 v[134:135], v[104:105], v[144:145], v[120:121]
	v_pk_mul_f32 v[136:137], v[128:129], v[128:129]
	v_pk_fma_f32 v[134:135], v[100:101], v[140:141], v[134:135]
	v_pk_mul_f32 v[138:139], v[130:131], v[130:131]
	v_pk_fma_f32 v[136:137], v[136:137], s[84:85], v[246:247] op_sel_hi:[1,0,0]
	v_pk_fma_f32 v[138:139], v[138:139], s[84:85], v[246:247] op_sel_hi:[1,0,0]
	v_pk_mul_f32 v[136:137], v[128:129], v[136:137]
	v_pk_mul_f32 v[138:139], v[130:131], v[138:139]
	v_exp_f32_e32 v136, v136
	v_exp_f32_e32 v138, v138
	v_exp_f32_e32 v137, v137
	v_exp_f32_e32 v139, v139
	v_pk_fma_f32 v[132:133], v[106:107], v[146:147], v[122:123]
	v_pk_fma_f32 v[134:135], v[88:89], v[92:93], v[134:135]
	v_pk_add_f32 v[136:137], v[136:137], 1.0 op_sel_hi:[1,0]
	v_pk_add_f32 v[138:139], v[138:139], 1.0 op_sel_hi:[1,0]
	v_rcp_f32_e32 v136, v136
	v_rcp_f32_e32 v138, v138
	v_rcp_f32_e32 v137, v137
	v_rcp_f32_e32 v139, v139
	v_pk_fma_f32 v[132:133], v[102:103], v[142:143], v[132:133]
	v_pk_mul_f32 v[130:131], v[130:131], v[134:135]
	v_pk_fma_f32 v[132:133], v[90:91], v[94:95], v[132:133]
	v_pk_mul_f32 v[130:131], v[130:131], v[138:139]
	v_pk_mul_f32 v[128:129], v[128:129], v[132:133]
	v_pk_mul_f32 v[128:129], v[128:129], v[136:137]
	v_cvt_pk_bf16_f32 v130, v130, v131
	v_cvt_pk_bf16_f32 v131, v128, v129
	s_mul_i32 s100, s37, 0x80
	v_lshl_add_u64 v[144:145], v[178:179], 0, s[100:101]
	v_add_u32_e32 v146, v155, v215
	ds_bpermute_b32 v236, v244, v144
	ds_bpermute_b32 v237, v244, v145
	ds_bpermute_b32 v238, v244, v130
	ds_bpermute_b32 v239, v244, v131
	s_waitcnt lgkmcnt(0)
	global_store_dwordx2 v[236:237], v[238:239], off
	s_and_saveexec_b64 s[78:79], s[34:35]
	s_cbranch_execz .LBB0_611
	v_mov_b64_e32 v[128:129], s[24:25]
	v_mad_i64_i32 v[128:129], vcc, v146, s36, v[128:129]
	v_lshl_add_u64 v[128:129], v[196:197], 2, v[128:129]
	global_store_dwordx4 v[128:129], v[124:127], off
	v_add_co_u32_e32 v128, vcc, 0x2000, v128
	s_nop 1
	v_addc_co_u32_e32 v129, vcc, 0, v129, vcc
	global_store_dwordx4 v[128:129], v[88:91], off offset:3072
.LBB0_611:
	s_or_b64 exec, exec, s[78:79]
	v_add_u32_e32 v128, 0xffffc090, v225
	v_ashrrev_i32_e32 v128, 1, v128
	v_and_b32_e32 v147, 0xffffffee, v128
	s_and_b64 vcc, exec, s[22:23]
	s_mov_b64 s[78:79], -1
	s_cbranch_vccnz .LBB0_613
	v_or_b32_e32 v130, 1, v128
	v_mov_b64_e32 v[128:129], s[40:41]
	v_mad_i64_i32 v[130:131], vcc, v130, s36, v[128:129]
	v_mad_i64_i32 v[128:129], vcc, v147, s36, v[128:129]
	v_lshl_add_u64 v[142:143], v[130:131], 0, v[198:199]
	v_lshl_add_u64 v[140:141], v[128:129], 0, v[198:199]
	global_load_dwordx4 v[128:131], v[142:143], off
	global_load_dwordx4 v[132:135], v[140:141], off
	v_mov_b32_e32 v136, v84
	v_mov_b32_e32 v137, v84
	v_mov_b32_e32 v138, v85
	v_mov_b32_e32 v139, v85
	v_mov_b32_e32 v163, v86
	v_mov_b32_e32 v226, v87
	v_mov_b32_e32 v155, v86
	v_mov_b32_e32 v171, v87
	v_mov_b32_dpp v136, v136 row_ror:1 row_mask:0xf bank_mask:0xf
	v_mov_b32_dpp v137, v137 row_ror:2 row_mask:0xf bank_mask:0xf
	v_mov_b32_dpp v138, v138 row_ror:1 row_mask:0xf bank_mask:0xf
	v_mov_b32_dpp v139, v139 row_ror:2 row_mask:0xf bank_mask:0xf
	v_mov_b32_dpp v163, v163 row_ror:2 row_mask:0xf bank_mask:0xf
	v_mov_b32_dpp v226, v226 row_ror:2 row_mask:0xf bank_mask:0xf
	v_mov_b32_dpp v155, v155 row_ror:1 row_mask:0xf bank_mask:0xf
	v_mov_b32_dpp v171, v171 row_ror:1 row_mask:0xf bank_mask:0xf
	s_waitcnt vmcnt(1)
	v_cndmask_b32_e64 v137, v137, v128, s[14:15]
	v_cndmask_b32_e64 v128, v136, v128, s[12:13]
	v_cndmask_b32_e64 v136, v139, v129, s[14:15]
	v_cndmask_b32_e64 v129, v138, v129, s[12:13]
	v_cndmask_b32_e64 v138, v163, v130, s[14:15]
	v_cndmask_b32_e64 v139, v226, v131, s[14:15]
	v_cndmask_b32_e64 v130, v155, v130, s[12:13]
	v_cndmask_b32_e64 v131, v171, v131, s[12:13]
	s_waitcnt vmcnt(0)
	v_cndmask_b32_e64 v132, v137, v132, s[12:13]
	v_cndmask_b32_e64 v133, v136, v133, s[12:13]
	v_cndmask_b32_e64 v134, v138, v134, s[12:13]
	v_cndmask_b32_e64 v135, v139, v135, s[12:13]
	s_cbranch_execnz .LBB0_615
	s_branch .LBB0_614

; __device__ __forceinline__ f32x4 gelu_mul4(f32x4 x, f32x4 v) {
;     const f32x4 t = x * x;
;     const f32x4 u = t * (-2.0f * 0.7978845608028654f * 0.044715f * 1.4426950408889634f) + (-2.0f * 0.7978845608028654f * 1.4426950408889634f);
;     const f32x4 z = x * u;
;     __device__ __forceinline__ void operator()(const f32x4 (&acc)[2][2][4][2], const pg8::Unit& u, int wr, int wc, int fr, int fq, PG8_LAS unsigned char* xl) const {
;     ...
;                         const f32x4 cur = acc[ai][bj][m][n]; f32x4 p1, p2;
;                         if (!sample) { const f32x4 prv = (m == 0) ? hb[bj] : acc[ai][bj][m == 0 ? 0 : m - 1][n];
; #pragma unroll
;                             for (int j = 0; j < 4; ++j) { const float s1 = fr == 15 ? prv[j] : cur[j], s2 = fr >= 14 ? prv[j] : cur[j]; p1[j] = dpp_ror<1>(s1); p2[j] = dpp_ror<2>(s2); }
;                         } else { const int t = fr & 3, b = (row - MP) >> 2;
; #pragma unroll
;                             for (int j = 0; j < 4; ++j) { p1[j] = dpp_ror<1>(cur[j]); p2[j] = dpp_ror<2>(cur[j]); }
;                             const f32x4 c1 = *(const f32x4*)(ctx_s + (size_t)(b * 2 + 1) * FF2 + bj * FF + jc0 + 4 * n), c0 = *(const f32x4*)(ctx_s + (size_t)(b * 2) * FF2 + bj * FF + jc0 + 4 * n);
; #pragma unroll
;                             for (int j = 0; j < 4; ++j) { p2[j] = t == 0 ? c0[j] : (t == 1 ? c1[j] : p2[j]); p1[j] = t == 0 ? c1[j] : p1[j]; }
;                         }
;                         cc[bj] = bb[bj] + w0[bj] * p2 + w1[bj] * p1 + w2[bj] * cur;
;                     }
;                     const f32x4 gv = gelu_mul4(cc[0], cc[1]);
;                     u32x2 w; w.x = pk2(gv[0], gv[1]); w.y = pk2(gv[2], gv[3]);
;                     *(u32x2*)(G + (size_t)row * FF + jc0 + 4 * n) = w;
;                     if (!sample && ai == 0 && wr == 0 && m == 0 && fr < 2 && (pm & 7) != 0) {
; #pragma unroll
;                         for (int bj = 0; bj < 2; ++bj) *(f32x4*)(PH + (size_t)(pm * 2 + fr) * FF2 + bj * FF + jc0 + 4 * n) = cc[bj];
;                     }
;                     if (sample && (fr & 3) >= 2) { const int b = (row - MP) >> 2, t = fr & 3;
; #pragma unroll
;                         for (int bj = 0; bj < 2; ++bj) *(f32x4*)(nf_s + (size_t)(b * 2 + t - 2) * FF2 + bj * FF + jc0 + 4 * n) = acc[ai][bj][m][n];
.LBB0_619:
	v_pk_fma_f32 v[88:89], v[114:115], v[134:135], v[118:119]
	v_pk_fma_f32 v[90:91], v[112:113], v[132:133], v[116:117]
	v_pk_fma_f32 v[88:89], v[110:111], v[130:131], v[88:89]
	v_pk_fma_f32 v[90:91], v[108:109], v[128:129], v[90:91]
	v_pk_fma_f32 v[88:89], v[86:87], v[98:99], v[88:89]
	v_pk_fma_f32 v[90:91], v[84:85], v[96:97], v[90:91]
	v_pk_fma_f32 v[128:129], v[106:107], v[138:139], v[122:123]
	v_pk_fma_f32 v[130:131], v[104:105], v[136:137], v[120:121]
	v_pk_fma_f32 v[126:127], v[102:103], v[126:127], v[128:129]
	v_pk_fma_f32 v[124:125], v[100:101], v[124:125], v[130:131]
	v_pk_mul_f32 v[128:129], v[88:89], v[88:89]
	v_pk_mul_f32 v[130:131], v[90:91], v[90:91]
	v_pk_fma_f32 v[128:129], v[128:129], s[84:85], v[246:247] op_sel_hi:[1,0,0]
	v_pk_fma_f32 v[130:131], v[130:131], s[84:85], v[246:247] op_sel_hi:[1,0,0]
	v_pk_mul_f32 v[128:129], v[88:89], v[128:129]
	v_pk_mul_f32 v[130:131], v[90:91], v[130:131]
	v_exp_f32_e32 v128, v128
	v_exp_f32_e32 v130, v130
	v_exp_f32_e32 v129, v129
	v_exp_f32_e32 v131, v131
	v_pk_fma_f32 v[126:127], v[82:83], v[94:95], v[126:127]
	v_pk_fma_f32 v[124:125], v[80:81], v[92:93], v[124:125]
	v_pk_add_f32 v[128:129], v[128:129], 1.0 op_sel_hi:[1,0]
	v_pk_add_f32 v[130:131], v[130:131], 1.0 op_sel_hi:[1,0]
	v_rcp_f32_e32 v128, v128
	v_rcp_f32_e32 v130, v130
	v_rcp_f32_e32 v129, v129
	v_rcp_f32_e32 v131, v131
	v_pk_mul_f32 v[88:89], v[88:89], v[126:127]
	v_pk_mul_f32 v[90:91], v[90:91], v[124:125]
	v_pk_mul_f32 v[88:89], v[88:89], v[128:129]
	v_pk_mul_f32 v[90:91], v[90:91], v[130:131]
	v_cvt_pk_bf16_f32 v90, v90, v91
	v_cvt_pk_bf16_f32 v91, v88, v89
	s_mul_i32 s100, s37, 0x90
	v_lshl_add_u64 v[136:137], v[178:179], 0, s[100:101]
	v_add_u32_e32 v138, v147, v215
	ds_bpermute_b32 v236, v244, v136
	ds_bpermute_b32 v237, v244, v137
	ds_bpermute_b32 v238, v244, v90
	ds_bpermute_b32 v239, v244, v91
	s_waitcnt lgkmcnt(0)
	global_store_dwordx2 v[236:237], v[238:239], off
	s_and_saveexec_b64 s[78:79], s[34:35]
	s_cbranch_execz .LBB0_621
	v_mov_b64_e32 v[88:89], s[24:25]
	v_mad_i64_i32 v[88:89], vcc, v138, s36, v[88:89]
	v_lshl_add_u64 v[88:89], v[196:197], 2, v[88:89]
	global_store_dwordx4 v[88:89], v[84:87], off
	v_add_co_u32_e32 v88, vcc, 0x2000, v88
	s_nop 1
	v_addc_co_u32_e32 v89, vcc, 0, v89, vcc
	global_store_dwordx4 v[88:89], v[80:83], off offset:3072
.LBB0_621:
	s_or_b64 exec, exec, s[78:79]
	v_add_u32_e32 v88, 0xffffc0a0, v225
	v_ashrrev_i32_e32 v88, 1, v88
	v_and_b32_e32 v139, -10, v88
	s_and_b64 vcc, exec, s[22:23]
	s_mov_b64 s[78:79], -1
	s_cbranch_vccnz .LBB0_623
	v_or_b32_e32 v90, 1, v88
	v_mov_b64_e32 v[88:89], s[40:41]
	v_mad_i64_i32 v[90:91], vcc, v90, s36, v[88:89]
	v_mad_i64_i32 v[88:89], vcc, v139, s36, v[88:89]
	v_lshl_add_u64 v[134:135], v[90:91], 0, v[198:199]
	v_lshl_add_u64 v[132:133], v[88:89], 0, v[198:199]
	global_load_dwordx4 v[88:91], v[134:135], off
	global_load_dwordx4 v[124:127], v[132:133], off
	v_mov_b32_e32 v128, v76
	v_mov_b32_e32 v129, v76
	v_mov_b32_e32 v130, v77
	v_mov_b32_e32 v131, v77
	v_mov_b32_e32 v155, v78
	v_mov_b32_e32 v171, v79
	v_mov_b32_e32 v147, v78
	v_mov_b32_e32 v163, v79
	v_mov_b32_dpp v128, v128 row_ror:1 row_mask:0xf bank_mask:0xf
	v_mov_b32_dpp v129, v129 row_ror:2 row_mask:0xf bank_mask:0xf
	v_mov_b32_dpp v130, v130 row_ror:1 row_mask:0xf bank_mask:0xf
	v_mov_b32_dpp v131, v131 row_ror:2 row_mask:0xf bank_mask:0xf
	v_mov_b32_dpp v155, v155 row_ror:2 row_mask:0xf bank_mask:0xf
	v_mov_b32_dpp v171, v171 row_ror:2 row_mask:0xf bank_mask:0xf
	v_mov_b32_dpp v147, v147 row_ror:1 row_mask:0xf bank_mask:0xf
	v_mov_b32_dpp v163, v163 row_ror:1 row_mask:0xf bank_mask:0xf
	s_waitcnt vmcnt(1)
	v_cndmask_b32_e64 v129, v129, v88, s[14:15]
	v_cndmask_b32_e64 v88, v128, v88, s[12:13]
	v_cndmask_b32_e64 v128, v131, v89, s[14:15]
	v_cndmask_b32_e64 v89, v130, v89, s[12:13]
	v_cndmask_b32_e64 v130, v155, v90, s[14:15]
	v_cndmask_b32_e64 v131, v171, v91, s[14:15]
	v_cndmask_b32_e64 v90, v147, v90, s[12:13]
	v_cndmask_b32_e64 v91, v163, v91, s[12:13]
	s_waitcnt vmcnt(0)
	v_cndmask_b32_e64 v124, v129, v124, s[12:13]
	v_cndmask_b32_e64 v125, v128, v125, s[12:13]
	v_cndmask_b32_e64 v126, v130, v126, s[12:13]
	v_cndmask_b32_e64 v127, v131, v127, s[12:13]
	s_cbranch_execnz .LBB0_625
	s_branch .LBB0_624

; __device__ __forceinline__ f32x4 gelu_mul4(f32x4 x, f32x4 v) {
;     const f32x4 t = x * x;
;     const f32x4 u = t * (-2.0f * 0.7978845608028654f * 0.044715f * 1.4426950408889634f) + (-2.0f * 0.7978845608028654f * 1.4426950408889634f);
;     const f32x4 z = x * u;
;     __device__ __forceinline__ void operator()(const f32x4 (&acc)[2][2][4][2], const pg8::Unit& u, int wr, int wc, int fr, int fq, PG8_LAS unsigned char* xl) const {
;     ...
;                         const f32x4 cur = acc[ai][bj][m][n]; f32x4 p1, p2;
;                         if (!sample) { const f32x4 prv = (m == 0) ? hb[bj] : acc[ai][bj][m == 0 ? 0 : m - 1][n];
; #pragma unroll
;                             for (int j = 0; j < 4; ++j) { const float s1 = fr == 15 ? prv[j] : cur[j], s2 = fr >= 14 ? prv[j] : cur[j]; p1[j] = dpp_ror<1>(s1); p2[j] = dpp_ror<2>(s2); }
;                         } else { const int t = fr & 3, b = (row - MP) >> 2;
; #pragma unroll
;                             for (int j = 0; j < 4; ++j) { p1[j] = dpp_ror<1>(cur[j]); p2[j] = dpp_ror<2>(cur[j]); }
;                             const f32x4 c1 = *(const f32x4*)(ctx_s + (size_t)(b * 2 + 1) * FF2 + bj * FF + jc0 + 4 * n), c0 = *(const f32x4*)(ctx_s + (size_t)(b * 2) * FF2 + bj * FF + jc0 + 4 * n);
; #pragma unroll
;                             for (int j = 0; j < 4; ++j) { p2[j] = t == 0 ? c0[j] : (t == 1 ? c1[j] : p2[j]); p1[j] = t == 0 ? c1[j] : p1[j]; }
;                         }
;                         cc[bj] = bb[bj] + w0[bj] * p2 + w1[bj] * p1 + w2[bj] * cur;
;                     }
;                     const f32x4 gv = gelu_mul4(cc[0], cc[1]);
;                     u32x2 w; w.x = pk2(gv[0], gv[1]); w.y = pk2(gv[2], gv[3]);
;                     *(u32x2*)(G + (size_t)row * FF + jc0 + 4 * n) = w;
;                     if (!sample && ai == 0 && wr == 0 && m == 0 && fr < 2 && (pm & 7) != 0) {
; #pragma unroll
;                         for (int bj = 0; bj < 2; ++bj) *(f32x4*)(PH + (size_t)(pm * 2 + fr) * FF2 + bj * FF + jc0 + 4 * n) = cc[bj];
;                     }
;                     if (sample && (fr & 3) >= 2) { const int b = (row - MP) >> 2, t = fr & 3;
; #pragma unroll
;                         for (int bj = 0; bj < 2; ++bj) *(f32x4*)(nf_s + (size_t)(b * 2 + t - 2) * FF2 + bj * FF + jc0 + 4 * n) = acc[ai][bj][m][n];
.LBB0_629:
	v_pk_fma_f32 v[80:81], v[114:115], v[126:127], v[118:119]
	v_pk_fma_f32 v[82:83], v[112:113], v[124:125], v[116:117]
	v_pk_fma_f32 v[80:81], v[110:111], v[90:91], v[80:81]
	v_pk_fma_f32 v[82:83], v[108:109], v[88:89], v[82:83]
	v_pk_fma_f32 v[80:81], v[78:79], v[98:99], v[80:81]
	v_pk_fma_f32 v[82:83], v[76:77], v[96:97], v[82:83]
	v_pk_fma_f32 v[88:89], v[106:107], v[130:131], v[122:123]
	v_pk_fma_f32 v[90:91], v[104:105], v[128:129], v[120:121]
	v_pk_fma_f32 v[86:87], v[102:103], v[86:87], v[88:89]
	v_pk_fma_f32 v[84:85], v[100:101], v[84:85], v[90:91]
	v_pk_mul_f32 v[88:89], v[80:81], v[80:81]
	v_pk_mul_f32 v[90:91], v[82:83], v[82:83]
	v_pk_fma_f32 v[88:89], v[88:89], s[84:85], v[246:247] op_sel_hi:[1,0,0]
	v_pk_fma_f32 v[90:91], v[90:91], s[84:85], v[246:247] op_sel_hi:[1,0,0]
	v_pk_mul_f32 v[88:89], v[80:81], v[88:89]
	v_pk_mul_f32 v[90:91], v[82:83], v[90:91]
	v_exp_f32_e32 v88, v88
	v_exp_f32_e32 v90, v90
	v_exp_f32_e32 v89, v89
	v_exp_f32_e32 v91, v91
	v_pk_fma_f32 v[86:87], v[74:75], v[94:95], v[86:87]
	v_pk_fma_f32 v[84:85], v[72:73], v[92:93], v[84:85]
	v_pk_add_f32 v[88:89], v[88:89], 1.0 op_sel_hi:[1,0]
	v_pk_add_f32 v[90:91], v[90:91], 1.0 op_sel_hi:[1,0]
	v_rcp_f32_e32 v88, v88
	v_rcp_f32_e32 v90, v90
	v_rcp_f32_e32 v89, v89
	v_rcp_f32_e32 v91, v91
	v_pk_mul_f32 v[80:81], v[80:81], v[86:87]
	v_pk_mul_f32 v[82:83], v[82:83], v[84:85]
	v_pk_mul_f32 v[80:81], v[80:81], v[88:89]
	v_pk_mul_f32 v[82:83], v[82:83], v[90:91]
	v_cvt_pk_bf16_f32 v82, v82, v83
	v_cvt_pk_bf16_f32 v83, v80, v81
	s_mul_i32 s100, s37, 0xa0
	v_lshl_add_u64 v[128:129], v[178:179], 0, s[100:101]
	v_add_u32_e32 v139, v139, v215
	ds_bpermute_b32 v236, v244, v128
	ds_bpermute_b32 v237, v244, v129
	ds_bpermute_b32 v238, v244, v82
	ds_bpermute_b32 v239, v244, v83
	s_waitcnt lgkmcnt(0)
	global_store_dwordx2 v[236:237], v[238:239], off
	s_and_saveexec_b64 s[78:79], s[34:35]
	s_cbranch_execz .LBB0_631
	v_mov_b64_e32 v[80:81], s[24:25]
	v_mad_i64_i32 v[80:81], vcc, v139, s36, v[80:81]
	v_lshl_add_u64 v[80:81], v[196:197], 2, v[80:81]
	global_store_dwordx4 v[80:81], v[76:79], off
	v_add_co_u32_e32 v80, vcc, 0x2000, v80
	s_nop 1
	v_addc_co_u32_e32 v81, vcc, 0, v81, vcc
	global_store_dwordx4 v[80:81], v[72:75], off offset:3072
.LBB0_631:
	s_or_b64 exec, exec, s[78:79]
	v_add_u32_e32 v80, 0xffffc0b0, v225
	v_ashrrev_i32_e32 v80, 1, v80
	v_and_b32_e32 v147, -2, v80
	s_and_b64 vcc, exec, s[22:23]
	s_mov_b64 s[78:79], -1
	s_cbranch_vccnz .LBB0_633
	v_or_b32_e32 v82, 1, v80
	v_mov_b64_e32 v[80:81], s[40:41]
	v_mad_i64_i32 v[82:83], vcc, v82, s36, v[80:81]
	v_mad_i64_i32 v[80:81], vcc, v147, s36, v[80:81]
	v_lshl_add_u64 v[126:127], v[82:83], 0, v[198:199]
	v_lshl_add_u64 v[124:125], v[80:81], 0, v[198:199]
	global_load_dwordx4 v[80:83], v[126:127], off
	global_load_dwordx4 v[84:87], v[124:125], off
	v_mov_b32_e32 v88, v12
	v_mov_b32_e32 v89, v12
	v_mov_b32_e32 v90, v13
	v_mov_b32_e32 v91, v13
	v_mov_b32_e32 v131, v14
	v_mov_b32_e32 v163, v15
	v_mov_b32_e32 v130, v14
	v_mov_b32_e32 v155, v15
	v_mov_b32_dpp v88, v88 row_ror:1 row_mask:0xf bank_mask:0xf
	v_mov_b32_dpp v89, v89 row_ror:2 row_mask:0xf bank_mask:0xf
	v_mov_b32_dpp v90, v90 row_ror:1 row_mask:0xf bank_mask:0xf
	v_mov_b32_dpp v91, v91 row_ror:2 row_mask:0xf bank_mask:0xf
	v_mov_b32_dpp v131, v131 row_ror:2 row_mask:0xf bank_mask:0xf
	v_mov_b32_dpp v163, v163 row_ror:2 row_mask:0xf bank_mask:0xf
	v_mov_b32_dpp v130, v130 row_ror:1 row_mask:0xf bank_mask:0xf
	v_mov_b32_dpp v155, v155 row_ror:1 row_mask:0xf bank_mask:0xf
	s_waitcnt vmcnt(1)
	v_cndmask_b32_e64 v89, v89, v80, s[14:15]
	v_cndmask_b32_e64 v80, v88, v80, s[12:13]
	v_cndmask_b32_e64 v88, v91, v81, s[14:15]
	v_cndmask_b32_e64 v81, v90, v81, s[12:13]
	v_cndmask_b32_e64 v90, v131, v82, s[14:15]
	v_cndmask_b32_e64 v91, v163, v83, s[14:15]
	v_cndmask_b32_e64 v82, v130, v82, s[12:13]
	v_cndmask_b32_e64 v83, v155, v83, s[12:13]
	s_waitcnt vmcnt(0)
	v_cndmask_b32_e64 v84, v89, v84, s[12:13]
	v_cndmask_b32_e64 v85, v88, v85, s[12:13]
	v_cndmask_b32_e64 v86, v90, v86, s[12:13]
	v_cndmask_b32_e64 v87, v91, v87, s[12:13]
	s_cbranch_execnz .LBB0_635
	s_branch .LBB0_634

; __device__ __forceinline__ unsigned pk2(float lo, float hi) { const f32x2 v = {lo, hi}; const bf16x2_t b = __builtin_convertvector(v, bf16x2_t); return __builtin_bit_cast(unsigned, b); }
; __device__ __forceinline__ f32x4 gelu_mul4(f32x4 x, f32x4 v) {
;     const f32x4 t = x * x;
;     const f32x4 u = t * (-2.0f * 0.7978845608028654f * 0.044715f * 1.4426950408889634f) + (-2.0f * 0.7978845608028654f * 1.4426950408889634f);
;     const f32x4 z = x * u;
;     f32x4 d; d[0] = __builtin_amdgcn_exp2f(z[0]); d[1] = __builtin_amdgcn_exp2f(z[1]); d[2] = __builtin_amdgcn_exp2f(z[2]); d[3] = __builtin_amdgcn_exp2f(z[3]);
;     d = d + 1.0f;
;     f32x4 r; r[0] = __builtin_amdgcn_rcpf(d[0]); r[1] = __builtin_amdgcn_rcpf(d[1]); r[2] = __builtin_amdgcn_rcpf(d[2]); r[3] = __builtin_amdgcn_rcpf(d[3]);
;     return (x * v) * r;
; }
;     __device__ __forceinline__ void operator()(const f32x4 (&acc)[2][2][4][2], const pg8::Unit& u, int wr, int wc, int fr, int fq, PG8_LAS unsigned char* xl) const {
;     ...
;                         cc[bj] = bb[bj] + w0[bj] * p2 + w1[bj] * p1 + w2[bj] * cur;
;                     }
;                     const f32x4 gv = gelu_mul4(cc[0], cc[1]);
;                     u32x2 w; w.x = pk2(gv[0], gv[1]); w.y = pk2(gv[2], gv[3]);
;                     *(u32x2*)(G + (size_t)row * FF + jc0 + 4 * n) = w;
;                     if (!sample && ai == 0 && wr == 0 && m == 0 && fr < 2 && (pm & 7) != 0) {
; #pragma unroll
;                         for (int bj = 0; bj < 2; ++bj) *(f32x4*)(PH + (size_t)(pm * 2 + fr) * FF2 + bj * FF + jc0 + 4 * n) = cc[bj];
;                     }
;                     if (sample && (fr & 3) >= 2) { const int b = (row - MP) >> 2, t = fr & 3;
; #pragma unroll
;                         for (int bj = 0; bj < 2; ++bj) *(f32x4*)(nf_s + (size_t)(b * 2 + t - 2) * FF2 + bj * FF + jc0 + 4 * n) = acc[ai][bj][m][n];
.LBB0_639:
	v_pk_fma_f32 v[72:73], v[114:115], v[86:87], v[118:119]
	v_pk_fma_f32 v[74:75], v[112:113], v[84:85], v[116:117]
	v_pk_fma_f32 v[72:73], v[110:111], v[82:83], v[72:73]
	v_pk_fma_f32 v[74:75], v[108:109], v[80:81], v[74:75]
	v_pk_fma_f32 v[72:73], v[14:15], v[98:99], v[72:73]
	v_pk_fma_f32 v[74:75], v[12:13], v[96:97], v[74:75]
	v_pk_fma_f32 v[80:81], v[106:107], v[90:91], v[122:123]
	v_pk_fma_f32 v[82:83], v[104:105], v[88:89], v[120:121]
	v_pk_fma_f32 v[78:79], v[102:103], v[78:79], v[80:81]
	v_pk_fma_f32 v[76:77], v[100:101], v[76:77], v[82:83]
	v_pk_mul_f32 v[80:81], v[72:73], v[72:73]
	v_pk_mul_f32 v[82:83], v[74:75], v[74:75]
	v_pk_fma_f32 v[80:81], v[80:81], s[84:85], v[246:247] op_sel_hi:[1,0,0]
	v_pk_fma_f32 v[82:83], v[82:83], s[84:85], v[246:247] op_sel_hi:[1,0,0]
	v_pk_mul_f32 v[80:81], v[72:73], v[80:81]
	v_pk_mul_f32 v[82:83], v[74:75], v[82:83]
	v_exp_f32_e32 v80, v80
	v_exp_f32_e32 v82, v82
	v_exp_f32_e32 v81, v81
	v_exp_f32_e32 v83, v83
	v_pk_fma_f32 v[78:79], v[6:7], v[94:95], v[78:79]
	v_pk_fma_f32 v[76:77], v[4:5], v[92:93], v[76:77]
	v_pk_add_f32 v[80:81], v[80:81], 1.0 op_sel_hi:[1,0]
	v_pk_add_f32 v[82:83], v[82:83], 1.0 op_sel_hi:[1,0]
	v_rcp_f32_e32 v80, v80
	v_rcp_f32_e32 v82, v82
	v_rcp_f32_e32 v81, v81
	v_rcp_f32_e32 v83, v83
	v_pk_mul_f32 v[72:73], v[72:73], v[78:79]
	v_pk_mul_f32 v[74:75], v[74:75], v[76:77]
	v_pk_mul_f32 v[72:73], v[72:73], v[80:81]
	v_pk_mul_f32 v[74:75], v[74:75], v[82:83]
	v_cvt_pk_bf16_f32 v74, v74, v75
	v_cvt_pk_bf16_f32 v75, v72, v73
	s_mul_i32 s100, s37, 0xb0
	v_lshl_add_u64 v[130:131], v[178:179], 0, s[100:101]
	v_add_u32_e32 v147, v147, v215
	ds_bpermute_b32 v236, v244, v130
	ds_bpermute_b32 v237, v244, v131
	ds_bpermute_b32 v238, v244, v74
	ds_bpermute_b32 v239, v244, v75
	s_waitcnt lgkmcnt(0)
	global_store_dwordx2 v[236:237], v[238:239], off
	s_and_saveexec_b64 s[78:79], s[34:35]
	s_cbranch_execz .LBB0_641
	v_mov_b64_e32 v[72:73], s[24:25]
	v_mad_i64_i32 v[72:73], vcc, v147, s36, v[72:73]
	v_lshl_add_u64 v[72:73], v[196:197], 2, v[72:73]
	global_store_dwordx4 v[72:73], v[12:15], off
	v_add_co_u32_e32 v72, vcc, 0x2000, v72
	s_nop 1
	v_addc_co_u32_e32 v73, vcc, 0, v73, vcc
	global_store_dwordx4 v[72:73], v[4:7], off offset:3072

; __device__ __forceinline__ unsigned pk2(float lo, float hi) { const f32x2 v = {lo, hi}; const bf16x2_t b = __builtin_convertvector(v, bf16x2_t); return __builtin_bit_cast(unsigned, b); }
; __device__ __forceinline__ f32x4 gelu_mul4(f32x4 x, f32x4 v) {
;     const f32x4 t = x * x;
;     const f32x4 u = t * (-2.0f * 0.7978845608028654f * 0.044715f * 1.4426950408889634f) + (-2.0f * 0.7978845608028654f * 1.4426950408889634f);
;     const f32x4 z = x * u;
;     f32x4 d; d[0] = __builtin_amdgcn_exp2f(z[0]); d[1] = __builtin_amdgcn_exp2f(z[1]); d[2] = __builtin_amdgcn_exp2f(z[2]); d[3] = __builtin_amdgcn_exp2f(z[3]);
;     d = d + 1.0f;
;     f32x4 r; r[0] = __builtin_amdgcn_rcpf(d[0]); r[1] = __builtin_amdgcn_rcpf(d[1]); r[2] = __builtin_amdgcn_rcpf(d[2]); r[3] = __builtin_amdgcn_rcpf(d[3]);
;     return (x * v) * r;
; }
;     __device__ __forceinline__ void operator()(const f32x4 (&acc)[2][2][4][2], const pg8::Unit& u, int wr, int wc, int fr, int fq, PG8_LAS unsigned char* xl) const {
;     ...
;                         cc[bj] = bb[bj] + w0[bj] * p2 + w1[bj] * p1 + w2[bj] * cur;
;                     }
;                     const f32x4 gv = gelu_mul4(cc[0], cc[1]);
;                     u32x2 w; w.x = pk2(gv[0], gv[1]); w.y = pk2(gv[2], gv[3]);
;                     *(u32x2*)(G + (size_t)row * FF + jc0 + 4 * n) = w;
;                     if (!sample && ai == 0 && wr == 0 && m == 0 && fr < 2 && (pm & 7) != 0) {
; #pragma unroll
;                         for (int bj = 0; bj < 2; ++bj) *(f32x4*)(PH + (size_t)(pm * 2 + fr) * FF2 + bj * FF + jc0 + 4 * n) = cc[bj];
;                     }
;                     if (sample && (fr & 3) >= 2) { const int b = (row - MP) >> 2, t = fr & 3;
; #pragma unroll
;                         for (int bj = 0; bj < 2; ++bj) *(f32x4*)(nf_s + (size_t)(b * 2 + t - 2) * FF2 + bj * FF + jc0 + 4 * n) = acc[ai][bj][m][n];
.LBB0_651:
	s_waitcnt vmcnt(4) lgkmcnt(0)
	v_pk_fma_f32 v[104:105], v[94:95], v[114:115], v[102:103]
	v_pk_fma_f32 v[106:107], v[92:93], v[112:113], v[100:101]
	v_pk_fma_f32 v[104:105], v[90:91], v[110:111], v[104:105]
	v_pk_fma_f32 v[108:109], v[88:89], v[108:109], v[106:107]
	v_pk_fma_f32 v[106:107], v[70:71], v[82:83], v[104:105]
	v_pk_fma_f32 v[104:105], v[68:69], v[80:81], v[108:109]
	s_waitcnt vmcnt(0)
	v_pk_fma_f32 v[110:111], v[84:85], v[120:121], v[96:97]
	v_pk_mul_f32 v[114:115], v[104:105], v[104:105]
	v_pk_fma_f32 v[112:113], v[76:77], v[116:117], v[110:111]
	v_pk_mul_f32 v[110:111], v[106:107], v[106:107]
	v_pk_fma_f32 v[110:111], v[110:111], s[84:85], v[246:247] op_sel_hi:[1,0,0]
	v_pk_fma_f32 v[114:115], v[114:115], s[84:85], v[246:247] op_sel_hi:[1,0,0]
	v_pk_mul_f32 v[110:111], v[106:107], v[110:111]
	v_pk_mul_f32 v[114:115], v[104:105], v[114:115]
	v_exp_f32_e32 v116, v110
	v_exp_f32_e32 v114, v114
	v_exp_f32_e32 v117, v111
	v_exp_f32_e32 v115, v115
	v_pk_fma_f32 v[108:109], v[86:87], v[122:123], v[98:99]
	v_pk_add_f32 v[114:115], v[114:115], 1.0 op_sel_hi:[1,0]
	v_pk_fma_f32 v[108:109], v[78:79], v[118:119], v[108:109]
	v_rcp_f32_e32 v114, v114
	v_pk_fma_f32 v[110:111], v[66:67], v[74:75], v[108:109]
	v_pk_fma_f32 v[108:109], v[64:65], v[72:73], v[112:113]
	v_pk_add_f32 v[112:113], v[116:117], 1.0 op_sel_hi:[1,0]
	v_rcp_f32_e32 v115, v115
	v_rcp_f32_e32 v112, v112
	v_rcp_f32_e32 v113, v113
	v_pk_mul_f32 v[116:117], v[106:107], v[110:111]
	v_pk_mul_f32 v[118:119], v[104:105], v[108:109]
	v_pk_mul_f32 v[112:113], v[116:117], v[112:113]
	v_pk_mul_f32 v[114:115], v[118:119], v[114:115]
	s_nop 0
	v_cvt_pk_bf16_f32 v114, v114, v115
	v_cvt_pk_bf16_f32 v115, v112, v113
	ds_bpermute_b32 v236, v244, v178
	ds_bpermute_b32 v237, v244, v179
	ds_bpermute_b32 v238, v244, v114
	ds_bpermute_b32 v239, v244, v115
	s_waitcnt lgkmcnt(0)
	global_store_dwordx2 v[236:237], v[238:239], off offset:8
	s_and_saveexec_b64 s[58:59], s[6:7]
	s_cbranch_execz .LBB0_653
	global_store_dwordx4 v[176:177], v[104:107], off offset:16
	s_nop 1
	v_add_co_u32_e32 v104, vcc, 0x2000, v176
	s_nop 1
	v_addc_co_u32_e32 v105, vcc, 0, v177, vcc
	global_store_dwordx4 v[104:105], v[108:111], off offset:3088
	s_or_b64 exec, exec, s[58:59]
	s_and_saveexec_b64 s[6:7], s[34:35]
	s_cbranch_execz .LBB0_655
	s_branch .LBB0_654

; __device__ __forceinline__ unsigned pk2(float lo, float hi) { const f32x2 v = {lo, hi}; const bf16x2_t b = __builtin_convertvector(v, bf16x2_t); return __builtin_bit_cast(unsigned, b); }
; __device__ __forceinline__ f32x4 gelu_mul4(f32x4 x, f32x4 v) {
;     const f32x4 t = x * x;
;     const f32x4 u = t * (-2.0f * 0.7978845608028654f * 0.044715f * 1.4426950408889634f) + (-2.0f * 0.7978845608028654f * 1.4426950408889634f);
;     const f32x4 z = x * u;
;     f32x4 d; d[0] = __builtin_amdgcn_exp2f(z[0]); d[1] = __builtin_amdgcn_exp2f(z[1]); d[2] = __builtin_amdgcn_exp2f(z[2]); d[3] = __builtin_amdgcn_exp2f(z[3]);
;     d = d + 1.0f;
;     f32x4 r; r[0] = __builtin_amdgcn_rcpf(d[0]); r[1] = __builtin_amdgcn_rcpf(d[1]); r[2] = __builtin_amdgcn_rcpf(d[2]); r[3] = __builtin_amdgcn_rcpf(d[3]);
;     return (x * v) * r;
; }
;     __device__ __forceinline__ void operator()(const f32x4 (&acc)[2][2][4][2], const pg8::Unit& u, int wr, int wc, int fr, int fq, PG8_LAS unsigned char* xl) const {
;     ...
;                         cc[bj] = bb[bj] + w0[bj] * p2 + w1[bj] * p1 + w2[bj] * cur;
;                     }
;                     const f32x4 gv = gelu_mul4(cc[0], cc[1]);
;                     u32x2 w; w.x = pk2(gv[0], gv[1]); w.y = pk2(gv[2], gv[3]);
;                     *(u32x2*)(G + (size_t)row * FF + jc0 + 4 * n) = w;
;                     if (!sample && ai == 0 && wr == 0 && m == 0 && fr < 2 && (pm & 7) != 0) {
; #pragma unroll
;                         for (int bj = 0; bj < 2; ++bj) *(f32x4*)(PH + (size_t)(pm * 2 + fr) * FF2 + bj * FF + jc0 + 4 * n) = cc[bj];
;                     }
;                     if (sample && (fr & 3) >= 2) { const int b = (row - MP) >> 2, t = fr & 3;
; #pragma unroll
;                         for (int bj = 0; bj < 2; ++bj) *(f32x4*)(nf_s + (size_t)(b * 2 + t - 2) * FF2 + bj * FF + jc0 + 4 * n) = acc[ai][bj][m][n];
.LBB0_663:
	v_pk_fma_f32 v[64:65], v[94:95], v[110:111], v[102:103]
	v_pk_fma_f32 v[66:67], v[92:93], v[108:109], v[100:101]
	v_pk_fma_f32 v[64:65], v[90:91], v[106:107], v[64:65]
	v_pk_fma_f32 v[66:67], v[88:89], v[104:105], v[66:67]
	v_pk_fma_f32 v[64:65], v[62:63], v[82:83], v[64:65]
	v_pk_fma_f32 v[66:67], v[60:61], v[80:81], v[66:67]
	v_pk_fma_f32 v[104:105], v[86:87], v[114:115], v[98:99]
	v_pk_fma_f32 v[106:107], v[84:85], v[112:113], v[96:97]
	v_pk_fma_f32 v[70:71], v[78:79], v[70:71], v[104:105]
	v_pk_fma_f32 v[68:69], v[76:77], v[68:69], v[106:107]
	v_pk_mul_f32 v[104:105], v[64:65], v[64:65]
	v_pk_mul_f32 v[106:107], v[66:67], v[66:67]
	v_pk_fma_f32 v[104:105], v[104:105], s[84:85], v[246:247] op_sel_hi:[1,0,0]
	v_pk_fma_f32 v[106:107], v[106:107], s[84:85], v[246:247] op_sel_hi:[1,0,0]
	v_pk_mul_f32 v[104:105], v[64:65], v[104:105]
	v_pk_mul_f32 v[106:107], v[66:67], v[106:107]
	v_exp_f32_e32 v104, v104
	v_exp_f32_e32 v106, v106
	v_exp_f32_e32 v105, v105
	v_exp_f32_e32 v107, v107
	v_pk_fma_f32 v[70:71], v[58:59], v[74:75], v[70:71]
	v_pk_fma_f32 v[68:69], v[56:57], v[72:73], v[68:69]
	v_pk_add_f32 v[104:105], v[104:105], 1.0 op_sel_hi:[1,0]
	v_pk_add_f32 v[106:107], v[106:107], 1.0 op_sel_hi:[1,0]
	v_rcp_f32_e32 v104, v104
	v_rcp_f32_e32 v106, v106
	v_rcp_f32_e32 v105, v105
	v_rcp_f32_e32 v107, v107
	v_pk_mul_f32 v[64:65], v[64:65], v[70:71]
	v_pk_mul_f32 v[66:67], v[66:67], v[68:69]
	v_pk_mul_f32 v[64:65], v[64:65], v[104:105]
	v_pk_mul_f32 v[66:67], v[66:67], v[106:107]
	s_nop 0
	v_cvt_pk_bf16_f32 v66, v66, v67
	v_cvt_pk_bf16_f32 v67, v64, v65
	ds_bpermute_b32 v236, v244, v168
	ds_bpermute_b32 v237, v244, v169
	ds_bpermute_b32 v238, v244, v66
	ds_bpermute_b32 v239, v244, v67
	s_waitcnt lgkmcnt(0)
	global_store_dwordx2 v[236:237], v[238:239], off offset:8
	s_and_saveexec_b64 s[6:7], s[34:35]
	s_cbranch_execz .LBB0_665
	v_mov_b64_e32 v[64:65], s[24:25]
	v_mad_i64_i32 v[64:65], s[58:59], v170, s36, v[64:65]
	v_lshl_add_u64 v[64:65], v[196:197], 2, v[64:65]
	global_store_dwordx4 v[64:65], v[60:63], off offset:16
	v_add_co_u32_e32 v64, vcc, 0x2000, v64
	s_nop 1
	v_addc_co_u32_e32 v65, vcc, 0, v65, vcc
	global_store_dwordx4 v[64:65], v[56:59], off offset:3088

; __device__ __forceinline__ unsigned pk2(float lo, float hi) { const f32x2 v = {lo, hi}; const bf16x2_t b = __builtin_convertvector(v, bf16x2_t); return __builtin_bit_cast(unsigned, b); }
; __device__ __forceinline__ f32x4 gelu_mul4(f32x4 x, f32x4 v) {
;     const f32x4 t = x * x;
;     const f32x4 u = t * (-2.0f * 0.7978845608028654f * 0.044715f * 1.4426950408889634f) + (-2.0f * 0.7978845608028654f * 1.4426950408889634f);
;     const f32x4 z = x * u;
;     f32x4 d; d[0] = __builtin_amdgcn_exp2f(z[0]); d[1] = __builtin_amdgcn_exp2f(z[1]); d[2] = __builtin_amdgcn_exp2f(z[2]); d[3] = __builtin_amdgcn_exp2f(z[3]);
;     d = d + 1.0f;
;     f32x4 r; r[0] = __builtin_amdgcn_rcpf(d[0]); r[1] = __builtin_amdgcn_rcpf(d[1]); r[2] = __builtin_amdgcn_rcpf(d[2]); r[3] = __builtin_amdgcn_rcpf(d[3]);
;     return (x * v) * r;
; }
;     __device__ __forceinline__ void operator()(const f32x4 (&acc)[2][2][4][2], const pg8::Unit& u, int wr, int wc, int fr, int fq, PG8_LAS unsigned char* xl) const {
;     ...
;                         cc[bj] = bb[bj] + w0[bj] * p2 + w1[bj] * p1 + w2[bj] * cur;
;                     }
;                     const f32x4 gv = gelu_mul4(cc[0], cc[1]);
;                     u32x2 w; w.x = pk2(gv[0], gv[1]); w.y = pk2(gv[2], gv[3]);
;                     *(u32x2*)(G + (size_t)row * FF + jc0 + 4 * n) = w;
;                     if (!sample && ai == 0 && wr == 0 && m == 0 && fr < 2 && (pm & 7) != 0) {
; #pragma unroll
;                         for (int bj = 0; bj < 2; ++bj) *(f32x4*)(PH + (size_t)(pm * 2 + fr) * FF2 + bj * FF + jc0 + 4 * n) = cc[bj];
;                     }
;                     if (sample && (fr & 3) >= 2) { const int b = (row - MP) >> 2, t = fr & 3;
; #pragma unroll
;                         for (int bj = 0; bj < 2; ++bj) *(f32x4*)(nf_s + (size_t)(b * 2 + t - 2) * FF2 + bj * FF + jc0 + 4 * n) = acc[ai][bj][m][n];
.LBB0_673:
	v_pk_fma_f32 v[56:57], v[94:95], v[70:71], v[102:103]
	v_pk_fma_f32 v[58:59], v[92:93], v[68:69], v[100:101]
	v_pk_fma_f32 v[56:57], v[90:91], v[66:67], v[56:57]
	v_pk_fma_f32 v[58:59], v[88:89], v[64:65], v[58:59]
	v_pk_fma_f32 v[56:57], v[54:55], v[82:83], v[56:57]
	v_pk_fma_f32 v[58:59], v[52:53], v[80:81], v[58:59]
	v_pk_fma_f32 v[64:65], v[86:87], v[106:107], v[98:99]
	v_pk_fma_f32 v[66:67], v[84:85], v[104:105], v[96:97]
	v_pk_fma_f32 v[62:63], v[78:79], v[62:63], v[64:65]
	v_pk_fma_f32 v[60:61], v[76:77], v[60:61], v[66:67]
	v_pk_mul_f32 v[64:65], v[56:57], v[56:57]
	v_pk_mul_f32 v[66:67], v[58:59], v[58:59]
	v_pk_fma_f32 v[64:65], v[64:65], s[84:85], v[246:247] op_sel_hi:[1,0,0]
	v_pk_fma_f32 v[66:67], v[66:67], s[84:85], v[246:247] op_sel_hi:[1,0,0]
	v_pk_mul_f32 v[64:65], v[56:57], v[64:65]
	v_pk_mul_f32 v[66:67], v[58:59], v[66:67]
	v_exp_f32_e32 v64, v64
	v_exp_f32_e32 v66, v66
	v_exp_f32_e32 v65, v65
	v_exp_f32_e32 v67, v67
	v_pk_fma_f32 v[62:63], v[50:51], v[74:75], v[62:63]
	v_pk_fma_f32 v[60:61], v[48:49], v[72:73], v[60:61]
	v_pk_add_f32 v[64:65], v[64:65], 1.0 op_sel_hi:[1,0]
	v_pk_add_f32 v[66:67], v[66:67], 1.0 op_sel_hi:[1,0]
	v_rcp_f32_e32 v64, v64
	v_rcp_f32_e32 v66, v66
	v_rcp_f32_e32 v65, v65
	v_rcp_f32_e32 v67, v67
	v_pk_mul_f32 v[56:57], v[56:57], v[62:63]
	v_pk_mul_f32 v[58:59], v[58:59], v[60:61]
	v_pk_mul_f32 v[56:57], v[56:57], v[64:65]
	v_pk_mul_f32 v[58:59], v[58:59], v[66:67]
	s_nop 0
	v_cvt_pk_bf16_f32 v58, v58, v59
	v_cvt_pk_bf16_f32 v59, v56, v57
	ds_bpermute_b32 v236, v244, v160
	ds_bpermute_b32 v237, v244, v161
	ds_bpermute_b32 v238, v244, v58
	ds_bpermute_b32 v239, v244, v59
	s_waitcnt lgkmcnt(0)
	global_store_dwordx2 v[236:237], v[238:239], off offset:8
	s_and_saveexec_b64 s[6:7], s[34:35]
	s_cbranch_execz .LBB0_675
	v_mov_b64_e32 v[56:57], s[24:25]
	v_mad_i64_i32 v[56:57], s[58:59], v162, s36, v[56:57]
	v_lshl_add_u64 v[56:57], v[196:197], 2, v[56:57]
	global_store_dwordx4 v[56:57], v[52:55], off offset:16
	v_add_co_u32_e32 v56, vcc, 0x2000, v56
	s_nop 1
	v_addc_co_u32_e32 v57, vcc, 0, v57, vcc
	global_store_dwordx4 v[56:57], v[48:51], off offset:3088

; __device__ __forceinline__ unsigned pk2(float lo, float hi) { const f32x2 v = {lo, hi}; const bf16x2_t b = __builtin_convertvector(v, bf16x2_t); return __builtin_bit_cast(unsigned, b); }
; __device__ __forceinline__ f32x4 gelu_mul4(f32x4 x, f32x4 v) {
;     const f32x4 t = x * x;
;     const f32x4 u = t * (-2.0f * 0.7978845608028654f * 0.044715f * 1.4426950408889634f) + (-2.0f * 0.7978845608028654f * 1.4426950408889634f);
;     const f32x4 z = x * u;
;     f32x4 d; d[0] = __builtin_amdgcn_exp2f(z[0]); d[1] = __builtin_amdgcn_exp2f(z[1]); d[2] = __builtin_amdgcn_exp2f(z[2]); d[3] = __builtin_amdgcn_exp2f(z[3]);
;     d = d + 1.0f;
;     f32x4 r; r[0] = __builtin_amdgcn_rcpf(d[0]); r[1] = __builtin_amdgcn_rcpf(d[1]); r[2] = __builtin_amdgcn_rcpf(d[2]); r[3] = __builtin_amdgcn_rcpf(d[3]);
;     return (x * v) * r;
; }
;     __device__ __forceinline__ void operator()(const f32x4 (&acc)[2][2][4][2], const pg8::Unit& u, int wr, int wc, int fr, int fq, PG8_LAS unsigned char* xl) const {
;     ...
;                         cc[bj] = bb[bj] + w0[bj] * p2 + w1[bj] * p1 + w2[bj] * cur;
;                     }
;                     const f32x4 gv = gelu_mul4(cc[0], cc[1]);
;                     u32x2 w; w.x = pk2(gv[0], gv[1]); w.y = pk2(gv[2], gv[3]);
;                     *(u32x2*)(G + (size_t)row * FF + jc0 + 4 * n) = w;
;                     if (!sample && ai == 0 && wr == 0 && m == 0 && fr < 2 && (pm & 7) != 0) {
; #pragma unroll
;                         for (int bj = 0; bj < 2; ++bj) *(f32x4*)(PH + (size_t)(pm * 2 + fr) * FF2 + bj * FF + jc0 + 4 * n) = cc[bj];
;                     }
;                     if (sample && (fr & 3) >= 2) { const int b = (row - MP) >> 2, t = fr & 3;
; #pragma unroll
;                         for (int bj = 0; bj < 2; ++bj) *(f32x4*)(nf_s + (size_t)(b * 2 + t - 2) * FF2 + bj * FF + jc0 + 4 * n) = acc[ai][bj][m][n];
.LBB0_683:
	v_pk_fma_f32 v[48:49], v[94:95], v[62:63], v[102:103]
	v_pk_fma_f32 v[50:51], v[92:93], v[60:61], v[100:101]
	v_pk_fma_f32 v[48:49], v[90:91], v[58:59], v[48:49]
	v_pk_fma_f32 v[50:51], v[88:89], v[56:57], v[50:51]
	v_pk_fma_f32 v[48:49], v[46:47], v[82:83], v[48:49]
	v_pk_fma_f32 v[50:51], v[44:45], v[80:81], v[50:51]
	v_pk_fma_f32 v[56:57], v[86:87], v[66:67], v[98:99]
	v_pk_fma_f32 v[58:59], v[84:85], v[64:65], v[96:97]
	v_pk_fma_f32 v[54:55], v[78:79], v[54:55], v[56:57]
	v_pk_fma_f32 v[52:53], v[76:77], v[52:53], v[58:59]
	v_pk_mul_f32 v[56:57], v[48:49], v[48:49]
	v_pk_mul_f32 v[58:59], v[50:51], v[50:51]
	v_pk_fma_f32 v[56:57], v[56:57], s[84:85], v[246:247] op_sel_hi:[1,0,0]
	v_pk_fma_f32 v[58:59], v[58:59], s[84:85], v[246:247] op_sel_hi:[1,0,0]
	v_pk_mul_f32 v[56:57], v[48:49], v[56:57]
	v_pk_mul_f32 v[58:59], v[50:51], v[58:59]
	v_exp_f32_e32 v56, v56
	v_exp_f32_e32 v58, v58
	v_exp_f32_e32 v57, v57
	v_exp_f32_e32 v59, v59
	v_pk_fma_f32 v[54:55], v[42:43], v[74:75], v[54:55]
	v_pk_fma_f32 v[52:53], v[40:41], v[72:73], v[52:53]
	v_pk_add_f32 v[56:57], v[56:57], 1.0 op_sel_hi:[1,0]
	v_pk_add_f32 v[58:59], v[58:59], 1.0 op_sel_hi:[1,0]
	v_rcp_f32_e32 v56, v56
	v_rcp_f32_e32 v58, v58
	v_rcp_f32_e32 v57, v57
	v_rcp_f32_e32 v59, v59
	v_pk_mul_f32 v[48:49], v[48:49], v[54:55]
	v_pk_mul_f32 v[50:51], v[50:51], v[52:53]
	v_pk_mul_f32 v[48:49], v[48:49], v[56:57]
	v_pk_mul_f32 v[50:51], v[50:51], v[58:59]
	s_nop 0
	v_cvt_pk_bf16_f32 v50, v50, v51
	v_cvt_pk_bf16_f32 v51, v48, v49
	ds_bpermute_b32 v236, v244, v152
	ds_bpermute_b32 v237, v244, v153
	ds_bpermute_b32 v238, v244, v50
	ds_bpermute_b32 v239, v244, v51
	s_waitcnt lgkmcnt(0)
	global_store_dwordx2 v[236:237], v[238:239], off offset:8
	s_and_saveexec_b64 s[6:7], s[34:35]
	s_cbranch_execz .LBB0_685
	v_mov_b64_e32 v[48:49], s[24:25]
	v_mad_i64_i32 v[48:49], s[58:59], v154, s36, v[48:49]
	v_lshl_add_u64 v[48:49], v[196:197], 2, v[48:49]
	global_store_dwordx4 v[48:49], v[44:47], off offset:16
	s_nop 1
	v_add_co_u32_e32 v44, vcc, 0x2000, v48
	s_nop 1
	v_addc_co_u32_e32 v45, vcc, 0, v49, vcc
	global_store_dwordx4 v[44:45], v[40:43], off offset:3088

; __device__ __forceinline__ unsigned pk2(float lo, float hi) { const f32x2 v = {lo, hi}; const bf16x2_t b = __builtin_convertvector(v, bf16x2_t); return __builtin_bit_cast(unsigned, b); }
; __device__ __forceinline__ f32x4 gelu_mul4(f32x4 x, f32x4 v) {
;     const f32x4 t = x * x;
;     const f32x4 u = t * (-2.0f * 0.7978845608028654f * 0.044715f * 1.4426950408889634f) + (-2.0f * 0.7978845608028654f * 1.4426950408889634f);
;     const f32x4 z = x * u;
;     f32x4 d; d[0] = __builtin_amdgcn_exp2f(z[0]); d[1] = __builtin_amdgcn_exp2f(z[1]); d[2] = __builtin_amdgcn_exp2f(z[2]); d[3] = __builtin_amdgcn_exp2f(z[3]);
;     d = d + 1.0f;
;     f32x4 r; r[0] = __builtin_amdgcn_rcpf(d[0]); r[1] = __builtin_amdgcn_rcpf(d[1]); r[2] = __builtin_amdgcn_rcpf(d[2]); r[3] = __builtin_amdgcn_rcpf(d[3]);
;     return (x * v) * r;
; }
;     __device__ __forceinline__ void operator()(const f32x4 (&acc)[2][2][4][2], const pg8::Unit& u, int wr, int wc, int fr, int fq, PG8_LAS unsigned char* xl) const {
;     ...
;                         cc[bj] = bb[bj] + w0[bj] * p2 + w1[bj] * p1 + w2[bj] * cur;
;                     }
;                     const f32x4 gv = gelu_mul4(cc[0], cc[1]);
;                     u32x2 w; w.x = pk2(gv[0], gv[1]); w.y = pk2(gv[2], gv[3]);
;                     *(u32x2*)(G + (size_t)row * FF + jc0 + 4 * n) = w;
;                     if (!sample && ai == 0 && wr == 0 && m == 0 && fr < 2 && (pm & 7) != 0) {
; #pragma unroll
;                         for (int bj = 0; bj < 2; ++bj) *(f32x4*)(PH + (size_t)(pm * 2 + fr) * FF2 + bj * FF + jc0 + 4 * n) = cc[bj];
;                     }
;                     if (sample && (fr & 3) >= 2) { const int b = (row - MP) >> 2, t = fr & 3;
; #pragma unroll
;                         for (int bj = 0; bj < 2; ++bj) *(f32x4*)(nf_s + (size_t)(b * 2 + t - 2) * FF2 + bj * FF + jc0 + 4 * n) = acc[ai][bj][m][n];
.LBB0_695:
	s_waitcnt lgkmcnt(0)
	v_pk_fma_f32 v[40:41], v[94:95], v[50:51], v[102:103]
	v_pk_fma_f32 v[42:43], v[92:93], v[48:49], v[100:101]
	v_pk_fma_f32 v[40:41], v[90:91], v[46:47], v[40:41]
	v_pk_fma_f32 v[42:43], v[88:89], v[44:45], v[42:43]
	v_pk_fma_f32 v[40:41], v[38:39], v[82:83], v[40:41]
	v_pk_fma_f32 v[42:43], v[36:37], v[80:81], v[42:43]
	v_pk_fma_f32 v[46:47], v[84:85], v[56:57], v[96:97]
	v_pk_mul_f32 v[48:49], v[40:41], v[40:41]
	v_pk_fma_f32 v[46:47], v[76:77], v[52:53], v[46:47]
	v_pk_mul_f32 v[50:51], v[42:43], v[42:43]
	v_pk_fma_f32 v[48:49], v[48:49], s[84:85], v[246:247] op_sel_hi:[1,0,0]
	v_pk_fma_f32 v[50:51], v[50:51], s[84:85], v[246:247] op_sel_hi:[1,0,0]
	v_pk_mul_f32 v[48:49], v[40:41], v[48:49]
	v_pk_mul_f32 v[50:51], v[42:43], v[50:51]
	v_exp_f32_e32 v48, v48
	v_exp_f32_e32 v50, v50
	v_exp_f32_e32 v49, v49
	v_exp_f32_e32 v51, v51
	v_pk_fma_f32 v[44:45], v[86:87], v[58:59], v[98:99]
	v_pk_fma_f32 v[46:47], v[32:33], v[72:73], v[46:47]
	v_pk_add_f32 v[48:49], v[48:49], 1.0 op_sel_hi:[1,0]
	v_pk_add_f32 v[50:51], v[50:51], 1.0 op_sel_hi:[1,0]
	v_rcp_f32_e32 v48, v48
	v_rcp_f32_e32 v50, v50
	v_rcp_f32_e32 v49, v49
	v_rcp_f32_e32 v51, v51
	v_pk_fma_f32 v[44:45], v[78:79], v[54:55], v[44:45]
	v_pk_mul_f32 v[42:43], v[42:43], v[46:47]
	v_pk_fma_f32 v[44:45], v[34:35], v[74:75], v[44:45]
	v_pk_mul_f32 v[42:43], v[42:43], v[50:51]
	v_pk_mul_f32 v[40:41], v[40:41], v[44:45]
	v_cvt_pk_bf16_f32 v42, v42, v43
	v_pk_mul_f32 v[40:41], v[40:41], v[48:49]
	s_nop 0
	v_cvt_pk_bf16_f32 v43, v40, v41
	ds_bpermute_b32 v236, v244, v144
	ds_bpermute_b32 v237, v244, v145
	ds_bpermute_b32 v238, v244, v42
	ds_bpermute_b32 v239, v244, v43
	s_waitcnt lgkmcnt(0)
	global_store_dwordx2 v[236:237], v[238:239], off offset:8
	s_and_saveexec_b64 s[6:7], s[34:35]
	s_cbranch_execz .LBB0_697
	v_mov_b64_e32 v[40:41], s[24:25]
	v_mad_i64_i32 v[40:41], s[10:11], v146, s36, v[40:41]
	v_lshl_add_u64 v[40:41], v[196:197], 2, v[40:41]
	global_store_dwordx4 v[40:41], v[36:39], off offset:16
	v_add_co_u32_e32 v40, vcc, 0x2000, v40
	s_nop 1
	v_addc_co_u32_e32 v41, vcc, 0, v41, vcc
	global_store_dwordx4 v[40:41], v[32:35], off offset:3088

; __device__ __forceinline__ unsigned pk2(float lo, float hi) { const f32x2 v = {lo, hi}; const bf16x2_t b = __builtin_convertvector(v, bf16x2_t); return __builtin_bit_cast(unsigned, b); }
; __device__ __forceinline__ f32x4 gelu_mul4(f32x4 x, f32x4 v) {
;     const f32x4 t = x * x;
;     const f32x4 u = t * (-2.0f * 0.7978845608028654f * 0.044715f * 1.4426950408889634f) + (-2.0f * 0.7978845608028654f * 1.4426950408889634f);
;     const f32x4 z = x * u;
;     f32x4 d; d[0] = __builtin_amdgcn_exp2f(z[0]); d[1] = __builtin_amdgcn_exp2f(z[1]); d[2] = __builtin_amdgcn_exp2f(z[2]); d[3] = __builtin_amdgcn_exp2f(z[3]);
;     d = d + 1.0f;
;     f32x4 r; r[0] = __builtin_amdgcn_rcpf(d[0]); r[1] = __builtin_amdgcn_rcpf(d[1]); r[2] = __builtin_amdgcn_rcpf(d[2]); r[3] = __builtin_amdgcn_rcpf(d[3]);
;     return (x * v) * r;
; }
;     __device__ __forceinline__ void operator()(const f32x4 (&acc)[2][2][4][2], const pg8::Unit& u, int wr, int wc, int fr, int fq, PG8_LAS unsigned char* xl) const {
;     ...
;                         cc[bj] = bb[bj] + w0[bj] * p2 + w1[bj] * p1 + w2[bj] * cur;
;                     }
;                     const f32x4 gv = gelu_mul4(cc[0], cc[1]);
;                     u32x2 w; w.x = pk2(gv[0], gv[1]); w.y = pk2(gv[2], gv[3]);
;                     *(u32x2*)(G + (size_t)row * FF + jc0 + 4 * n) = w;
;                     if (!sample && ai == 0 && wr == 0 && m == 0 && fr < 2 && (pm & 7) != 0) {
; #pragma unroll
;                         for (int bj = 0; bj < 2; ++bj) *(f32x4*)(PH + (size_t)(pm * 2 + fr) * FF2 + bj * FF + jc0 + 4 * n) = cc[bj];
;                     }
;                     if (sample && (fr & 3) >= 2) { const int b = (row - MP) >> 2, t = fr & 3;
; #pragma unroll
;                         for (int bj = 0; bj < 2; ++bj) *(f32x4*)(nf_s + (size_t)(b * 2 + t - 2) * FF2 + bj * FF + jc0 + 4 * n) = acc[ai][bj][m][n];
.LBB0_705:
	v_pk_fma_f32 v[32:33], v[94:95], v[46:47], v[102:103]
	v_pk_fma_f32 v[34:35], v[92:93], v[44:45], v[100:101]
	v_pk_fma_f32 v[32:33], v[90:91], v[42:43], v[32:33]
	v_pk_fma_f32 v[34:35], v[88:89], v[40:41], v[34:35]
	v_pk_fma_f32 v[32:33], v[30:31], v[82:83], v[32:33]
	v_pk_fma_f32 v[34:35], v[28:29], v[80:81], v[34:35]
	v_pk_fma_f32 v[40:41], v[86:87], v[50:51], v[98:99]
	v_pk_fma_f32 v[42:43], v[84:85], v[48:49], v[96:97]
	v_pk_fma_f32 v[38:39], v[78:79], v[38:39], v[40:41]
	v_pk_fma_f32 v[36:37], v[76:77], v[36:37], v[42:43]
	v_pk_mul_f32 v[40:41], v[32:33], v[32:33]
	v_pk_mul_f32 v[42:43], v[34:35], v[34:35]
	v_pk_fma_f32 v[40:41], v[40:41], s[84:85], v[246:247] op_sel_hi:[1,0,0]
	v_pk_fma_f32 v[42:43], v[42:43], s[84:85], v[246:247] op_sel_hi:[1,0,0]
	v_pk_mul_f32 v[40:41], v[32:33], v[40:41]
	v_pk_mul_f32 v[42:43], v[34:35], v[42:43]
	v_exp_f32_e32 v40, v40
	v_exp_f32_e32 v42, v42
	v_exp_f32_e32 v41, v41
	v_exp_f32_e32 v43, v43
	v_pk_fma_f32 v[38:39], v[26:27], v[74:75], v[38:39]
	v_pk_fma_f32 v[36:37], v[24:25], v[72:73], v[36:37]
	v_pk_add_f32 v[40:41], v[40:41], 1.0 op_sel_hi:[1,0]
	v_pk_add_f32 v[42:43], v[42:43], 1.0 op_sel_hi:[1,0]
	v_rcp_f32_e32 v40, v40
	v_rcp_f32_e32 v42, v42
	v_rcp_f32_e32 v41, v41
	v_rcp_f32_e32 v43, v43
	v_pk_mul_f32 v[32:33], v[32:33], v[38:39]
	v_pk_mul_f32 v[34:35], v[34:35], v[36:37]
	v_pk_mul_f32 v[32:33], v[32:33], v[40:41]
	v_pk_mul_f32 v[34:35], v[34:35], v[42:43]
	s_nop 0
	v_cvt_pk_bf16_f32 v34, v34, v35
	v_cvt_pk_bf16_f32 v35, v32, v33
	ds_bpermute_b32 v236, v244, v136
	ds_bpermute_b32 v237, v244, v137
	ds_bpermute_b32 v238, v244, v34
	ds_bpermute_b32 v239, v244, v35
	s_waitcnt lgkmcnt(0)
	global_store_dwordx2 v[236:237], v[238:239], off offset:8
	s_and_saveexec_b64 s[6:7], s[34:35]
	s_cbranch_execz .LBB0_707
	v_mov_b64_e32 v[32:33], s[24:25]
	v_mad_i64_i32 v[32:33], s[10:11], v138, s36, v[32:33]
	v_lshl_add_u64 v[32:33], v[196:197], 2, v[32:33]
	global_store_dwordx4 v[32:33], v[28:31], off offset:16
	v_add_co_u32_e32 v32, vcc, 0x2000, v32
	s_nop 1
	v_addc_co_u32_e32 v33, vcc, 0, v33, vcc
	global_store_dwordx4 v[32:33], v[24:27], off offset:3088

; __device__ __forceinline__ unsigned pk2(float lo, float hi) { const f32x2 v = {lo, hi}; const bf16x2_t b = __builtin_convertvector(v, bf16x2_t); return __builtin_bit_cast(unsigned, b); }
; __device__ __forceinline__ f32x4 gelu_mul4(f32x4 x, f32x4 v) {
;     const f32x4 t = x * x;
;     const f32x4 u = t * (-2.0f * 0.7978845608028654f * 0.044715f * 1.4426950408889634f) + (-2.0f * 0.7978845608028654f * 1.4426950408889634f);
;     const f32x4 z = x * u;
;     f32x4 d; d[0] = __builtin_amdgcn_exp2f(z[0]); d[1] = __builtin_amdgcn_exp2f(z[1]); d[2] = __builtin_amdgcn_exp2f(z[2]); d[3] = __builtin_amdgcn_exp2f(z[3]);
;     d = d + 1.0f;
;     f32x4 r; r[0] = __builtin_amdgcn_rcpf(d[0]); r[1] = __builtin_amdgcn_rcpf(d[1]); r[2] = __builtin_amdgcn_rcpf(d[2]); r[3] = __builtin_amdgcn_rcpf(d[3]);
;     return (x * v) * r;
; }
;     __device__ __forceinline__ void operator()(const f32x4 (&acc)[2][2][4][2], const pg8::Unit& u, int wr, int wc, int fr, int fq, PG8_LAS unsigned char* xl) const {
;     ...
;                         cc[bj] = bb[bj] + w0[bj] * p2 + w1[bj] * p1 + w2[bj] * cur;
;                     }
;                     const f32x4 gv = gelu_mul4(cc[0], cc[1]);
;                     u32x2 w; w.x = pk2(gv[0], gv[1]); w.y = pk2(gv[2], gv[3]);
;                     *(u32x2*)(G + (size_t)row * FF + jc0 + 4 * n) = w;
;                     if (!sample && ai == 0 && wr == 0 && m == 0 && fr < 2 && (pm & 7) != 0) {
; #pragma unroll
;                         for (int bj = 0; bj < 2; ++bj) *(f32x4*)(PH + (size_t)(pm * 2 + fr) * FF2 + bj * FF + jc0 + 4 * n) = cc[bj];
;                     }
;                     if (sample && (fr & 3) >= 2) { const int b = (row - MP) >> 2, t = fr & 3;
; #pragma unroll
;                         for (int bj = 0; bj < 2; ++bj) *(f32x4*)(nf_s + (size_t)(b * 2 + t - 2) * FF2 + bj * FF + jc0 + 4 * n) = acc[ai][bj][m][n];
.LBB0_715:
	v_pk_fma_f32 v[24:25], v[94:95], v[38:39], v[102:103]
	v_pk_fma_f32 v[26:27], v[92:93], v[36:37], v[100:101]
	v_pk_fma_f32 v[24:25], v[90:91], v[34:35], v[24:25]
	v_pk_fma_f32 v[26:27], v[88:89], v[32:33], v[26:27]
	v_pk_fma_f32 v[24:25], v[22:23], v[82:83], v[24:25]
	v_pk_fma_f32 v[26:27], v[20:21], v[80:81], v[26:27]
	v_pk_fma_f32 v[32:33], v[86:87], v[42:43], v[98:99]
	v_pk_fma_f32 v[34:35], v[84:85], v[40:41], v[96:97]
	v_pk_fma_f32 v[30:31], v[78:79], v[30:31], v[32:33]
	v_pk_fma_f32 v[28:29], v[76:77], v[28:29], v[34:35]
	v_pk_mul_f32 v[32:33], v[24:25], v[24:25]
	v_pk_mul_f32 v[34:35], v[26:27], v[26:27]
	v_pk_fma_f32 v[32:33], v[32:33], s[84:85], v[246:247] op_sel_hi:[1,0,0]
	v_pk_fma_f32 v[34:35], v[34:35], s[84:85], v[246:247] op_sel_hi:[1,0,0]
	v_pk_mul_f32 v[32:33], v[24:25], v[32:33]
	v_pk_mul_f32 v[34:35], v[26:27], v[34:35]
	v_exp_f32_e32 v32, v32
	v_exp_f32_e32 v34, v34
	v_exp_f32_e32 v33, v33
	v_exp_f32_e32 v35, v35
	v_pk_fma_f32 v[30:31], v[18:19], v[74:75], v[30:31]
	v_pk_fma_f32 v[28:29], v[16:17], v[72:73], v[28:29]
	v_pk_add_f32 v[32:33], v[32:33], 1.0 op_sel_hi:[1,0]
	v_pk_add_f32 v[34:35], v[34:35], 1.0 op_sel_hi:[1,0]
	v_rcp_f32_e32 v32, v32
	v_rcp_f32_e32 v34, v34
	v_rcp_f32_e32 v33, v33
	v_rcp_f32_e32 v35, v35
	v_pk_mul_f32 v[24:25], v[24:25], v[30:31]
	v_pk_mul_f32 v[26:27], v[26:27], v[28:29]
	v_pk_mul_f32 v[24:25], v[24:25], v[32:33]
	v_pk_mul_f32 v[26:27], v[26:27], v[34:35]
	s_nop 0
	v_cvt_pk_bf16_f32 v26, v26, v27
	v_cvt_pk_bf16_f32 v27, v24, v25
	ds_bpermute_b32 v236, v244, v128
	ds_bpermute_b32 v237, v244, v129
	ds_bpermute_b32 v238, v244, v26
	ds_bpermute_b32 v239, v244, v27
	s_waitcnt lgkmcnt(0)
	global_store_dwordx2 v[236:237], v[238:239], off offset:8
	s_and_saveexec_b64 s[6:7], s[34:35]
	s_cbranch_execz .LBB0_717
	v_mov_b64_e32 v[24:25], s[24:25]
	v_mad_i64_i32 v[24:25], s[10:11], v139, s36, v[24:25]
	v_lshl_add_u64 v[24:25], v[196:197], 2, v[24:25]
	global_store_dwordx4 v[24:25], v[20:23], off offset:16
	v_add_co_u32_e32 v24, vcc, 0x2000, v24
	s_nop 1
	v_addc_co_u32_e32 v25, vcc, 0, v25, vcc
	global_store_dwordx4 v[24:25], v[16:19], off offset:3088

; __device__ __forceinline__ unsigned pk2(float lo, float hi) { const f32x2 v = {lo, hi}; const bf16x2_t b = __builtin_convertvector(v, bf16x2_t); return __builtin_bit_cast(unsigned, b); }
; __device__ __forceinline__ f32x4 gelu_mul4(f32x4 x, f32x4 v) {
;     const f32x4 t = x * x;
;     const f32x4 u = t * (-2.0f * 0.7978845608028654f * 0.044715f * 1.4426950408889634f) + (-2.0f * 0.7978845608028654f * 1.4426950408889634f);
;     const f32x4 z = x * u;
;     f32x4 d; d[0] = __builtin_amdgcn_exp2f(z[0]); d[1] = __builtin_amdgcn_exp2f(z[1]); d[2] = __builtin_amdgcn_exp2f(z[2]); d[3] = __builtin_amdgcn_exp2f(z[3]);
;     d = d + 1.0f;
;     f32x4 r; r[0] = __builtin_amdgcn_rcpf(d[0]); r[1] = __builtin_amdgcn_rcpf(d[1]); r[2] = __builtin_amdgcn_rcpf(d[2]); r[3] = __builtin_amdgcn_rcpf(d[3]);
;     return (x * v) * r;
; }
;     __device__ __forceinline__ void operator()(const f32x4 (&acc)[2][2][4][2], const pg8::Unit& u, int wr, int wc, int fr, int fq, PG8_LAS unsigned char* xl) const {
;     ...
;                         cc[bj] = bb[bj] + w0[bj] * p2 + w1[bj] * p1 + w2[bj] * cur;
;                     }
;                     const f32x4 gv = gelu_mul4(cc[0], cc[1]);
;                     u32x2 w; w.x = pk2(gv[0], gv[1]); w.y = pk2(gv[2], gv[3]);
;                     *(u32x2*)(G + (size_t)row * FF + jc0 + 4 * n) = w;
;                     if (!sample && ai == 0 && wr == 0 && m == 0 && fr < 2 && (pm & 7) != 0) {
; #pragma unroll
;                         for (int bj = 0; bj < 2; ++bj) *(f32x4*)(PH + (size_t)(pm * 2 + fr) * FF2 + bj * FF + jc0 + 4 * n) = cc[bj];
;                     }
;                     if (sample && (fr & 3) >= 2) { const int b = (row - MP) >> 2, t = fr & 3;
; #pragma unroll
;                         for (int bj = 0; bj < 2; ++bj) *(f32x4*)(nf_s + (size_t)(b * 2 + t - 2) * FF2 + bj * FF + jc0 + 4 * n) = acc[ai][bj][m][n];
.LBB0_725:
	v_pk_fma_f32 v[16:17], v[94:95], v[30:31], v[102:103]
	v_pk_fma_f32 v[18:19], v[92:93], v[28:29], v[100:101]
	v_pk_fma_f32 v[16:17], v[90:91], v[26:27], v[16:17]
	v_pk_fma_f32 v[18:19], v[88:89], v[24:25], v[18:19]
	v_pk_fma_f32 v[16:17], v[10:11], v[82:83], v[16:17]
	v_pk_fma_f32 v[18:19], v[8:9], v[80:81], v[18:19]
	v_pk_fma_f32 v[24:25], v[86:87], v[34:35], v[98:99]
	v_pk_fma_f32 v[26:27], v[84:85], v[32:33], v[96:97]
	v_pk_fma_f32 v[22:23], v[78:79], v[22:23], v[24:25]
	v_pk_fma_f32 v[20:21], v[76:77], v[20:21], v[26:27]
	v_pk_mul_f32 v[24:25], v[16:17], v[16:17]
	v_pk_mul_f32 v[26:27], v[18:19], v[18:19]
	v_pk_fma_f32 v[24:25], v[24:25], s[84:85], v[246:247] op_sel_hi:[1,0,0]
	v_pk_fma_f32 v[26:27], v[26:27], s[84:85], v[246:247] op_sel_hi:[1,0,0]
	v_pk_mul_f32 v[24:25], v[16:17], v[24:25]
	v_pk_mul_f32 v[26:27], v[18:19], v[26:27]
	v_exp_f32_e32 v24, v24
	v_exp_f32_e32 v26, v26
	v_exp_f32_e32 v25, v25
	v_exp_f32_e32 v27, v27
	v_pk_fma_f32 v[22:23], v[2:3], v[74:75], v[22:23]
	v_pk_fma_f32 v[20:21], v[0:1], v[72:73], v[20:21]
	v_pk_add_f32 v[24:25], v[24:25], 1.0 op_sel_hi:[1,0]
	v_pk_add_f32 v[26:27], v[26:27], 1.0 op_sel_hi:[1,0]
	v_rcp_f32_e32 v24, v24
	v_rcp_f32_e32 v26, v26
	v_rcp_f32_e32 v25, v25
	v_rcp_f32_e32 v27, v27
	v_pk_mul_f32 v[16:17], v[16:17], v[22:23]
	v_pk_mul_f32 v[18:19], v[18:19], v[20:21]
	v_pk_mul_f32 v[16:17], v[16:17], v[24:25]
	v_pk_mul_f32 v[18:19], v[18:19], v[26:27]
	s_nop 0
	v_cvt_pk_bf16_f32 v18, v18, v19
	v_cvt_pk_bf16_f32 v19, v16, v17
	ds_bpermute_b32 v236, v244, v130
	ds_bpermute_b32 v237, v244, v131
	ds_bpermute_b32 v238, v244, v18
	ds_bpermute_b32 v239, v244, v19
	s_waitcnt lgkmcnt(0)
	global_store_dwordx2 v[236:237], v[238:239], off offset:8
	s_and_saveexec_b64 s[6:7], s[34:35]
	s_cbranch_execz .LBB0_727
	v_mov_b64_e32 v[16:17], s[24:25]
	v_mad_i64_i32 v[16:17], s[10:11], v147, s36, v[16:17]
	v_lshl_add_u64 v[16:17], v[196:197], 2, v[16:17]
	global_store_dwordx4 v[16:17], v[8:11], off offset:16
	v_add_co_u32_e32 v16, vcc, 0x2000, v16
	s_nop 1
	v_addc_co_u32_e32 v17, vcc, 0, v17, vcc
	global_store_dwordx4 v[16:17], v[0:3], off offset:3088

; template <int N> __device__ __forceinline__ float dpp_ror(float v) { const int i = __builtin_bit_cast(int, v); return __builtin_bit_cast(float, __builtin_amdgcn_update_dpp(i, i, 0x120 + N, 0xF, 0xF, false)); }
;     __device__ __forceinline__ void operator()(const f32x4 (&acc)[2][2][4][2], const pg8::Unit& u, int wr, int wc, int fr, int fq, PG8_LAS unsigned char* xl) const {
;     ...
;                 for (int m = 0; m < 4; ++m) {
;                     const int row = pm * 256 + ai * 128 + wr * 64 + m * 16 + fr;
;                     f32x4 cc[2];
; #pragma unroll
;                     for (int bj = 0; bj < 2; ++bj) {
;                         const f32x4 cur = acc[ai][bj][m][n]; f32x4 p1, p2;
;                         if (!sample) { const f32x4 prv = (m == 0) ? hb[bj] : acc[ai][bj][m == 0 ? 0 : m - 1][n];
; #pragma unroll
;                             for (int j = 0; j < 4; ++j) { const float s1 = fr == 15 ? prv[j] : cur[j], s2 = fr >= 14 ? prv[j] : cur[j]; p1[j] = dpp_ror<1>(s1); p2[j] = dpp_ror<2>(s2); }
;                         } else { const int t = fr & 3, b = (row - MP) >> 2;
; #pragma unroll
;                             for (int j = 0; j < 4; ++j) { p1[j] = dpp_ror<1>(cur[j]); p2[j] = dpp_ror<2>(cur[j]); }
;                             const f32x4 c1 = *(const f32x4*)(ctx_s + (size_t)(b * 2 + 1) * FF2 + bj * FF + jc0 + 4 * n), c0 = *(const f32x4*)(ctx_s + (size_t)(b * 2) * FF2 + bj * FF + jc0 + 4 * n);
; #pragma unroll
;                             for (int j = 0; j < 4; ++j) { p2[j] = t == 0 ? c0[j] : (t == 1 ? c1[j] : p2[j]); p1[j] = t == 0 ? c1[j] : p1[j]; }
;                         }
.LBB0_1675:
	s_or_b64 exec, exec, s[6:7]
	v_lshl_add_u32 v221, s36, 8, v206
	v_add_u32_e32 v164, 0xffffc000, v221
	v_ashrrev_i32_e32 v164, 1, v164
	v_and_b32_e32 v220, 0xffffffe6, v164
	s_mov_b64 s[6:7], -1
	s_and_b64 vcc, exec, s[58:59]
	s_cbranch_vccz .LBB0_1677
	v_or_b32_e32 v166, 1, v164
	v_mov_b64_e32 v[164:165], s[48:49]
	v_mad_i64_i32 v[166:167], vcc, v166, s76, v[164:165]
	v_mad_i64_i32 v[164:165], vcc, v220, s76, v[164:165]
	v_lshl_add_u64 v[202:203], v[166:167], 0, v[198:199]
	v_lshl_add_u64 v[200:201], v[164:165], 0, v[198:199]
	global_load_dwordx4 v[164:167], v[202:203], off
	global_load_dwordx4 v[168:171], v[200:201], off
	v_mov_b32_e32 v176, v156
	v_mov_b32_e32 v177, v156
	v_mov_b32_e32 v178, v157
	v_mov_b32_e32 v179, v157
	v_mov_b32_e32 v223, v158
	v_mov_b32_e32 v225, v159
	v_mov_b32_e32 v222, v158
	v_mov_b32_e32 v224, v159
	v_mov_b32_dpp v176, v176 row_ror:1 row_mask:0xf bank_mask:0xf
	v_mov_b32_dpp v177, v177 row_ror:2 row_mask:0xf bank_mask:0xf
	v_mov_b32_dpp v178, v178 row_ror:1 row_mask:0xf bank_mask:0xf
	v_mov_b32_dpp v179, v179 row_ror:2 row_mask:0xf bank_mask:0xf
	v_mov_b32_dpp v223, v223 row_ror:2 row_mask:0xf bank_mask:0xf
	v_mov_b32_dpp v225, v225 row_ror:2 row_mask:0xf bank_mask:0xf
	v_mov_b32_dpp v222, v222 row_ror:1 row_mask:0xf bank_mask:0xf
	v_mov_b32_dpp v224, v224 row_ror:1 row_mask:0xf bank_mask:0xf
	s_mov_b64 s[6:7], 0
	s_waitcnt vmcnt(0)
	v_cndmask_b32_e64 v177, v177, v164, s[14:15]
	v_cndmask_b32_e64 v164, v176, v164, s[12:13]
	v_cndmask_b32_e64 v176, v179, v165, s[14:15]
	v_cndmask_b32_e64 v165, v178, v165, s[12:13]
	v_cndmask_b32_e64 v178, v223, v166, s[14:15]
	v_cndmask_b32_e64 v179, v225, v167, s[14:15]
	v_cndmask_b32_e64 v166, v222, v166, s[12:13]
	v_cndmask_b32_e64 v167, v224, v167, s[12:13]
	v_cndmask_b32_e64 v168, v177, v168, s[12:13]
	v_cndmask_b32_e64 v169, v176, v169, s[12:13]
	v_cndmask_b32_e64 v170, v178, v170, s[12:13]
	v_cndmask_b32_e64 v171, v179, v171, s[12:13]

; __device__ __forceinline__ unsigned pk2(float lo, float hi) { const f32x2 v = {lo, hi}; const bf16x2_t b = __builtin_convertvector(v, bf16x2_t); return __builtin_bit_cast(unsigned, b); }
; __device__ __forceinline__ f32x4 gelu_mul4(f32x4 x, f32x4 v) {
;     const f32x4 t = x * x;
;     const f32x4 u = t * (-2.0f * 0.7978845608028654f * 0.044715f * 1.4426950408889634f) + (-2.0f * 0.7978845608028654f * 1.4426950408889634f);
;     const f32x4 z = x * u;
;     f32x4 d; d[0] = __builtin_amdgcn_exp2f(z[0]); d[1] = __builtin_amdgcn_exp2f(z[1]); d[2] = __builtin_amdgcn_exp2f(z[2]); d[3] = __builtin_amdgcn_exp2f(z[3]);
;     d = d + 1.0f;
;     f32x4 r; r[0] = __builtin_amdgcn_rcpf(d[0]); r[1] = __builtin_amdgcn_rcpf(d[1]); r[2] = __builtin_amdgcn_rcpf(d[2]); r[3] = __builtin_amdgcn_rcpf(d[3]);
;     return (x * v) * r;
; }
;     __device__ __forceinline__ void operator()(const f32x4 (&acc)[2][2][4][2], const pg8::Unit& u, int wr, int wc, int fr, int fq, PG8_LAS unsigned char* xl) const {
;     ...
;                         cc[bj] = bb[bj] + w0[bj] * p2 + w1[bj] * p1 + w2[bj] * cur;
;                     }
;                     const f32x4 gv = gelu_mul4(cc[0], cc[1]);
;                     u32x2 w; w.x = pk2(gv[0], gv[1]); w.y = pk2(gv[2], gv[3]);
;                     *(u32x2*)(G + (size_t)row * FF + jc0 + 4 * n) = w;
;                     if (!sample && ai == 0 && wr == 0 && m == 0 && fr < 2 && (pm & 7) != 0) {
; #pragma unroll
;                         for (int bj = 0; bj < 2; ++bj) *(f32x4*)(PH + (size_t)(pm * 2 + fr) * FF2 + bj * FF + jc0 + 4 * n) = cc[bj];
;                     }
;                     if (sample && (fr & 3) >= 2) { const int b = (row - MP) >> 2, t = fr & 3;
; #pragma unroll
;                         for (int bj = 0; bj < 2; ++bj) *(f32x4*)(nf_s + (size_t)(b * 2 + t - 2) * FF2 + bj * FF + jc0 + 4 * n) = acc[ai][bj][m][n];
.LBB0_1683:
	s_and_b32 s73, s36, 7
	s_waitcnt vmcnt(0)
	v_pk_fma_f32 v[160:161], v[114:115], v[170:171], v[118:119]
	v_pk_fma_f32 v[162:163], v[112:113], v[168:169], v[116:117]
	s_cmp_lg_u32 s73, 0
	v_pk_fma_f32 v[160:161], v[106:107], v[166:167], v[160:161]
	v_pk_fma_f32 v[164:165], v[104:105], v[164:165], v[162:163]
	s_cselect_b64 s[6:7], -1, 0
	s_lshl_b32 s85, s36, 1
	v_pk_fma_f32 v[162:163], v[158:159], v[98:99], v[160:161]
	v_pk_fma_f32 v[160:161], v[156:157], v[96:97], v[164:165]
	v_add_u32_e32 v164, s85, v205
	v_mad_i64_i32 v[168:169], s[58:59], v164, s76, 0
	v_pk_fma_f32 v[164:165], v[110:111], v[178:179], v[122:123]
	v_pk_fma_f32 v[166:167], v[108:109], v[176:177], v[120:121]
	v_pk_fma_f32 v[164:165], v[102:103], v[174:175], v[164:165]
	v_pk_fma_f32 v[170:171], v[100:101], v[172:173], v[166:167]
	v_pk_mul_f32 v[166:167], v[162:163], v[162:163]
	v_pk_mul_f32 v[172:173], v[160:161], v[160:161]
	v_mov_b64_e32 v[246:247], s[80:81]
	v_pk_fma_f32 v[166:167], v[166:167], s[82:83], v[246:247] op_sel_hi:[1,0,0]
	v_pk_fma_f32 v[172:173], v[172:173], s[82:83], v[246:247] op_sel_hi:[1,0,0]
	v_pk_mul_f32 v[166:167], v[162:163], v[166:167]
	v_pk_mul_f32 v[172:173], v[160:161], v[172:173]
	v_exp_f32_e32 v174, v166
	v_exp_f32_e32 v172, v172
	v_exp_f32_e32 v175, v167
	v_exp_f32_e32 v173, v173
	v_pk_fma_f32 v[166:167], v[154:155], v[94:95], v[164:165]
	v_pk_fma_f32 v[164:165], v[152:153], v[92:93], v[170:171]
	v_pk_add_f32 v[170:171], v[174:175], 1.0 op_sel_hi:[1,0]
	v_pk_add_f32 v[172:173], v[172:173], 1.0 op_sel_hi:[1,0]
	v_rcp_f32_e32 v170, v170
	v_rcp_f32_e32 v172, v172
	v_rcp_f32_e32 v171, v171
	v_rcp_f32_e32 v173, v173
	v_pk_mul_f32 v[174:175], v[162:163], v[166:167]
	v_pk_mul_f32 v[176:177], v[160:161], v[164:165]
	v_pk_mul_f32 v[170:171], v[174:175], v[170:171]
	v_pk_mul_f32 v[172:173], v[176:177], v[172:173]
	v_lshl_add_u64 v[168:169], s[44:45], 0, v[168:169]
	v_cvt_pk_bf16_f32 v172, v172, v173
	v_cvt_pk_bf16_f32 v173, v170, v171
	v_mov_b64_e32 v[170:171], s[40:41]
	v_mad_i64_i32 v[170:171], s[58:59], v221, s77, v[170:171]
	s_and_b64 s[58:59], s[66:67], s[94:95]
	s_xor_b64 s[58:59], s[58:59], -1
	s_nor_b64 s[58:59], s[58:59], s[18:19]
	v_lshl_add_u64 v[178:179], v[196:197], 1, v[170:171]
	s_mov_b32 s101, 0
	s_and_b64 s[58:59], s[6:7], s[58:59]
	v_lshl_add_u64 v[176:177], v[196:197], 2, v[168:169]
	ds_bpermute_b32 v236, v244, v178
	ds_bpermute_b32 v237, v244, v179
	ds_bpermute_b32 v238, v244, v172
	ds_bpermute_b32 v239, v244, v173
	s_waitcnt lgkmcnt(0)
	global_store_dwordx2 v[236:237], v[238:239], off
	s_and_saveexec_b64 s[6:7], s[58:59]
	s_cbranch_execz .LBB0_1685
	global_store_dwordx4 v[176:177], v[160:163], off
	s_nop 1
	v_add_co_u32_e32 v160, vcc, 0x2000, v176
	s_nop 1
	v_addc_co_u32_e32 v161, vcc, 0, v177, vcc
	global_store_dwordx4 v[160:161], v[164:167], off offset:3072

; template <int N> __device__ __forceinline__ float dpp_ror(float v) { const int i = __builtin_bit_cast(int, v); return __builtin_bit_cast(float, __builtin_amdgcn_update_dpp(i, i, 0x120 + N, 0xF, 0xF, false)); }
;     __device__ __forceinline__ void operator()(const f32x4 (&acc)[2][2][4][2], const pg8::Unit& u, int wr, int wc, int fr, int fq, PG8_LAS unsigned char* xl) const {
;     ...
;                 for (int m = 0; m < 4; ++m) {
;                     const int row = pm * 256 + ai * 128 + wr * 64 + m * 16 + fr;
;                     f32x4 cc[2];
; #pragma unroll
;                     for (int bj = 0; bj < 2; ++bj) {
;                         const f32x4 cur = acc[ai][bj][m][n]; f32x4 p1, p2;
;                         if (!sample) { const f32x4 prv = (m == 0) ? hb[bj] : acc[ai][bj][m == 0 ? 0 : m - 1][n];
; #pragma unroll
;                             for (int j = 0; j < 4; ++j) { const float s1 = fr == 15 ? prv[j] : cur[j], s2 = fr >= 14 ? prv[j] : cur[j]; p1[j] = dpp_ror<1>(s1); p2[j] = dpp_ror<2>(s2); }
;                         } else { const int t = fr & 3, b = (row - MP) >> 2;
; #pragma unroll
;                             for (int j = 0; j < 4; ++j) { p1[j] = dpp_ror<1>(cur[j]); p2[j] = dpp_ror<2>(cur[j]); }
;                             const f32x4 c1 = *(const f32x4*)(ctx_s + (size_t)(b * 2 + 1) * FF2 + bj * FF + jc0 + 4 * n), c0 = *(const f32x4*)(ctx_s + (size_t)(b * 2) * FF2 + bj * FF + jc0 + 4 * n);
; #pragma unroll
;                             for (int j = 0; j < 4; ++j) { p2[j] = t == 0 ? c0[j] : (t == 1 ? c1[j] : p2[j]); p1[j] = t == 0 ? c1[j] : p1[j]; }
;                         }
.LBB0_1687:
	s_or_b64 exec, exec, s[6:7]
	v_add_u32_e32 v160, 0xffffc010, v221
	v_ashrrev_i32_e32 v160, 1, v160
	v_and_b32_e32 v222, 0xffffffee, v160
	s_and_b64 vcc, exec, s[22:23]
	s_mov_b64 s[6:7], -1
	s_cbranch_vccnz .LBB0_1689
	v_or_b32_e32 v162, 1, v160
	v_mov_b64_e32 v[160:161], s[48:49]
	v_mad_i64_i32 v[162:163], vcc, v162, s76, v[160:161]
	v_mad_i64_i32 v[160:161], vcc, v222, s76, v[160:161]
	v_lshl_add_u64 v[174:175], v[162:163], 0, v[198:199]
	v_lshl_add_u64 v[172:173], v[160:161], 0, v[198:199]
	global_load_dwordx4 v[160:163], v[174:175], off
	global_load_dwordx4 v[164:167], v[172:173], off
	v_mov_b32_e32 v168, v148
	v_mov_b32_e32 v169, v148
	v_mov_b32_e32 v170, v149
	v_mov_b32_e32 v171, v149
	v_mov_b32_e32 v224, v150
	v_mov_b32_e32 v226, v151
	v_mov_b32_e32 v223, v150
	v_mov_b32_e32 v225, v151
	v_mov_b32_dpp v168, v168 row_ror:1 row_mask:0xf bank_mask:0xf
	v_mov_b32_dpp v169, v169 row_ror:2 row_mask:0xf bank_mask:0xf
	v_mov_b32_dpp v170, v170 row_ror:1 row_mask:0xf bank_mask:0xf
	v_mov_b32_dpp v171, v171 row_ror:2 row_mask:0xf bank_mask:0xf
	v_mov_b32_dpp v224, v224 row_ror:2 row_mask:0xf bank_mask:0xf
	v_mov_b32_dpp v226, v226 row_ror:2 row_mask:0xf bank_mask:0xf
	v_mov_b32_dpp v223, v223 row_ror:1 row_mask:0xf bank_mask:0xf
	v_mov_b32_dpp v225, v225 row_ror:1 row_mask:0xf bank_mask:0xf
	s_waitcnt vmcnt(1)
	v_cndmask_b32_e64 v169, v169, v160, s[14:15]
	v_cndmask_b32_e64 v160, v168, v160, s[12:13]
	v_cndmask_b32_e64 v168, v171, v161, s[14:15]
	v_cndmask_b32_e64 v161, v170, v161, s[12:13]
	v_cndmask_b32_e64 v170, v224, v162, s[14:15]
	v_cndmask_b32_e64 v171, v226, v163, s[14:15]
	v_cndmask_b32_e64 v162, v223, v162, s[12:13]
	v_cndmask_b32_e64 v163, v225, v163, s[12:13]
	s_waitcnt vmcnt(0)
	v_cndmask_b32_e64 v164, v169, v164, s[12:13]
	v_cndmask_b32_e64 v165, v168, v165, s[12:13]
	v_cndmask_b32_e64 v166, v170, v166, s[12:13]
	v_cndmask_b32_e64 v167, v171, v167, s[12:13]
	s_cbranch_execnz .LBB0_1691
	s_branch .LBB0_1690

; __device__ __forceinline__ f32x4 gelu_mul4(f32x4 x, f32x4 v) {
;     const f32x4 t = x * x;
;     const f32x4 u = t * (-2.0f * 0.7978845608028654f * 0.044715f * 1.4426950408889634f) + (-2.0f * 0.7978845608028654f * 1.4426950408889634f);
;     const f32x4 z = x * u;
;     __device__ __forceinline__ void operator()(const f32x4 (&acc)[2][2][4][2], const pg8::Unit& u, int wr, int wc, int fr, int fq, PG8_LAS unsigned char* xl) const {
;     ...
;                         const f32x4 cur = acc[ai][bj][m][n]; f32x4 p1, p2;
;                         if (!sample) { const f32x4 prv = (m == 0) ? hb[bj] : acc[ai][bj][m == 0 ? 0 : m - 1][n];
; #pragma unroll
;                             for (int j = 0; j < 4; ++j) { const float s1 = fr == 15 ? prv[j] : cur[j], s2 = fr >= 14 ? prv[j] : cur[j]; p1[j] = dpp_ror<1>(s1); p2[j] = dpp_ror<2>(s2); }
;                         } else { const int t = fr & 3, b = (row - MP) >> 2;
; #pragma unroll
;                             for (int j = 0; j < 4; ++j) { p1[j] = dpp_ror<1>(cur[j]); p2[j] = dpp_ror<2>(cur[j]); }
;                             const f32x4 c1 = *(const f32x4*)(ctx_s + (size_t)(b * 2 + 1) * FF2 + bj * FF + jc0 + 4 * n), c0 = *(const f32x4*)(ctx_s + (size_t)(b * 2) * FF2 + bj * FF + jc0 + 4 * n);
; #pragma unroll
;                             for (int j = 0; j < 4; ++j) { p2[j] = t == 0 ? c0[j] : (t == 1 ? c1[j] : p2[j]); p1[j] = t == 0 ? c1[j] : p1[j]; }
;                         }
;                         cc[bj] = bb[bj] + w0[bj] * p2 + w1[bj] * p1 + w2[bj] * cur;
;                     }
;                     const f32x4 gv = gelu_mul4(cc[0], cc[1]);
;                     u32x2 w; w.x = pk2(gv[0], gv[1]); w.y = pk2(gv[2], gv[3]);
;                     *(u32x2*)(G + (size_t)row * FF + jc0 + 4 * n) = w;
;                     if (!sample && ai == 0 && wr == 0 && m == 0 && fr < 2 && (pm & 7) != 0) {
; #pragma unroll
;                         for (int bj = 0; bj < 2; ++bj) *(f32x4*)(PH + (size_t)(pm * 2 + fr) * FF2 + bj * FF + jc0 + 4 * n) = cc[bj];
;                     }
;                     if (sample && (fr & 3) >= 2) { const int b = (row - MP) >> 2, t = fr & 3;
; #pragma unroll
;                         for (int bj = 0; bj < 2; ++bj) *(f32x4*)(nf_s + (size_t)(b * 2 + t - 2) * FF2 + bj * FF + jc0 + 4 * n) = acc[ai][bj][m][n];
.LBB0_1695:
	v_pk_fma_f32 v[152:153], v[114:115], v[166:167], v[118:119]
	v_pk_fma_f32 v[154:155], v[112:113], v[164:165], v[116:117]
	v_pk_fma_f32 v[152:153], v[106:107], v[162:163], v[152:153]
	v_pk_fma_f32 v[154:155], v[104:105], v[160:161], v[154:155]
	v_pk_fma_f32 v[152:153], v[150:151], v[98:99], v[152:153]
	v_pk_fma_f32 v[154:155], v[148:149], v[96:97], v[154:155]
	v_pk_fma_f32 v[160:161], v[110:111], v[170:171], v[122:123]
	v_pk_fma_f32 v[162:163], v[108:109], v[168:169], v[120:121]
	v_pk_fma_f32 v[158:159], v[102:103], v[158:159], v[160:161]
	v_pk_fma_f32 v[156:157], v[100:101], v[156:157], v[162:163]
	v_pk_mul_f32 v[160:161], v[152:153], v[152:153]
	v_pk_mul_f32 v[162:163], v[154:155], v[154:155]
	v_pk_fma_f32 v[160:161], v[160:161], s[82:83], v[246:247] op_sel_hi:[1,0,0]
	v_pk_fma_f32 v[162:163], v[162:163], s[82:83], v[246:247] op_sel_hi:[1,0,0]
	v_pk_mul_f32 v[160:161], v[152:153], v[160:161]
	v_pk_mul_f32 v[162:163], v[154:155], v[162:163]
	v_exp_f32_e32 v160, v160
	v_exp_f32_e32 v162, v162
	v_exp_f32_e32 v161, v161
	v_exp_f32_e32 v163, v163
	v_pk_fma_f32 v[158:159], v[146:147], v[94:95], v[158:159]
	v_pk_fma_f32 v[156:157], v[144:145], v[92:93], v[156:157]
	v_pk_add_f32 v[160:161], v[160:161], 1.0 op_sel_hi:[1,0]
	v_pk_add_f32 v[162:163], v[162:163], 1.0 op_sel_hi:[1,0]
	v_rcp_f32_e32 v160, v160
	v_rcp_f32_e32 v162, v162
	v_rcp_f32_e32 v161, v161
	v_rcp_f32_e32 v163, v163
	v_pk_mul_f32 v[152:153], v[152:153], v[158:159]
	v_pk_mul_f32 v[154:155], v[154:155], v[156:157]
	v_pk_mul_f32 v[152:153], v[152:153], v[160:161]
	v_pk_mul_f32 v[154:155], v[154:155], v[162:163]
	v_cvt_pk_bf16_f32 v154, v154, v155
	v_cvt_pk_bf16_f32 v155, v152, v153
	s_mul_i32 s100, s77, 16
	v_lshl_add_u64 v[168:169], v[178:179], 0, s[100:101]
	v_add_u32_e32 v170, v222, v211
	ds_bpermute_b32 v236, v244, v168
	ds_bpermute_b32 v237, v244, v169
	ds_bpermute_b32 v238, v244, v154
	ds_bpermute_b32 v239, v244, v155
	s_waitcnt lgkmcnt(0)
	global_store_dwordx2 v[236:237], v[238:239], off
	s_and_saveexec_b64 s[6:7], s[96:97]
	s_cbranch_execz .LBB0_1697
	v_mov_b64_e32 v[152:153], s[24:25]
	v_mad_i64_i32 v[152:153], vcc, v170, s76, v[152:153]
	v_lshl_add_u64 v[152:153], v[196:197], 2, v[152:153]
	global_store_dwordx4 v[152:153], v[148:151], off
	v_add_co_u32_e32 v152, vcc, 0x2000, v152
	s_nop 1
	v_addc_co_u32_e32 v153, vcc, 0, v153, vcc
	global_store_dwordx4 v[152:153], v[144:147], off offset:3072
.LBB0_1697:
	s_or_b64 exec, exec, s[6:7]
	v_add_u32_e32 v152, 0xffffc020, v221
	v_ashrrev_i32_e32 v152, 1, v152
	v_and_b32_e32 v171, -10, v152
	s_and_b64 vcc, exec, s[22:23]
	s_mov_b64 s[6:7], -1
	s_cbranch_vccnz .LBB0_1699
	v_or_b32_e32 v154, 1, v152
	v_mov_b64_e32 v[152:153], s[48:49]
	v_mad_i64_i32 v[154:155], vcc, v154, s76, v[152:153]
	v_mad_i64_i32 v[152:153], vcc, v171, s76, v[152:153]
	v_lshl_add_u64 v[166:167], v[154:155], 0, v[198:199]
	v_lshl_add_u64 v[164:165], v[152:153], 0, v[198:199]
	global_load_dwordx4 v[152:155], v[166:167], off
	global_load_dwordx4 v[156:159], v[164:165], off
	v_mov_b32_e32 v160, v140
	v_mov_b32_e32 v161, v140
	v_mov_b32_e32 v162, v141
	v_mov_b32_e32 v163, v141
	v_mov_b32_e32 v223, v142
	v_mov_b32_e32 v225, v143
	v_mov_b32_e32 v222, v142
	v_mov_b32_e32 v224, v143
	v_mov_b32_dpp v160, v160 row_ror:1 row_mask:0xf bank_mask:0xf
	v_mov_b32_dpp v161, v161 row_ror:2 row_mask:0xf bank_mask:0xf
	v_mov_b32_dpp v162, v162 row_ror:1 row_mask:0xf bank_mask:0xf
	v_mov_b32_dpp v163, v163 row_ror:2 row_mask:0xf bank_mask:0xf
	v_mov_b32_dpp v223, v223 row_ror:2 row_mask:0xf bank_mask:0xf
	v_mov_b32_dpp v225, v225 row_ror:2 row_mask:0xf bank_mask:0xf
	v_mov_b32_dpp v222, v222 row_ror:1 row_mask:0xf bank_mask:0xf
	v_mov_b32_dpp v224, v224 row_ror:1 row_mask:0xf bank_mask:0xf
	s_waitcnt vmcnt(1)
	v_cndmask_b32_e64 v161, v161, v152, s[14:15]
	v_cndmask_b32_e64 v152, v160, v152, s[12:13]
	v_cndmask_b32_e64 v160, v163, v153, s[14:15]
	v_cndmask_b32_e64 v153, v162, v153, s[12:13]
	v_cndmask_b32_e64 v162, v223, v154, s[14:15]
	v_cndmask_b32_e64 v163, v225, v155, s[14:15]
	v_cndmask_b32_e64 v154, v222, v154, s[12:13]
	v_cndmask_b32_e64 v155, v224, v155, s[12:13]
	s_waitcnt vmcnt(0)
	v_cndmask_b32_e64 v156, v161, v156, s[12:13]
	v_cndmask_b32_e64 v157, v160, v157, s[12:13]
	v_cndmask_b32_e64 v158, v162, v158, s[12:13]
	v_cndmask_b32_e64 v159, v163, v159, s[12:13]
	s_cbranch_execnz .LBB0_1701
	s_branch .LBB0_1700

; __device__ __forceinline__ f32x4 gelu_mul4(f32x4 x, f32x4 v) {
;     const f32x4 t = x * x;
;     const f32x4 u = t * (-2.0f * 0.7978845608028654f * 0.044715f * 1.4426950408889634f) + (-2.0f * 0.7978845608028654f * 1.4426950408889634f);
;     const f32x4 z = x * u;
;     __device__ __forceinline__ void operator()(const f32x4 (&acc)[2][2][4][2], const pg8::Unit& u, int wr, int wc, int fr, int fq, PG8_LAS unsigned char* xl) const {
;     ...
;                         const f32x4 cur = acc[ai][bj][m][n]; f32x4 p1, p2;
;                         if (!sample) { const f32x4 prv = (m == 0) ? hb[bj] : acc[ai][bj][m == 0 ? 0 : m - 1][n];
; #pragma unroll
;                             for (int j = 0; j < 4; ++j) { const float s1 = fr == 15 ? prv[j] : cur[j], s2 = fr >= 14 ? prv[j] : cur[j]; p1[j] = dpp_ror<1>(s1); p2[j] = dpp_ror<2>(s2); }
;                         } else { const int t = fr & 3, b = (row - MP) >> 2;
; #pragma unroll
;                             for (int j = 0; j < 4; ++j) { p1[j] = dpp_ror<1>(cur[j]); p2[j] = dpp_ror<2>(cur[j]); }
;                             const f32x4 c1 = *(const f32x4*)(ctx_s + (size_t)(b * 2 + 1) * FF2 + bj * FF + jc0 + 4 * n), c0 = *(const f32x4*)(ctx_s + (size_t)(b * 2) * FF2 + bj * FF + jc0 + 4 * n);
; #pragma unroll
;                             for (int j = 0; j < 4; ++j) { p2[j] = t == 0 ? c0[j] : (t == 1 ? c1[j] : p2[j]); p1[j] = t == 0 ? c1[j] : p1[j]; }
;                         }
;                         cc[bj] = bb[bj] + w0[bj] * p2 + w1[bj] * p1 + w2[bj] * cur;
;                     }
;                     const f32x4 gv = gelu_mul4(cc[0], cc[1]);
;                     u32x2 w; w.x = pk2(gv[0], gv[1]); w.y = pk2(gv[2], gv[3]);
;                     *(u32x2*)(G + (size_t)row * FF + jc0 + 4 * n) = w;
;                     if (!sample && ai == 0 && wr == 0 && m == 0 && fr < 2 && (pm & 7) != 0) {
; #pragma unroll
;                         for (int bj = 0; bj < 2; ++bj) *(f32x4*)(PH + (size_t)(pm * 2 + fr) * FF2 + bj * FF + jc0 + 4 * n) = cc[bj];
;                     }
;                     if (sample && (fr & 3) >= 2) { const int b = (row - MP) >> 2, t = fr & 3;
; #pragma unroll
;                         for (int bj = 0; bj < 2; ++bj) *(f32x4*)(nf_s + (size_t)(b * 2 + t - 2) * FF2 + bj * FF + jc0 + 4 * n) = acc[ai][bj][m][n];
.LBB0_1705:
	v_pk_fma_f32 v[144:145], v[114:115], v[158:159], v[118:119]
	v_pk_fma_f32 v[146:147], v[112:113], v[156:157], v[116:117]
	v_pk_fma_f32 v[144:145], v[106:107], v[154:155], v[144:145]
	v_pk_fma_f32 v[146:147], v[104:105], v[152:153], v[146:147]
	v_pk_fma_f32 v[144:145], v[142:143], v[98:99], v[144:145]
	v_pk_fma_f32 v[146:147], v[140:141], v[96:97], v[146:147]
	v_pk_fma_f32 v[152:153], v[110:111], v[162:163], v[122:123]
	v_pk_fma_f32 v[154:155], v[108:109], v[160:161], v[120:121]
	v_pk_fma_f32 v[150:151], v[102:103], v[150:151], v[152:153]
	v_pk_fma_f32 v[148:149], v[100:101], v[148:149], v[154:155]
	v_pk_mul_f32 v[152:153], v[144:145], v[144:145]
	v_pk_mul_f32 v[154:155], v[146:147], v[146:147]
	v_pk_fma_f32 v[152:153], v[152:153], s[82:83], v[246:247] op_sel_hi:[1,0,0]
	v_pk_fma_f32 v[154:155], v[154:155], s[82:83], v[246:247] op_sel_hi:[1,0,0]
	v_pk_mul_f32 v[152:153], v[144:145], v[152:153]
	v_pk_mul_f32 v[154:155], v[146:147], v[154:155]
	v_exp_f32_e32 v152, v152
	v_exp_f32_e32 v154, v154
	v_exp_f32_e32 v153, v153
	v_exp_f32_e32 v155, v155
	v_pk_fma_f32 v[150:151], v[138:139], v[94:95], v[150:151]
	v_pk_fma_f32 v[148:149], v[136:137], v[92:93], v[148:149]
	v_pk_add_f32 v[152:153], v[152:153], 1.0 op_sel_hi:[1,0]
	v_pk_add_f32 v[154:155], v[154:155], 1.0 op_sel_hi:[1,0]
	v_rcp_f32_e32 v152, v152
	v_rcp_f32_e32 v154, v154
	v_rcp_f32_e32 v153, v153
	v_rcp_f32_e32 v155, v155
	v_pk_mul_f32 v[144:145], v[144:145], v[150:151]
	v_pk_mul_f32 v[146:147], v[146:147], v[148:149]
	v_pk_mul_f32 v[144:145], v[144:145], v[152:153]
	v_pk_mul_f32 v[146:147], v[146:147], v[154:155]
	v_cvt_pk_bf16_f32 v146, v146, v147
	v_cvt_pk_bf16_f32 v147, v144, v145
	s_mul_i32 s100, s77, 32
	v_lshl_add_u64 v[160:161], v[178:179], 0, s[100:101]
	v_add_u32_e32 v162, v171, v211
	ds_bpermute_b32 v236, v244, v160
	ds_bpermute_b32 v237, v244, v161
	ds_bpermute_b32 v238, v244, v146
	ds_bpermute_b32 v239, v244, v147
	s_waitcnt lgkmcnt(0)
	global_store_dwordx2 v[236:237], v[238:239], off
	s_and_saveexec_b64 s[6:7], s[96:97]
	s_cbranch_execz .LBB0_1707
	v_mov_b64_e32 v[144:145], s[24:25]
	v_mad_i64_i32 v[144:145], vcc, v162, s76, v[144:145]
	v_lshl_add_u64 v[144:145], v[196:197], 2, v[144:145]
	global_store_dwordx4 v[144:145], v[140:143], off
	v_add_co_u32_e32 v144, vcc, 0x2000, v144
	s_nop 1
	v_addc_co_u32_e32 v145, vcc, 0, v145, vcc
	global_store_dwordx4 v[144:145], v[136:139], off offset:3072
.LBB0_1707:
	s_or_b64 exec, exec, s[6:7]
	v_add_u32_e32 v144, 0xffffc030, v221
	v_ashrrev_i32_e32 v144, 1, v144
	v_and_b32_e32 v163, -2, v144
	s_and_b64 vcc, exec, s[22:23]
	s_mov_b64 s[6:7], -1
	s_cbranch_vccnz .LBB0_1709
	v_or_b32_e32 v146, 1, v144
	v_mov_b64_e32 v[144:145], s[48:49]
	v_mad_i64_i32 v[146:147], vcc, v146, s76, v[144:145]
	v_mad_i64_i32 v[144:145], vcc, v163, s76, v[144:145]
	v_lshl_add_u64 v[158:159], v[146:147], 0, v[198:199]
	v_lshl_add_u64 v[156:157], v[144:145], 0, v[198:199]
	global_load_dwordx4 v[144:147], v[158:159], off
	global_load_dwordx4 v[148:151], v[156:157], off
	v_mov_b32_e32 v152, v132
	v_mov_b32_e32 v153, v132
	v_mov_b32_e32 v154, v133
	v_mov_b32_e32 v155, v133
	v_mov_b32_e32 v222, v134
	v_mov_b32_e32 v224, v135
	v_mov_b32_e32 v171, v134
	v_mov_b32_e32 v223, v135
	v_mov_b32_dpp v152, v152 row_ror:1 row_mask:0xf bank_mask:0xf
	v_mov_b32_dpp v153, v153 row_ror:2 row_mask:0xf bank_mask:0xf
	v_mov_b32_dpp v154, v154 row_ror:1 row_mask:0xf bank_mask:0xf
	v_mov_b32_dpp v155, v155 row_ror:2 row_mask:0xf bank_mask:0xf
	v_mov_b32_dpp v222, v222 row_ror:2 row_mask:0xf bank_mask:0xf
	v_mov_b32_dpp v224, v224 row_ror:2 row_mask:0xf bank_mask:0xf
	v_mov_b32_dpp v171, v171 row_ror:1 row_mask:0xf bank_mask:0xf
	v_mov_b32_dpp v223, v223 row_ror:1 row_mask:0xf bank_mask:0xf
	s_waitcnt vmcnt(1)
	v_cndmask_b32_e64 v153, v153, v144, s[14:15]
	v_cndmask_b32_e64 v144, v152, v144, s[12:13]
	v_cndmask_b32_e64 v152, v155, v145, s[14:15]
	v_cndmask_b32_e64 v145, v154, v145, s[12:13]
	v_cndmask_b32_e64 v154, v222, v146, s[14:15]
	v_cndmask_b32_e64 v155, v224, v147, s[14:15]
	v_cndmask_b32_e64 v146, v171, v146, s[12:13]
	v_cndmask_b32_e64 v147, v223, v147, s[12:13]
	s_waitcnt vmcnt(0)
	v_cndmask_b32_e64 v148, v153, v148, s[12:13]
	v_cndmask_b32_e64 v149, v152, v149, s[12:13]
	v_cndmask_b32_e64 v150, v154, v150, s[12:13]
	v_cndmask_b32_e64 v151, v155, v151, s[12:13]
	s_cbranch_execnz .LBB0_1711
	s_branch .LBB0_1710

; __device__ __forceinline__ unsigned pk2(float lo, float hi) { const f32x2 v = {lo, hi}; const bf16x2_t b = __builtin_convertvector(v, bf16x2_t); return __builtin_bit_cast(unsigned, b); }
; __device__ __forceinline__ f32x4 gelu_mul4(f32x4 x, f32x4 v) {
;     const f32x4 t = x * x;
;     const f32x4 u = t * (-2.0f * 0.7978845608028654f * 0.044715f * 1.4426950408889634f) + (-2.0f * 0.7978845608028654f * 1.4426950408889634f);
;     const f32x4 z = x * u;
;     f32x4 d; d[0] = __builtin_amdgcn_exp2f(z[0]); d[1] = __builtin_amdgcn_exp2f(z[1]); d[2] = __builtin_amdgcn_exp2f(z[2]); d[3] = __builtin_amdgcn_exp2f(z[3]);
;     d = d + 1.0f;
;     f32x4 r; r[0] = __builtin_amdgcn_rcpf(d[0]); r[1] = __builtin_amdgcn_rcpf(d[1]); r[2] = __builtin_amdgcn_rcpf(d[2]); r[3] = __builtin_amdgcn_rcpf(d[3]);
;     return (x * v) * r;
; }
;     __device__ __forceinline__ void operator()(const f32x4 (&acc)[2][2][4][2], const pg8::Unit& u, int wr, int wc, int fr, int fq, PG8_LAS unsigned char* xl) const {
;     ...
;                         cc[bj] = bb[bj] + w0[bj] * p2 + w1[bj] * p1 + w2[bj] * cur;
;                     }
;                     const f32x4 gv = gelu_mul4(cc[0], cc[1]);
;                     u32x2 w; w.x = pk2(gv[0], gv[1]); w.y = pk2(gv[2], gv[3]);
;                     *(u32x2*)(G + (size_t)row * FF + jc0 + 4 * n) = w;
;                     if (!sample && ai == 0 && wr == 0 && m == 0 && fr < 2 && (pm & 7) != 0) {
; #pragma unroll
;                         for (int bj = 0; bj < 2; ++bj) *(f32x4*)(PH + (size_t)(pm * 2 + fr) * FF2 + bj * FF + jc0 + 4 * n) = cc[bj];
;                     }
;                     if (sample && (fr & 3) >= 2) { const int b = (row - MP) >> 2, t = fr & 3;
; #pragma unroll
;                         for (int bj = 0; bj < 2; ++bj) *(f32x4*)(nf_s + (size_t)(b * 2 + t - 2) * FF2 + bj * FF + jc0 + 4 * n) = acc[ai][bj][m][n];
.LBB0_1715:
	v_pk_fma_f32 v[136:137], v[114:115], v[150:151], v[118:119]
	v_pk_fma_f32 v[138:139], v[112:113], v[148:149], v[116:117]
	v_pk_fma_f32 v[136:137], v[106:107], v[146:147], v[136:137]
	v_pk_fma_f32 v[138:139], v[104:105], v[144:145], v[138:139]
	v_pk_fma_f32 v[136:137], v[134:135], v[98:99], v[136:137]
	v_pk_fma_f32 v[138:139], v[132:133], v[96:97], v[138:139]
	v_pk_fma_f32 v[144:145], v[110:111], v[154:155], v[122:123]
	v_pk_fma_f32 v[146:147], v[108:109], v[152:153], v[120:121]
	v_pk_fma_f32 v[142:143], v[102:103], v[142:143], v[144:145]
	v_pk_fma_f32 v[140:141], v[100:101], v[140:141], v[146:147]
	v_pk_mul_f32 v[144:145], v[136:137], v[136:137]
	v_pk_mul_f32 v[146:147], v[138:139], v[138:139]
	v_pk_fma_f32 v[144:145], v[144:145], s[82:83], v[246:247] op_sel_hi:[1,0,0]
	v_pk_fma_f32 v[146:147], v[146:147], s[82:83], v[246:247] op_sel_hi:[1,0,0]
	v_pk_mul_f32 v[144:145], v[136:137], v[144:145]
	v_pk_mul_f32 v[146:147], v[138:139], v[146:147]
	v_exp_f32_e32 v144, v144
	v_exp_f32_e32 v146, v146
	v_exp_f32_e32 v145, v145
	v_exp_f32_e32 v147, v147
	v_pk_fma_f32 v[142:143], v[130:131], v[94:95], v[142:143]
	v_pk_fma_f32 v[140:141], v[128:129], v[92:93], v[140:141]
	v_pk_add_f32 v[144:145], v[144:145], 1.0 op_sel_hi:[1,0]
	v_pk_add_f32 v[146:147], v[146:147], 1.0 op_sel_hi:[1,0]
	v_rcp_f32_e32 v144, v144
	v_rcp_f32_e32 v146, v146
	v_rcp_f32_e32 v145, v145
	v_rcp_f32_e32 v147, v147
	v_pk_mul_f32 v[136:137], v[136:137], v[142:143]
	v_pk_mul_f32 v[138:139], v[138:139], v[140:141]
	v_pk_mul_f32 v[136:137], v[136:137], v[144:145]
	v_pk_mul_f32 v[138:139], v[138:139], v[146:147]
	v_cvt_pk_bf16_f32 v138, v138, v139
	v_cvt_pk_bf16_f32 v139, v136, v137
	s_mul_i32 s100, s77, 48
	v_lshl_add_u64 v[152:153], v[178:179], 0, s[100:101]
	v_add_u32_e32 v154, v163, v211
	ds_bpermute_b32 v236, v244, v152
	ds_bpermute_b32 v237, v244, v153
	ds_bpermute_b32 v238, v244, v138
	ds_bpermute_b32 v239, v244, v139
	s_waitcnt lgkmcnt(0)
	global_store_dwordx2 v[236:237], v[238:239], off
	s_and_saveexec_b64 s[6:7], s[96:97]
	s_cbranch_execz .LBB0_1717
	v_mov_b64_e32 v[136:137], s[24:25]
	v_mad_i64_i32 v[136:137], vcc, v154, s76, v[136:137]
	v_lshl_add_u64 v[136:137], v[196:197], 2, v[136:137]
	global_store_dwordx4 v[136:137], v[132:135], off
	s_nop 1
	v_add_co_u32_e32 v132, vcc, 0x2000, v136
	s_nop 1
	v_addc_co_u32_e32 v133, vcc, 0, v137, vcc
	global_store_dwordx4 v[132:133], v[128:131], off offset:3072

; template <int N> __device__ __forceinline__ float dpp_ror(float v) { const int i = __builtin_bit_cast(int, v); return __builtin_bit_cast(float, __builtin_amdgcn_update_dpp(i, i, 0x120 + N, 0xF, 0xF, false)); }
;     __device__ __forceinline__ void operator()(const f32x4 (&acc)[2][2][4][2], const pg8::Unit& u, int wr, int wc, int fr, int fq, PG8_LAS unsigned char* xl) const {
;     ...
;                 for (int m = 0; m < 4; ++m) {
;                     const int row = pm * 256 + ai * 128 + wr * 64 + m * 16 + fr;
;                     f32x4 cc[2];
; #pragma unroll
;                     for (int bj = 0; bj < 2; ++bj) {
;                         const f32x4 cur = acc[ai][bj][m][n]; f32x4 p1, p2;
;                         if (!sample) { const f32x4 prv = (m == 0) ? hb[bj] : acc[ai][bj][m == 0 ? 0 : m - 1][n];
; #pragma unroll
;                             for (int j = 0; j < 4; ++j) { const float s1 = fr == 15 ? prv[j] : cur[j], s2 = fr >= 14 ? prv[j] : cur[j]; p1[j] = dpp_ror<1>(s1); p2[j] = dpp_ror<2>(s2); }
;                         } else { const int t = fr & 3, b = (row - MP) >> 2;
; #pragma unroll
;                             for (int j = 0; j < 4; ++j) { p1[j] = dpp_ror<1>(cur[j]); p2[j] = dpp_ror<2>(cur[j]); }
;                             const f32x4 c1 = *(const f32x4*)(ctx_s + (size_t)(b * 2 + 1) * FF2 + bj * FF + jc0 + 4 * n), c0 = *(const f32x4*)(ctx_s + (size_t)(b * 2) * FF2 + bj * FF + jc0 + 4 * n);
; #pragma unroll
;                             for (int j = 0; j < 4; ++j) { p2[j] = t == 0 ? c0[j] : (t == 1 ? c1[j] : p2[j]); p1[j] = t == 0 ? c1[j] : p1[j]; }
;                         }
.LBB0_1719:
	s_or_b64 exec, exec, s[6:7]
	v_add_u32_e32 v132, 0xffffc080, v221
	v_ashrrev_i32_e32 v132, 1, v132
	v_and_b32_e32 v155, 0xffffffe6, v132
	s_and_b64 vcc, exec, s[22:23]
	s_mov_b64 s[6:7], -1
	s_cbranch_vccnz .LBB0_1721
	v_or_b32_e32 v134, 1, v132
	v_mov_b64_e32 v[132:133], s[48:49]
	v_mad_i64_i32 v[134:135], vcc, v134, s76, v[132:133]
	v_mad_i64_i32 v[132:133], vcc, v155, s76, v[132:133]
	v_lshl_add_u64 v[150:151], v[134:135], 0, v[198:199]
	v_lshl_add_u64 v[148:149], v[132:133], 0, v[198:199]
	global_load_dwordx4 v[132:135], v[150:151], off
	global_load_dwordx4 v[136:139], v[148:149], off
	v_mov_b32_e32 v144, v124
	v_mov_b32_e32 v145, v124
	v_mov_b32_e32 v146, v125
	v_mov_b32_e32 v147, v125
	v_mov_b32_e32 v171, v126
	v_mov_b32_e32 v223, v127
	v_mov_b32_e32 v163, v126
	v_mov_b32_e32 v222, v127
	v_mov_b32_dpp v144, v144 row_ror:1 row_mask:0xf bank_mask:0xf
	v_mov_b32_dpp v145, v145 row_ror:2 row_mask:0xf bank_mask:0xf
	v_mov_b32_dpp v146, v146 row_ror:1 row_mask:0xf bank_mask:0xf
	v_mov_b32_dpp v147, v147 row_ror:2 row_mask:0xf bank_mask:0xf
	v_mov_b32_dpp v171, v171 row_ror:2 row_mask:0xf bank_mask:0xf
	v_mov_b32_dpp v223, v223 row_ror:2 row_mask:0xf bank_mask:0xf
	v_mov_b32_dpp v163, v163 row_ror:1 row_mask:0xf bank_mask:0xf
	v_mov_b32_dpp v222, v222 row_ror:1 row_mask:0xf bank_mask:0xf
	s_waitcnt vmcnt(1)
	v_cndmask_b32_e64 v145, v145, v132, s[14:15]
	v_cndmask_b32_e64 v132, v144, v132, s[12:13]
	v_cndmask_b32_e64 v144, v147, v133, s[14:15]
	v_cndmask_b32_e64 v133, v146, v133, s[12:13]
	v_cndmask_b32_e64 v146, v171, v134, s[14:15]
	v_cndmask_b32_e64 v147, v223, v135, s[14:15]
	v_cndmask_b32_e64 v134, v163, v134, s[12:13]
	v_cndmask_b32_e64 v135, v222, v135, s[12:13]
	s_waitcnt vmcnt(0)
	v_cndmask_b32_e64 v136, v145, v136, s[12:13]
	v_cndmask_b32_e64 v137, v144, v137, s[12:13]
	v_cndmask_b32_e64 v138, v146, v138, s[12:13]
	v_cndmask_b32_e64 v139, v147, v139, s[12:13]
	s_cbranch_execnz .LBB0_1723
	s_branch .LBB0_1722

; __device__ __forceinline__ f32x4 gelu_mul4(f32x4 x, f32x4 v) {
;     const f32x4 t = x * x;
;     const f32x4 u = t * (-2.0f * 0.7978845608028654f * 0.044715f * 1.4426950408889634f) + (-2.0f * 0.7978845608028654f * 1.4426950408889634f);
;     const f32x4 z = x * u;
;     __device__ __forceinline__ void operator()(const f32x4 (&acc)[2][2][4][2], const pg8::Unit& u, int wr, int wc, int fr, int fq, PG8_LAS unsigned char* xl) const {
;     ...
;                         const f32x4 cur = acc[ai][bj][m][n]; f32x4 p1, p2;
;                         if (!sample) { const f32x4 prv = (m == 0) ? hb[bj] : acc[ai][bj][m == 0 ? 0 : m - 1][n];
; #pragma unroll
;                             for (int j = 0; j < 4; ++j) { const float s1 = fr == 15 ? prv[j] : cur[j], s2 = fr >= 14 ? prv[j] : cur[j]; p1[j] = dpp_ror<1>(s1); p2[j] = dpp_ror<2>(s2); }
;                         } else { const int t = fr & 3, b = (row - MP) >> 2;
; #pragma unroll
;                             for (int j = 0; j < 4; ++j) { p1[j] = dpp_ror<1>(cur[j]); p2[j] = dpp_ror<2>(cur[j]); }
;                             const f32x4 c1 = *(const f32x4*)(ctx_s + (size_t)(b * 2 + 1) * FF2 + bj * FF + jc0 + 4 * n), c0 = *(const f32x4*)(ctx_s + (size_t)(b * 2) * FF2 + bj * FF + jc0 + 4 * n);
; #pragma unroll
;                             for (int j = 0; j < 4; ++j) { p2[j] = t == 0 ? c0[j] : (t == 1 ? c1[j] : p2[j]); p1[j] = t == 0 ? c1[j] : p1[j]; }
;                         }
;                         cc[bj] = bb[bj] + w0[bj] * p2 + w1[bj] * p1 + w2[bj] * cur;
;                     }
;                     const f32x4 gv = gelu_mul4(cc[0], cc[1]);
;                     u32x2 w; w.x = pk2(gv[0], gv[1]); w.y = pk2(gv[2], gv[3]);
;                     *(u32x2*)(G + (size_t)row * FF + jc0 + 4 * n) = w;
;                     if (!sample && ai == 0 && wr == 0 && m == 0 && fr < 2 && (pm & 7) != 0) {
; #pragma unroll
;                         for (int bj = 0; bj < 2; ++bj) *(f32x4*)(PH + (size_t)(pm * 2 + fr) * FF2 + bj * FF + jc0 + 4 * n) = cc[bj];
;                     }
;                     if (sample && (fr & 3) >= 2) { const int b = (row - MP) >> 2, t = fr & 3;
; #pragma unroll
;                         for (int bj = 0; bj < 2; ++bj) *(f32x4*)(nf_s + (size_t)(b * 2 + t - 2) * FF2 + bj * FF + jc0 + 4 * n) = acc[ai][bj][m][n];
.LBB0_1727:
	s_waitcnt lgkmcnt(0)
	v_pk_fma_f32 v[128:129], v[114:115], v[138:139], v[118:119]
	v_pk_fma_f32 v[130:131], v[112:113], v[136:137], v[116:117]
	v_pk_fma_f32 v[128:129], v[106:107], v[134:135], v[128:129]
	v_pk_fma_f32 v[130:131], v[104:105], v[132:133], v[130:131]
	v_pk_fma_f32 v[128:129], v[126:127], v[98:99], v[128:129]
	v_pk_fma_f32 v[130:131], v[124:125], v[96:97], v[130:131]
	v_pk_fma_f32 v[134:135], v[108:109], v[144:145], v[120:121]
	v_pk_mul_f32 v[136:137], v[128:129], v[128:129]
	v_pk_fma_f32 v[134:135], v[100:101], v[140:141], v[134:135]
	v_pk_mul_f32 v[138:139], v[130:131], v[130:131]
	v_pk_fma_f32 v[136:137], v[136:137], s[82:83], v[246:247] op_sel_hi:[1,0,0]
	v_pk_fma_f32 v[138:139], v[138:139], s[82:83], v[246:247] op_sel_hi:[1,0,0]
	v_pk_mul_f32 v[136:137], v[128:129], v[136:137]
	v_pk_mul_f32 v[138:139], v[130:131], v[138:139]
	v_exp_f32_e32 v136, v136
	v_exp_f32_e32 v138, v138
	v_exp_f32_e32 v137, v137
	v_exp_f32_e32 v139, v139
	v_pk_fma_f32 v[132:133], v[110:111], v[146:147], v[122:123]
	v_pk_fma_f32 v[134:135], v[88:89], v[92:93], v[134:135]
	v_pk_add_f32 v[136:137], v[136:137], 1.0 op_sel_hi:[1,0]
	v_pk_add_f32 v[138:139], v[138:139], 1.0 op_sel_hi:[1,0]
	v_rcp_f32_e32 v136, v136
	v_rcp_f32_e32 v138, v138
	v_rcp_f32_e32 v137, v137
	v_rcp_f32_e32 v139, v139
	v_pk_fma_f32 v[132:133], v[102:103], v[142:143], v[132:133]
	v_pk_mul_f32 v[130:131], v[130:131], v[134:135]
	v_pk_fma_f32 v[132:133], v[90:91], v[94:95], v[132:133]
	v_pk_mul_f32 v[130:131], v[130:131], v[138:139]
	v_pk_mul_f32 v[128:129], v[128:129], v[132:133]
	v_pk_mul_f32 v[128:129], v[128:129], v[136:137]
	v_cvt_pk_bf16_f32 v130, v130, v131
	v_cvt_pk_bf16_f32 v131, v128, v129
	s_mul_i32 s100, s77, 0x80
	v_lshl_add_u64 v[144:145], v[178:179], 0, s[100:101]
	v_add_u32_e32 v146, v155, v211
	ds_bpermute_b32 v236, v244, v144
	ds_bpermute_b32 v237, v244, v145
	ds_bpermute_b32 v238, v244, v130
	ds_bpermute_b32 v239, v244, v131
	s_waitcnt lgkmcnt(0)
	global_store_dwordx2 v[236:237], v[238:239], off
	s_and_saveexec_b64 s[6:7], s[96:97]
	s_cbranch_execz .LBB0_1729
	v_mov_b64_e32 v[128:129], s[24:25]
	v_mad_i64_i32 v[128:129], vcc, v146, s76, v[128:129]
	v_lshl_add_u64 v[128:129], v[196:197], 2, v[128:129]
	global_store_dwordx4 v[128:129], v[124:127], off
	v_add_co_u32_e32 v128, vcc, 0x2000, v128
	s_nop 1
	v_addc_co_u32_e32 v129, vcc, 0, v129, vcc
	global_store_dwordx4 v[128:129], v[88:91], off offset:3072
.LBB0_1729:
	s_or_b64 exec, exec, s[6:7]
	v_add_u32_e32 v128, 0xffffc090, v221
	v_ashrrev_i32_e32 v128, 1, v128
	v_and_b32_e32 v147, 0xffffffee, v128
	s_and_b64 vcc, exec, s[22:23]
	s_mov_b64 s[6:7], -1
	s_cbranch_vccnz .LBB0_1731
	v_or_b32_e32 v130, 1, v128
	v_mov_b64_e32 v[128:129], s[48:49]
	v_mad_i64_i32 v[130:131], vcc, v130, s76, v[128:129]
	v_mad_i64_i32 v[128:129], vcc, v147, s76, v[128:129]
	v_lshl_add_u64 v[142:143], v[130:131], 0, v[198:199]
	v_lshl_add_u64 v[140:141], v[128:129], 0, v[198:199]
	global_load_dwordx4 v[128:131], v[142:143], off
	global_load_dwordx4 v[132:135], v[140:141], off
	v_mov_b32_e32 v136, v84
	v_mov_b32_e32 v137, v84
	v_mov_b32_e32 v138, v85
	v_mov_b32_e32 v139, v85
	v_mov_b32_e32 v163, v86
	v_mov_b32_e32 v222, v87
	v_mov_b32_e32 v155, v86
	v_mov_b32_e32 v171, v87
	v_mov_b32_dpp v136, v136 row_ror:1 row_mask:0xf bank_mask:0xf
	v_mov_b32_dpp v137, v137 row_ror:2 row_mask:0xf bank_mask:0xf
	v_mov_b32_dpp v138, v138 row_ror:1 row_mask:0xf bank_mask:0xf
	v_mov_b32_dpp v139, v139 row_ror:2 row_mask:0xf bank_mask:0xf
	v_mov_b32_dpp v163, v163 row_ror:2 row_mask:0xf bank_mask:0xf
	v_mov_b32_dpp v222, v222 row_ror:2 row_mask:0xf bank_mask:0xf
	v_mov_b32_dpp v155, v155 row_ror:1 row_mask:0xf bank_mask:0xf
	v_mov_b32_dpp v171, v171 row_ror:1 row_mask:0xf bank_mask:0xf
	s_waitcnt vmcnt(1)
	v_cndmask_b32_e64 v137, v137, v128, s[14:15]
	v_cndmask_b32_e64 v128, v136, v128, s[12:13]
	v_cndmask_b32_e64 v136, v139, v129, s[14:15]
	v_cndmask_b32_e64 v129, v138, v129, s[12:13]
	v_cndmask_b32_e64 v138, v163, v130, s[14:15]
	v_cndmask_b32_e64 v139, v222, v131, s[14:15]
	v_cndmask_b32_e64 v130, v155, v130, s[12:13]
	v_cndmask_b32_e64 v131, v171, v131, s[12:13]
	s_waitcnt vmcnt(0)
	v_cndmask_b32_e64 v132, v137, v132, s[12:13]
	v_cndmask_b32_e64 v133, v136, v133, s[12:13]
	v_cndmask_b32_e64 v134, v138, v134, s[12:13]
	v_cndmask_b32_e64 v135, v139, v135, s[12:13]
	s_cbranch_execnz .LBB0_1733
	s_branch .LBB0_1732

; __device__ __forceinline__ f32x4 gelu_mul4(f32x4 x, f32x4 v) {
;     const f32x4 t = x * x;
;     const f32x4 u = t * (-2.0f * 0.7978845608028654f * 0.044715f * 1.4426950408889634f) + (-2.0f * 0.7978845608028654f * 1.4426950408889634f);
;     const f32x4 z = x * u;
;     __device__ __forceinline__ void operator()(const f32x4 (&acc)[2][2][4][2], const pg8::Unit& u, int wr, int wc, int fr, int fq, PG8_LAS unsigned char* xl) const {
;     ...
;                         const f32x4 cur = acc[ai][bj][m][n]; f32x4 p1, p2;
;                         if (!sample) { const f32x4 prv = (m == 0) ? hb[bj] : acc[ai][bj][m == 0 ? 0 : m - 1][n];
; #pragma unroll
;                             for (int j = 0; j < 4; ++j) { const float s1 = fr == 15 ? prv[j] : cur[j], s2 = fr >= 14 ? prv[j] : cur[j]; p1[j] = dpp_ror<1>(s1); p2[j] = dpp_ror<2>(s2); }
;                         } else { const int t = fr & 3, b = (row - MP) >> 2;
; #pragma unroll
;                             for (int j = 0; j < 4; ++j) { p1[j] = dpp_ror<1>(cur[j]); p2[j] = dpp_ror<2>(cur[j]); }
;                             const f32x4 c1 = *(const f32x4*)(ctx_s + (size_t)(b * 2 + 1) * FF2 + bj * FF + jc0 + 4 * n), c0 = *(const f32x4*)(ctx_s + (size_t)(b * 2) * FF2 + bj * FF + jc0 + 4 * n);
; #pragma unroll
;                             for (int j = 0; j < 4; ++j) { p2[j] = t == 0 ? c0[j] : (t == 1 ? c1[j] : p2[j]); p1[j] = t == 0 ? c1[j] : p1[j]; }
;                         }
;                         cc[bj] = bb[bj] + w0[bj] * p2 + w1[bj] * p1 + w2[bj] * cur;
;                     }
;                     const f32x4 gv = gelu_mul4(cc[0], cc[1]);
;                     u32x2 w; w.x = pk2(gv[0], gv[1]); w.y = pk2(gv[2], gv[3]);
;                     *(u32x2*)(G + (size_t)row * FF + jc0 + 4 * n) = w;
;                     if (!sample && ai == 0 && wr == 0 && m == 0 && fr < 2 && (pm & 7) != 0) {
; #pragma unroll
;                         for (int bj = 0; bj < 2; ++bj) *(f32x4*)(PH + (size_t)(pm * 2 + fr) * FF2 + bj * FF + jc0 + 4 * n) = cc[bj];
;                     }
;                     if (sample && (fr & 3) >= 2) { const int b = (row - MP) >> 2, t = fr & 3;
; #pragma unroll
;                         for (int bj = 0; bj < 2; ++bj) *(f32x4*)(nf_s + (size_t)(b * 2 + t - 2) * FF2 + bj * FF + jc0 + 4 * n) = acc[ai][bj][m][n];
.LBB0_1737:
	v_pk_fma_f32 v[88:89], v[114:115], v[134:135], v[118:119]
	v_pk_fma_f32 v[90:91], v[112:113], v[132:133], v[116:117]
	v_pk_fma_f32 v[88:89], v[106:107], v[130:131], v[88:89]
	v_pk_fma_f32 v[90:91], v[104:105], v[128:129], v[90:91]
	v_pk_fma_f32 v[88:89], v[86:87], v[98:99], v[88:89]
	v_pk_fma_f32 v[90:91], v[84:85], v[96:97], v[90:91]
	v_pk_fma_f32 v[128:129], v[110:111], v[138:139], v[122:123]
	v_pk_fma_f32 v[130:131], v[108:109], v[136:137], v[120:121]
	v_pk_fma_f32 v[126:127], v[102:103], v[126:127], v[128:129]
	v_pk_fma_f32 v[124:125], v[100:101], v[124:125], v[130:131]
	v_pk_mul_f32 v[128:129], v[88:89], v[88:89]
	v_pk_mul_f32 v[130:131], v[90:91], v[90:91]
	v_pk_fma_f32 v[128:129], v[128:129], s[82:83], v[246:247] op_sel_hi:[1,0,0]
	v_pk_fma_f32 v[130:131], v[130:131], s[82:83], v[246:247] op_sel_hi:[1,0,0]
	v_pk_mul_f32 v[128:129], v[88:89], v[128:129]
	v_pk_mul_f32 v[130:131], v[90:91], v[130:131]
	v_exp_f32_e32 v128, v128
	v_exp_f32_e32 v130, v130
	v_exp_f32_e32 v129, v129
	v_exp_f32_e32 v131, v131
	v_pk_fma_f32 v[126:127], v[82:83], v[94:95], v[126:127]
	v_pk_fma_f32 v[124:125], v[80:81], v[92:93], v[124:125]
	v_pk_add_f32 v[128:129], v[128:129], 1.0 op_sel_hi:[1,0]
	v_pk_add_f32 v[130:131], v[130:131], 1.0 op_sel_hi:[1,0]
	v_rcp_f32_e32 v128, v128
	v_rcp_f32_e32 v130, v130
	v_rcp_f32_e32 v129, v129
	v_rcp_f32_e32 v131, v131
	v_pk_mul_f32 v[88:89], v[88:89], v[126:127]
	v_pk_mul_f32 v[90:91], v[90:91], v[124:125]
	v_pk_mul_f32 v[88:89], v[88:89], v[128:129]
	v_pk_mul_f32 v[90:91], v[90:91], v[130:131]
	v_cvt_pk_bf16_f32 v90, v90, v91
	v_cvt_pk_bf16_f32 v91, v88, v89
	s_mul_i32 s100, s77, 0x90
	v_lshl_add_u64 v[136:137], v[178:179], 0, s[100:101]
	v_add_u32_e32 v138, v147, v211
	ds_bpermute_b32 v236, v244, v136
	ds_bpermute_b32 v237, v244, v137
	ds_bpermute_b32 v238, v244, v90
	ds_bpermute_b32 v239, v244, v91
	s_waitcnt lgkmcnt(0)
	global_store_dwordx2 v[236:237], v[238:239], off
	s_and_saveexec_b64 s[6:7], s[96:97]
	s_cbranch_execz .LBB0_1739
	v_mov_b64_e32 v[88:89], s[24:25]
	v_mad_i64_i32 v[88:89], vcc, v138, s76, v[88:89]
	v_lshl_add_u64 v[88:89], v[196:197], 2, v[88:89]
	global_store_dwordx4 v[88:89], v[84:87], off
	v_add_co_u32_e32 v88, vcc, 0x2000, v88
	s_nop 1
	v_addc_co_u32_e32 v89, vcc, 0, v89, vcc
	global_store_dwordx4 v[88:89], v[80:83], off offset:3072
.LBB0_1739:
	s_or_b64 exec, exec, s[6:7]
	v_add_u32_e32 v88, 0xffffc0a0, v221
	v_ashrrev_i32_e32 v88, 1, v88
	v_and_b32_e32 v139, -10, v88
	s_and_b64 vcc, exec, s[22:23]
	s_mov_b64 s[6:7], -1
	s_cbranch_vccnz .LBB0_1741
	v_or_b32_e32 v90, 1, v88
	v_mov_b64_e32 v[88:89], s[48:49]
	v_mad_i64_i32 v[90:91], vcc, v90, s76, v[88:89]
	v_mad_i64_i32 v[88:89], vcc, v139, s76, v[88:89]
	v_lshl_add_u64 v[134:135], v[90:91], 0, v[198:199]
	v_lshl_add_u64 v[132:133], v[88:89], 0, v[198:199]
	global_load_dwordx4 v[88:91], v[134:135], off
	global_load_dwordx4 v[124:127], v[132:133], off
	v_mov_b32_e32 v128, v76
	v_mov_b32_e32 v129, v76
	v_mov_b32_e32 v130, v77
	v_mov_b32_e32 v131, v77
	v_mov_b32_e32 v155, v78
	v_mov_b32_e32 v171, v79
	v_mov_b32_e32 v147, v78
	v_mov_b32_e32 v163, v79
	v_mov_b32_dpp v128, v128 row_ror:1 row_mask:0xf bank_mask:0xf
	v_mov_b32_dpp v129, v129 row_ror:2 row_mask:0xf bank_mask:0xf
	v_mov_b32_dpp v130, v130 row_ror:1 row_mask:0xf bank_mask:0xf
	v_mov_b32_dpp v131, v131 row_ror:2 row_mask:0xf bank_mask:0xf
	v_mov_b32_dpp v155, v155 row_ror:2 row_mask:0xf bank_mask:0xf
	v_mov_b32_dpp v171, v171 row_ror:2 row_mask:0xf bank_mask:0xf
	v_mov_b32_dpp v147, v147 row_ror:1 row_mask:0xf bank_mask:0xf
	v_mov_b32_dpp v163, v163 row_ror:1 row_mask:0xf bank_mask:0xf
	s_waitcnt vmcnt(1)
	v_cndmask_b32_e64 v129, v129, v88, s[14:15]
	v_cndmask_b32_e64 v88, v128, v88, s[12:13]
	v_cndmask_b32_e64 v128, v131, v89, s[14:15]
	v_cndmask_b32_e64 v89, v130, v89, s[12:13]
	v_cndmask_b32_e64 v130, v155, v90, s[14:15]
	v_cndmask_b32_e64 v131, v171, v91, s[14:15]
	v_cndmask_b32_e64 v90, v147, v90, s[12:13]
	v_cndmask_b32_e64 v91, v163, v91, s[12:13]
	s_waitcnt vmcnt(0)
	v_cndmask_b32_e64 v124, v129, v124, s[12:13]
	v_cndmask_b32_e64 v125, v128, v125, s[12:13]
	v_cndmask_b32_e64 v126, v130, v126, s[12:13]
	v_cndmask_b32_e64 v127, v131, v127, s[12:13]
	s_cbranch_execnz .LBB0_1743
	s_branch .LBB0_1742

; __device__ __forceinline__ f32x4 gelu_mul4(f32x4 x, f32x4 v) {
;     const f32x4 t = x * x;
;     const f32x4 u = t * (-2.0f * 0.7978845608028654f * 0.044715f * 1.4426950408889634f) + (-2.0f * 0.7978845608028654f * 1.4426950408889634f);
;     const f32x4 z = x * u;
;     __device__ __forceinline__ void operator()(const f32x4 (&acc)[2][2][4][2], const pg8::Unit& u, int wr, int wc, int fr, int fq, PG8_LAS unsigned char* xl) const {
;     ...
;                         const f32x4 cur = acc[ai][bj][m][n]; f32x4 p1, p2;
;                         if (!sample) { const f32x4 prv = (m == 0) ? hb[bj] : acc[ai][bj][m == 0 ? 0 : m - 1][n];
; #pragma unroll
;                             for (int j = 0; j < 4; ++j) { const float s1 = fr == 15 ? prv[j] : cur[j], s2 = fr >= 14 ? prv[j] : cur[j]; p1[j] = dpp_ror<1>(s1); p2[j] = dpp_ror<2>(s2); }
;                         } else { const int t = fr & 3, b = (row - MP) >> 2;
; #pragma unroll
;                             for (int j = 0; j < 4; ++j) { p1[j] = dpp_ror<1>(cur[j]); p2[j] = dpp_ror<2>(cur[j]); }
;                             const f32x4 c1 = *(const f32x4*)(ctx_s + (size_t)(b * 2 + 1) * FF2 + bj * FF + jc0 + 4 * n), c0 = *(const f32x4*)(ctx_s + (size_t)(b * 2) * FF2 + bj * FF + jc0 + 4 * n);
; #pragma unroll
;                             for (int j = 0; j < 4; ++j) { p2[j] = t == 0 ? c0[j] : (t == 1 ? c1[j] : p2[j]); p1[j] = t == 0 ? c1[j] : p1[j]; }
;                         }
;                         cc[bj] = bb[bj] + w0[bj] * p2 + w1[bj] * p1 + w2[bj] * cur;
;                     }
;                     const f32x4 gv = gelu_mul4(cc[0], cc[1]);
;                     u32x2 w; w.x = pk2(gv[0], gv[1]); w.y = pk2(gv[2], gv[3]);
;                     *(u32x2*)(G + (size_t)row * FF + jc0 + 4 * n) = w;
;                     if (!sample && ai == 0 && wr == 0 && m == 0 && fr < 2 && (pm & 7) != 0) {
; #pragma unroll
;                         for (int bj = 0; bj < 2; ++bj) *(f32x4*)(PH + (size_t)(pm * 2 + fr) * FF2 + bj * FF + jc0 + 4 * n) = cc[bj];
;                     }
;                     if (sample && (fr & 3) >= 2) { const int b = (row - MP) >> 2, t = fr & 3;
; #pragma unroll
;                         for (int bj = 0; bj < 2; ++bj) *(f32x4*)(nf_s + (size_t)(b * 2 + t - 2) * FF2 + bj * FF + jc0 + 4 * n) = acc[ai][bj][m][n];
.LBB0_1747:
	v_pk_fma_f32 v[80:81], v[114:115], v[126:127], v[118:119]
	v_pk_fma_f32 v[82:83], v[112:113], v[124:125], v[116:117]
	v_pk_fma_f32 v[80:81], v[106:107], v[90:91], v[80:81]
	v_pk_fma_f32 v[82:83], v[104:105], v[88:89], v[82:83]
	v_pk_fma_f32 v[80:81], v[78:79], v[98:99], v[80:81]
	v_pk_fma_f32 v[82:83], v[76:77], v[96:97], v[82:83]
	v_pk_fma_f32 v[88:89], v[110:111], v[130:131], v[122:123]
	v_pk_fma_f32 v[90:91], v[108:109], v[128:129], v[120:121]
	v_pk_fma_f32 v[86:87], v[102:103], v[86:87], v[88:89]
	v_pk_fma_f32 v[84:85], v[100:101], v[84:85], v[90:91]
	v_pk_mul_f32 v[88:89], v[80:81], v[80:81]
	v_pk_mul_f32 v[90:91], v[82:83], v[82:83]
	v_pk_fma_f32 v[88:89], v[88:89], s[82:83], v[246:247] op_sel_hi:[1,0,0]
	v_pk_fma_f32 v[90:91], v[90:91], s[82:83], v[246:247] op_sel_hi:[1,0,0]
	v_pk_mul_f32 v[88:89], v[80:81], v[88:89]
	v_pk_mul_f32 v[90:91], v[82:83], v[90:91]
	v_exp_f32_e32 v88, v88
	v_exp_f32_e32 v90, v90
	v_exp_f32_e32 v89, v89
	v_exp_f32_e32 v91, v91
	v_pk_fma_f32 v[86:87], v[74:75], v[94:95], v[86:87]
	v_pk_fma_f32 v[84:85], v[72:73], v[92:93], v[84:85]
	v_pk_add_f32 v[88:89], v[88:89], 1.0 op_sel_hi:[1,0]
	v_pk_add_f32 v[90:91], v[90:91], 1.0 op_sel_hi:[1,0]
	v_rcp_f32_e32 v88, v88
	v_rcp_f32_e32 v90, v90
	v_rcp_f32_e32 v89, v89
	v_rcp_f32_e32 v91, v91
	v_pk_mul_f32 v[80:81], v[80:81], v[86:87]
	v_pk_mul_f32 v[82:83], v[82:83], v[84:85]
	v_pk_mul_f32 v[80:81], v[80:81], v[88:89]
	v_pk_mul_f32 v[82:83], v[82:83], v[90:91]
	v_cvt_pk_bf16_f32 v82, v82, v83
	v_cvt_pk_bf16_f32 v83, v80, v81
	s_mul_i32 s100, s77, 0xa0
	v_lshl_add_u64 v[128:129], v[178:179], 0, s[100:101]
	v_add_u32_e32 v139, v139, v211
	ds_bpermute_b32 v236, v244, v128
	ds_bpermute_b32 v237, v244, v129
	ds_bpermute_b32 v238, v244, v82
	ds_bpermute_b32 v239, v244, v83
	s_waitcnt lgkmcnt(0)
	global_store_dwordx2 v[236:237], v[238:239], off
	s_and_saveexec_b64 s[6:7], s[96:97]
	s_cbranch_execz .LBB0_1749
	v_mov_b64_e32 v[80:81], s[24:25]
	v_mad_i64_i32 v[80:81], vcc, v139, s76, v[80:81]
	v_lshl_add_u64 v[80:81], v[196:197], 2, v[80:81]
	global_store_dwordx4 v[80:81], v[76:79], off
	v_add_co_u32_e32 v80, vcc, 0x2000, v80
	s_nop 1
	v_addc_co_u32_e32 v81, vcc, 0, v81, vcc
	global_store_dwordx4 v[80:81], v[72:75], off offset:3072
.LBB0_1749:
	s_or_b64 exec, exec, s[6:7]
	v_add_u32_e32 v80, 0xffffc0b0, v221
	v_ashrrev_i32_e32 v80, 1, v80
	v_and_b32_e32 v147, -2, v80
	s_and_b64 vcc, exec, s[22:23]
	s_mov_b64 s[6:7], -1
	s_cbranch_vccnz .LBB0_1751
	v_or_b32_e32 v82, 1, v80
	v_mov_b64_e32 v[80:81], s[48:49]
	v_mad_i64_i32 v[82:83], vcc, v82, s76, v[80:81]
	v_mad_i64_i32 v[80:81], vcc, v147, s76, v[80:81]
	v_lshl_add_u64 v[126:127], v[82:83], 0, v[198:199]
	v_lshl_add_u64 v[124:125], v[80:81], 0, v[198:199]
	global_load_dwordx4 v[80:83], v[126:127], off
	global_load_dwordx4 v[84:87], v[124:125], off
	v_mov_b32_e32 v88, v12
	v_mov_b32_e32 v89, v12
	v_mov_b32_e32 v90, v13
	v_mov_b32_e32 v91, v13
	v_mov_b32_e32 v131, v14
	v_mov_b32_e32 v163, v15
	v_mov_b32_e32 v130, v14
	v_mov_b32_e32 v155, v15
	v_mov_b32_dpp v88, v88 row_ror:1 row_mask:0xf bank_mask:0xf
	v_mov_b32_dpp v89, v89 row_ror:2 row_mask:0xf bank_mask:0xf
	v_mov_b32_dpp v90, v90 row_ror:1 row_mask:0xf bank_mask:0xf
	v_mov_b32_dpp v91, v91 row_ror:2 row_mask:0xf bank_mask:0xf
	v_mov_b32_dpp v131, v131 row_ror:2 row_mask:0xf bank_mask:0xf
	v_mov_b32_dpp v163, v163 row_ror:2 row_mask:0xf bank_mask:0xf
	v_mov_b32_dpp v130, v130 row_ror:1 row_mask:0xf bank_mask:0xf
	v_mov_b32_dpp v155, v155 row_ror:1 row_mask:0xf bank_mask:0xf
	s_waitcnt vmcnt(1)
	v_cndmask_b32_e64 v89, v89, v80, s[14:15]
	v_cndmask_b32_e64 v80, v88, v80, s[12:13]
	v_cndmask_b32_e64 v88, v91, v81, s[14:15]
	v_cndmask_b32_e64 v81, v90, v81, s[12:13]
	v_cndmask_b32_e64 v90, v131, v82, s[14:15]
	v_cndmask_b32_e64 v91, v163, v83, s[14:15]
	v_cndmask_b32_e64 v82, v130, v82, s[12:13]
	v_cndmask_b32_e64 v83, v155, v83, s[12:13]
	s_waitcnt vmcnt(0)
	v_cndmask_b32_e64 v84, v89, v84, s[12:13]
	v_cndmask_b32_e64 v85, v88, v85, s[12:13]
	v_cndmask_b32_e64 v86, v90, v86, s[12:13]
	v_cndmask_b32_e64 v87, v91, v87, s[12:13]
	s_cbranch_execnz .LBB0_1753
	s_branch .LBB0_1752

; __device__ __forceinline__ unsigned pk2(float lo, float hi) { const f32x2 v = {lo, hi}; const bf16x2_t b = __builtin_convertvector(v, bf16x2_t); return __builtin_bit_cast(unsigned, b); }
; __device__ __forceinline__ f32x4 gelu_mul4(f32x4 x, f32x4 v) {
;     const f32x4 t = x * x;
;     const f32x4 u = t * (-2.0f * 0.7978845608028654f * 0.044715f * 1.4426950408889634f) + (-2.0f * 0.7978845608028654f * 1.4426950408889634f);
;     const f32x4 z = x * u;
;     f32x4 d; d[0] = __builtin_amdgcn_exp2f(z[0]); d[1] = __builtin_amdgcn_exp2f(z[1]); d[2] = __builtin_amdgcn_exp2f(z[2]); d[3] = __builtin_amdgcn_exp2f(z[3]);
;     d = d + 1.0f;
;     f32x4 r; r[0] = __builtin_amdgcn_rcpf(d[0]); r[1] = __builtin_amdgcn_rcpf(d[1]); r[2] = __builtin_amdgcn_rcpf(d[2]); r[3] = __builtin_amdgcn_rcpf(d[3]);
;     return (x * v) * r;
; }
;     __device__ __forceinline__ void operator()(const f32x4 (&acc)[2][2][4][2], const pg8::Unit& u, int wr, int wc, int fr, int fq, PG8_LAS unsigned char* xl) const {
;     ...
;                         cc[bj] = bb[bj] + w0[bj] * p2 + w1[bj] * p1 + w2[bj] * cur;
;                     }
;                     const f32x4 gv = gelu_mul4(cc[0], cc[1]);
;                     u32x2 w; w.x = pk2(gv[0], gv[1]); w.y = pk2(gv[2], gv[3]);
;                     *(u32x2*)(G + (size_t)row * FF + jc0 + 4 * n) = w;
;                     if (!sample && ai == 0 && wr == 0 && m == 0 && fr < 2 && (pm & 7) != 0) {
; #pragma unroll
;                         for (int bj = 0; bj < 2; ++bj) *(f32x4*)(PH + (size_t)(pm * 2 + fr) * FF2 + bj * FF + jc0 + 4 * n) = cc[bj];
;                     }
;                     if (sample && (fr & 3) >= 2) { const int b = (row - MP) >> 2, t = fr & 3;
; #pragma unroll
;                         for (int bj = 0; bj < 2; ++bj) *(f32x4*)(nf_s + (size_t)(b * 2 + t - 2) * FF2 + bj * FF + jc0 + 4 * n) = acc[ai][bj][m][n];
;                     }
.LBB0_1757:
	v_pk_fma_f32 v[72:73], v[114:115], v[86:87], v[118:119]
	v_pk_fma_f32 v[74:75], v[112:113], v[84:85], v[116:117]
	v_pk_fma_f32 v[72:73], v[106:107], v[82:83], v[72:73]
	v_pk_fma_f32 v[74:75], v[104:105], v[80:81], v[74:75]
	v_pk_fma_f32 v[72:73], v[14:15], v[98:99], v[72:73]
	v_pk_fma_f32 v[74:75], v[12:13], v[96:97], v[74:75]
	v_pk_fma_f32 v[80:81], v[110:111], v[90:91], v[122:123]
	v_pk_fma_f32 v[82:83], v[108:109], v[88:89], v[120:121]
	v_pk_fma_f32 v[78:79], v[102:103], v[78:79], v[80:81]
	v_pk_fma_f32 v[76:77], v[100:101], v[76:77], v[82:83]
	v_pk_mul_f32 v[80:81], v[72:73], v[72:73]
	v_pk_mul_f32 v[82:83], v[74:75], v[74:75]
	v_pk_fma_f32 v[80:81], v[80:81], s[82:83], v[246:247] op_sel_hi:[1,0,0]
	v_pk_fma_f32 v[82:83], v[82:83], s[82:83], v[246:247] op_sel_hi:[1,0,0]
	v_pk_mul_f32 v[80:81], v[72:73], v[80:81]
	v_pk_mul_f32 v[82:83], v[74:75], v[82:83]
	v_exp_f32_e32 v80, v80
	v_exp_f32_e32 v82, v82
	v_exp_f32_e32 v81, v81
	v_exp_f32_e32 v83, v83
	v_pk_fma_f32 v[78:79], v[6:7], v[94:95], v[78:79]
	v_pk_fma_f32 v[76:77], v[4:5], v[92:93], v[76:77]
	v_pk_add_f32 v[80:81], v[80:81], 1.0 op_sel_hi:[1,0]
	v_pk_add_f32 v[82:83], v[82:83], 1.0 op_sel_hi:[1,0]
	v_rcp_f32_e32 v80, v80
	v_rcp_f32_e32 v82, v82
	v_rcp_f32_e32 v81, v81
	v_rcp_f32_e32 v83, v83
	v_pk_mul_f32 v[72:73], v[72:73], v[78:79]
	v_pk_mul_f32 v[74:75], v[74:75], v[76:77]
	v_pk_mul_f32 v[72:73], v[72:73], v[80:81]
	v_pk_mul_f32 v[74:75], v[74:75], v[82:83]
	v_cvt_pk_bf16_f32 v74, v74, v75
	v_cvt_pk_bf16_f32 v75, v72, v73
	s_mul_i32 s100, s77, 0xb0
	v_lshl_add_u64 v[130:131], v[178:179], 0, s[100:101]
	v_add_u32_e32 v147, v147, v211
	ds_bpermute_b32 v236, v244, v130
	ds_bpermute_b32 v237, v244, v131
	ds_bpermute_b32 v238, v244, v74
	ds_bpermute_b32 v239, v244, v75
	s_waitcnt lgkmcnt(0)
	global_store_dwordx2 v[236:237], v[238:239], off
	s_and_saveexec_b64 s[6:7], s[96:97]
	s_cbranch_execz .LBB0_1759
	v_mov_b64_e32 v[72:73], s[24:25]
	v_mad_i64_i32 v[72:73], vcc, v147, s76, v[72:73]
	v_lshl_add_u64 v[72:73], v[196:197], 2, v[72:73]
	global_store_dwordx4 v[72:73], v[12:15], off
	v_add_co_u32_e32 v72, vcc, 0x2000, v72
	s_nop 1
	v_addc_co_u32_e32 v73, vcc, 0, v73, vcc
	global_store_dwordx4 v[72:73], v[4:7], off offset:3072

; __device__ __forceinline__ unsigned pk2(float lo, float hi) { const f32x2 v = {lo, hi}; const bf16x2_t b = __builtin_convertvector(v, bf16x2_t); return __builtin_bit_cast(unsigned, b); }
; __device__ __forceinline__ f32x4 gelu_mul4(f32x4 x, f32x4 v) {
;     const f32x4 t = x * x;
;     const f32x4 u = t * (-2.0f * 0.7978845608028654f * 0.044715f * 1.4426950408889634f) + (-2.0f * 0.7978845608028654f * 1.4426950408889634f);
;     const f32x4 z = x * u;
;     f32x4 d; d[0] = __builtin_amdgcn_exp2f(z[0]); d[1] = __builtin_amdgcn_exp2f(z[1]); d[2] = __builtin_amdgcn_exp2f(z[2]); d[3] = __builtin_amdgcn_exp2f(z[3]);
;     d = d + 1.0f;
;     f32x4 r; r[0] = __builtin_amdgcn_rcpf(d[0]); r[1] = __builtin_amdgcn_rcpf(d[1]); r[2] = __builtin_amdgcn_rcpf(d[2]); r[3] = __builtin_amdgcn_rcpf(d[3]);
;     return (x * v) * r;
; }
;     __device__ __forceinline__ void operator()(const f32x4 (&acc)[2][2][4][2], const pg8::Unit& u, int wr, int wc, int fr, int fq, PG8_LAS unsigned char* xl) const {
;     ...
;                         cc[bj] = bb[bj] + w0[bj] * p2 + w1[bj] * p1 + w2[bj] * cur;
;                     }
;                     const f32x4 gv = gelu_mul4(cc[0], cc[1]);
;                     u32x2 w; w.x = pk2(gv[0], gv[1]); w.y = pk2(gv[2], gv[3]);
;                     *(u32x2*)(G + (size_t)row * FF + jc0 + 4 * n) = w;
;                     if (!sample && ai == 0 && wr == 0 && m == 0 && fr < 2 && (pm & 7) != 0) {
; #pragma unroll
;                         for (int bj = 0; bj < 2; ++bj) *(f32x4*)(PH + (size_t)(pm * 2 + fr) * FF2 + bj * FF + jc0 + 4 * n) = cc[bj];
;                     }
;                     if (sample && (fr & 3) >= 2) { const int b = (row - MP) >> 2, t = fr & 3;
; #pragma unroll
;                         for (int bj = 0; bj < 2; ++bj) *(f32x4*)(nf_s + (size_t)(b * 2 + t - 2) * FF2 + bj * FF + jc0 + 4 * n) = acc[ai][bj][m][n];
;                     }
.LBB0_1769:
	s_waitcnt vmcnt(5) lgkmcnt(0)
	v_pk_fma_f32 v[104:105], v[98:99], v[114:115], v[102:103]
	v_pk_fma_f32 v[106:107], v[96:97], v[112:113], v[100:101]
	v_pk_fma_f32 v[104:105], v[90:91], v[110:111], v[104:105]
	v_pk_fma_f32 v[108:109], v[88:89], v[108:109], v[106:107]
	s_waitcnt vmcnt(4)
	v_pk_fma_f32 v[106:107], v[70:71], v[82:83], v[104:105]
	v_pk_fma_f32 v[104:105], v[68:69], v[80:81], v[108:109]
	s_waitcnt vmcnt(0)
	v_pk_fma_f32 v[110:111], v[84:85], v[120:121], v[92:93]
	v_pk_mul_f32 v[114:115], v[104:105], v[104:105]
	v_pk_fma_f32 v[112:113], v[76:77], v[116:117], v[110:111]
	v_pk_mul_f32 v[110:111], v[106:107], v[106:107]
	v_pk_fma_f32 v[110:111], v[110:111], s[82:83], v[246:247] op_sel_hi:[1,0,0]
	v_pk_fma_f32 v[114:115], v[114:115], s[82:83], v[246:247] op_sel_hi:[1,0,0]
	v_pk_mul_f32 v[110:111], v[106:107], v[110:111]
	v_pk_mul_f32 v[114:115], v[104:105], v[114:115]
	v_exp_f32_e32 v116, v110
	v_exp_f32_e32 v114, v114
	v_exp_f32_e32 v117, v111
	v_exp_f32_e32 v115, v115
	v_pk_fma_f32 v[108:109], v[86:87], v[122:123], v[94:95]
	v_pk_add_f32 v[114:115], v[114:115], 1.0 op_sel_hi:[1,0]
	v_pk_fma_f32 v[108:109], v[78:79], v[118:119], v[108:109]
	v_rcp_f32_e32 v114, v114
	v_pk_fma_f32 v[110:111], v[66:67], v[74:75], v[108:109]
	v_pk_fma_f32 v[108:109], v[64:65], v[72:73], v[112:113]
	v_pk_add_f32 v[112:113], v[116:117], 1.0 op_sel_hi:[1,0]
	v_rcp_f32_e32 v115, v115
	v_rcp_f32_e32 v112, v112
	v_rcp_f32_e32 v113, v113
	v_pk_mul_f32 v[116:117], v[106:107], v[110:111]
	v_pk_mul_f32 v[118:119], v[104:105], v[108:109]
	v_pk_mul_f32 v[112:113], v[116:117], v[112:113]
	v_pk_mul_f32 v[114:115], v[118:119], v[114:115]
	s_nop 0
	v_cvt_pk_bf16_f32 v114, v114, v115
	v_cvt_pk_bf16_f32 v115, v112, v113
	ds_bpermute_b32 v236, v244, v178
	ds_bpermute_b32 v237, v244, v179
	ds_bpermute_b32 v238, v244, v114
	ds_bpermute_b32 v239, v244, v115
	s_waitcnt lgkmcnt(0)
	global_store_dwordx2 v[236:237], v[238:239], off offset:8
	s_and_saveexec_b64 s[6:7], s[58:59]
	s_cbranch_execz .LBB0_1771
	global_store_dwordx4 v[176:177], v[104:107], off offset:16
	s_nop 1
	v_add_co_u32_e32 v104, vcc, 0x2000, v176
	s_nop 1
	v_addc_co_u32_e32 v105, vcc, 0, v177, vcc
	global_store_dwordx4 v[104:105], v[108:111], off offset:3088
	s_or_b64 exec, exec, s[6:7]
	s_and_saveexec_b64 s[6:7], s[96:97]
	s_cbranch_execz .LBB0_1773
	s_branch .LBB0_1772

; __device__ __forceinline__ unsigned pk2(float lo, float hi) { const f32x2 v = {lo, hi}; const bf16x2_t b = __builtin_convertvector(v, bf16x2_t); return __builtin_bit_cast(unsigned, b); }
; __device__ __forceinline__ f32x4 gelu_mul4(f32x4 x, f32x4 v) {
;     const f32x4 t = x * x;
;     const f32x4 u = t * (-2.0f * 0.7978845608028654f * 0.044715f * 1.4426950408889634f) + (-2.0f * 0.7978845608028654f * 1.4426950408889634f);
;     const f32x4 z = x * u;
;     f32x4 d; d[0] = __builtin_amdgcn_exp2f(z[0]); d[1] = __builtin_amdgcn_exp2f(z[1]); d[2] = __builtin_amdgcn_exp2f(z[2]); d[3] = __builtin_amdgcn_exp2f(z[3]);
;     d = d + 1.0f;
;     f32x4 r; r[0] = __builtin_amdgcn_rcpf(d[0]); r[1] = __builtin_amdgcn_rcpf(d[1]); r[2] = __builtin_amdgcn_rcpf(d[2]); r[3] = __builtin_amdgcn_rcpf(d[3]);
;     return (x * v) * r;
; }
;     __device__ __forceinline__ void operator()(const f32x4 (&acc)[2][2][4][2], const pg8::Unit& u, int wr, int wc, int fr, int fq, PG8_LAS unsigned char* xl) const {
;     ...
;                         cc[bj] = bb[bj] + w0[bj] * p2 + w1[bj] * p1 + w2[bj] * cur;
;                     }
;                     const f32x4 gv = gelu_mul4(cc[0], cc[1]);
;                     u32x2 w; w.x = pk2(gv[0], gv[1]); w.y = pk2(gv[2], gv[3]);
;                     *(u32x2*)(G + (size_t)row * FF + jc0 + 4 * n) = w;
;                     if (!sample && ai == 0 && wr == 0 && m == 0 && fr < 2 && (pm & 7) != 0) {
; #pragma unroll
;                         for (int bj = 0; bj < 2; ++bj) *(f32x4*)(PH + (size_t)(pm * 2 + fr) * FF2 + bj * FF + jc0 + 4 * n) = cc[bj];
;                     }
;                     if (sample && (fr & 3) >= 2) { const int b = (row - MP) >> 2, t = fr & 3;
; #pragma unroll
;                         for (int bj = 0; bj < 2; ++bj) *(f32x4*)(nf_s + (size_t)(b * 2 + t - 2) * FF2 + bj * FF + jc0 + 4 * n) = acc[ai][bj][m][n];
;                     }
.LBB0_1781:
	v_pk_fma_f32 v[64:65], v[98:99], v[110:111], v[102:103]
	v_pk_fma_f32 v[66:67], v[96:97], v[108:109], v[100:101]
	v_pk_fma_f32 v[64:65], v[90:91], v[106:107], v[64:65]
	v_pk_fma_f32 v[66:67], v[88:89], v[104:105], v[66:67]
	v_pk_fma_f32 v[64:65], v[62:63], v[82:83], v[64:65]
	v_pk_fma_f32 v[66:67], v[60:61], v[80:81], v[66:67]
	v_pk_fma_f32 v[104:105], v[86:87], v[114:115], v[94:95]
	v_pk_fma_f32 v[106:107], v[84:85], v[112:113], v[92:93]
	v_pk_fma_f32 v[70:71], v[78:79], v[70:71], v[104:105]
	v_pk_fma_f32 v[68:69], v[76:77], v[68:69], v[106:107]
	v_pk_mul_f32 v[104:105], v[64:65], v[64:65]
	v_pk_mul_f32 v[106:107], v[66:67], v[66:67]
	v_pk_fma_f32 v[104:105], v[104:105], s[82:83], v[246:247] op_sel_hi:[1,0,0]
	v_pk_fma_f32 v[106:107], v[106:107], s[82:83], v[246:247] op_sel_hi:[1,0,0]
	v_pk_mul_f32 v[104:105], v[64:65], v[104:105]
	v_pk_mul_f32 v[106:107], v[66:67], v[106:107]
	v_exp_f32_e32 v104, v104
	v_exp_f32_e32 v106, v106
	v_exp_f32_e32 v105, v105
	v_exp_f32_e32 v107, v107
	v_pk_fma_f32 v[70:71], v[58:59], v[74:75], v[70:71]
	v_pk_fma_f32 v[68:69], v[56:57], v[72:73], v[68:69]
	v_pk_add_f32 v[104:105], v[104:105], 1.0 op_sel_hi:[1,0]
	v_pk_add_f32 v[106:107], v[106:107], 1.0 op_sel_hi:[1,0]
	v_rcp_f32_e32 v104, v104
	v_rcp_f32_e32 v106, v106
	v_rcp_f32_e32 v105, v105
	v_rcp_f32_e32 v107, v107
	v_pk_mul_f32 v[64:65], v[64:65], v[70:71]
	v_pk_mul_f32 v[66:67], v[66:67], v[68:69]
	v_pk_mul_f32 v[64:65], v[64:65], v[104:105]
	v_pk_mul_f32 v[66:67], v[66:67], v[106:107]
	s_nop 0
	v_cvt_pk_bf16_f32 v66, v66, v67
	v_cvt_pk_bf16_f32 v67, v64, v65
	ds_bpermute_b32 v236, v244, v168
	ds_bpermute_b32 v237, v244, v169
	ds_bpermute_b32 v238, v244, v66
	ds_bpermute_b32 v239, v244, v67
	s_waitcnt lgkmcnt(0)
	global_store_dwordx2 v[236:237], v[238:239], off offset:8
	s_and_saveexec_b64 s[6:7], s[96:97]
	s_cbranch_execz .LBB0_1783
	v_mov_b64_e32 v[64:65], s[24:25]
	v_mad_i64_i32 v[64:65], s[58:59], v170, s76, v[64:65]
	v_lshl_add_u64 v[64:65], v[196:197], 2, v[64:65]
	global_store_dwordx4 v[64:65], v[60:63], off offset:16
	v_add_co_u32_e32 v64, vcc, 0x2000, v64
	s_nop 1
	v_addc_co_u32_e32 v65, vcc, 0, v65, vcc
	global_store_dwordx4 v[64:65], v[56:59], off offset:3088

; __device__ __forceinline__ unsigned pk2(float lo, float hi) { const f32x2 v = {lo, hi}; const bf16x2_t b = __builtin_convertvector(v, bf16x2_t); return __builtin_bit_cast(unsigned, b); }
; __device__ __forceinline__ f32x4 gelu_mul4(f32x4 x, f32x4 v) {
;     const f32x4 t = x * x;
;     const f32x4 u = t * (-2.0f * 0.7978845608028654f * 0.044715f * 1.4426950408889634f) + (-2.0f * 0.7978845608028654f * 1.4426950408889634f);
;     const f32x4 z = x * u;
;     f32x4 d; d[0] = __builtin_amdgcn_exp2f(z[0]); d[1] = __builtin_amdgcn_exp2f(z[1]); d[2] = __builtin_amdgcn_exp2f(z[2]); d[3] = __builtin_amdgcn_exp2f(z[3]);
;     d = d + 1.0f;
;     f32x4 r; r[0] = __builtin_amdgcn_rcpf(d[0]); r[1] = __builtin_amdgcn_rcpf(d[1]); r[2] = __builtin_amdgcn_rcpf(d[2]); r[3] = __builtin_amdgcn_rcpf(d[3]);
;     return (x * v) * r;
; }
;     __device__ __forceinline__ void operator()(const f32x4 (&acc)[2][2][4][2], const pg8::Unit& u, int wr, int wc, int fr, int fq, PG8_LAS unsigned char* xl) const {
;     ...
;                         cc[bj] = bb[bj] + w0[bj] * p2 + w1[bj] * p1 + w2[bj] * cur;
;                     }
;                     const f32x4 gv = gelu_mul4(cc[0], cc[1]);
;                     u32x2 w; w.x = pk2(gv[0], gv[1]); w.y = pk2(gv[2], gv[3]);
;                     *(u32x2*)(G + (size_t)row * FF + jc0 + 4 * n) = w;
;                     if (!sample && ai == 0 && wr == 0 && m == 0 && fr < 2 && (pm & 7) != 0) {
; #pragma unroll
;                         for (int bj = 0; bj < 2; ++bj) *(f32x4*)(PH + (size_t)(pm * 2 + fr) * FF2 + bj * FF + jc0 + 4 * n) = cc[bj];
;                     }
;                     if (sample && (fr & 3) >= 2) { const int b = (row - MP) >> 2, t = fr & 3;
; #pragma unroll
;                         for (int bj = 0; bj < 2; ++bj) *(f32x4*)(nf_s + (size_t)(b * 2 + t - 2) * FF2 + bj * FF + jc0 + 4 * n) = acc[ai][bj][m][n];
;                     }
.LBB0_1791:
	v_pk_fma_f32 v[56:57], v[98:99], v[70:71], v[102:103]
	v_pk_fma_f32 v[58:59], v[96:97], v[68:69], v[100:101]
	v_pk_fma_f32 v[56:57], v[90:91], v[66:67], v[56:57]
	v_pk_fma_f32 v[58:59], v[88:89], v[64:65], v[58:59]
	v_pk_fma_f32 v[56:57], v[54:55], v[82:83], v[56:57]
	v_pk_fma_f32 v[58:59], v[52:53], v[80:81], v[58:59]
	v_pk_fma_f32 v[64:65], v[86:87], v[106:107], v[94:95]
	v_pk_fma_f32 v[66:67], v[84:85], v[104:105], v[92:93]
	v_pk_fma_f32 v[62:63], v[78:79], v[62:63], v[64:65]
	v_pk_fma_f32 v[60:61], v[76:77], v[60:61], v[66:67]
	v_pk_mul_f32 v[64:65], v[56:57], v[56:57]
	v_pk_mul_f32 v[66:67], v[58:59], v[58:59]
	v_pk_fma_f32 v[64:65], v[64:65], s[82:83], v[246:247] op_sel_hi:[1,0,0]
	v_pk_fma_f32 v[66:67], v[66:67], s[82:83], v[246:247] op_sel_hi:[1,0,0]
	v_pk_mul_f32 v[64:65], v[56:57], v[64:65]
	v_pk_mul_f32 v[66:67], v[58:59], v[66:67]
	v_exp_f32_e32 v64, v64
	v_exp_f32_e32 v66, v66
	v_exp_f32_e32 v65, v65
	v_exp_f32_e32 v67, v67
	v_pk_fma_f32 v[62:63], v[50:51], v[74:75], v[62:63]
	v_pk_fma_f32 v[60:61], v[48:49], v[72:73], v[60:61]
	v_pk_add_f32 v[64:65], v[64:65], 1.0 op_sel_hi:[1,0]
	v_pk_add_f32 v[66:67], v[66:67], 1.0 op_sel_hi:[1,0]
	v_rcp_f32_e32 v64, v64
	v_rcp_f32_e32 v66, v66
	v_rcp_f32_e32 v65, v65
	v_rcp_f32_e32 v67, v67
	v_pk_mul_f32 v[56:57], v[56:57], v[62:63]
	v_pk_mul_f32 v[58:59], v[58:59], v[60:61]
	v_pk_mul_f32 v[56:57], v[56:57], v[64:65]
	v_pk_mul_f32 v[58:59], v[58:59], v[66:67]
	s_nop 0
	v_cvt_pk_bf16_f32 v58, v58, v59
	v_cvt_pk_bf16_f32 v59, v56, v57
	ds_bpermute_b32 v236, v244, v160
	ds_bpermute_b32 v237, v244, v161
	ds_bpermute_b32 v238, v244, v58
	ds_bpermute_b32 v239, v244, v59
	s_waitcnt lgkmcnt(0)
	global_store_dwordx2 v[236:237], v[238:239], off offset:8
	s_and_saveexec_b64 s[6:7], s[96:97]
	s_cbranch_execz .LBB0_1793
	v_mov_b64_e32 v[56:57], s[24:25]
	v_mad_i64_i32 v[56:57], s[58:59], v162, s76, v[56:57]
	v_lshl_add_u64 v[56:57], v[196:197], 2, v[56:57]
	global_store_dwordx4 v[56:57], v[52:55], off offset:16
	v_add_co_u32_e32 v56, vcc, 0x2000, v56
	s_nop 1
	v_addc_co_u32_e32 v57, vcc, 0, v57, vcc
	global_store_dwordx4 v[56:57], v[48:51], off offset:3088

; __device__ __forceinline__ unsigned pk2(float lo, float hi) { const f32x2 v = {lo, hi}; const bf16x2_t b = __builtin_convertvector(v, bf16x2_t); return __builtin_bit_cast(unsigned, b); }
; __device__ __forceinline__ f32x4 gelu_mul4(f32x4 x, f32x4 v) {
;     const f32x4 t = x * x;
;     const f32x4 u = t * (-2.0f * 0.7978845608028654f * 0.044715f * 1.4426950408889634f) + (-2.0f * 0.7978845608028654f * 1.4426950408889634f);
;     const f32x4 z = x * u;
;     f32x4 d; d[0] = __builtin_amdgcn_exp2f(z[0]); d[1] = __builtin_amdgcn_exp2f(z[1]); d[2] = __builtin_amdgcn_exp2f(z[2]); d[3] = __builtin_amdgcn_exp2f(z[3]);
;     d = d + 1.0f;
;     f32x4 r; r[0] = __builtin_amdgcn_rcpf(d[0]); r[1] = __builtin_amdgcn_rcpf(d[1]); r[2] = __builtin_amdgcn_rcpf(d[2]); r[3] = __builtin_amdgcn_rcpf(d[3]);
;     return (x * v) * r;
; }
;     __device__ __forceinline__ void operator()(const f32x4 (&acc)[2][2][4][2], const pg8::Unit& u, int wr, int wc, int fr, int fq, PG8_LAS unsigned char* xl) const {
;     ...
;                         cc[bj] = bb[bj] + w0[bj] * p2 + w1[bj] * p1 + w2[bj] * cur;
;                     }
;                     const f32x4 gv = gelu_mul4(cc[0], cc[1]);
;                     u32x2 w; w.x = pk2(gv[0], gv[1]); w.y = pk2(gv[2], gv[3]);
;                     *(u32x2*)(G + (size_t)row * FF + jc0 + 4 * n) = w;
;                     if (!sample && ai == 0 && wr == 0 && m == 0 && fr < 2 && (pm & 7) != 0) {
; #pragma unroll
;                         for (int bj = 0; bj < 2; ++bj) *(f32x4*)(PH + (size_t)(pm * 2 + fr) * FF2 + bj * FF + jc0 + 4 * n) = cc[bj];
;                     }
;                     if (sample && (fr & 3) >= 2) { const int b = (row - MP) >> 2, t = fr & 3;
; #pragma unroll
;                         for (int bj = 0; bj < 2; ++bj) *(f32x4*)(nf_s + (size_t)(b * 2 + t - 2) * FF2 + bj * FF + jc0 + 4 * n) = acc[ai][bj][m][n];
;                     }
.LBB0_1801:
	v_pk_fma_f32 v[48:49], v[98:99], v[62:63], v[102:103]
	v_pk_fma_f32 v[50:51], v[96:97], v[60:61], v[100:101]
	v_pk_fma_f32 v[48:49], v[90:91], v[58:59], v[48:49]
	v_pk_fma_f32 v[50:51], v[88:89], v[56:57], v[50:51]
	v_pk_fma_f32 v[48:49], v[46:47], v[82:83], v[48:49]
	v_pk_fma_f32 v[50:51], v[44:45], v[80:81], v[50:51]
	v_pk_fma_f32 v[56:57], v[86:87], v[66:67], v[94:95]
	v_pk_fma_f32 v[58:59], v[84:85], v[64:65], v[92:93]
	v_pk_fma_f32 v[54:55], v[78:79], v[54:55], v[56:57]
	v_pk_fma_f32 v[52:53], v[76:77], v[52:53], v[58:59]
	v_pk_mul_f32 v[56:57], v[48:49], v[48:49]
	v_pk_mul_f32 v[58:59], v[50:51], v[50:51]
	v_pk_fma_f32 v[56:57], v[56:57], s[82:83], v[246:247] op_sel_hi:[1,0,0]
	v_pk_fma_f32 v[58:59], v[58:59], s[82:83], v[246:247] op_sel_hi:[1,0,0]
	v_pk_mul_f32 v[56:57], v[48:49], v[56:57]
	v_pk_mul_f32 v[58:59], v[50:51], v[58:59]
	v_exp_f32_e32 v56, v56
	v_exp_f32_e32 v58, v58
	v_exp_f32_e32 v57, v57
	v_exp_f32_e32 v59, v59
	v_pk_fma_f32 v[54:55], v[42:43], v[74:75], v[54:55]
	v_pk_fma_f32 v[52:53], v[40:41], v[72:73], v[52:53]
	v_pk_add_f32 v[56:57], v[56:57], 1.0 op_sel_hi:[1,0]
	v_pk_add_f32 v[58:59], v[58:59], 1.0 op_sel_hi:[1,0]
	v_rcp_f32_e32 v56, v56
	v_rcp_f32_e32 v58, v58
	v_rcp_f32_e32 v57, v57
	v_rcp_f32_e32 v59, v59
	v_pk_mul_f32 v[48:49], v[48:49], v[54:55]
	v_pk_mul_f32 v[50:51], v[50:51], v[52:53]
	v_pk_mul_f32 v[48:49], v[48:49], v[56:57]
	v_pk_mul_f32 v[50:51], v[50:51], v[58:59]
	s_nop 0
	v_cvt_pk_bf16_f32 v50, v50, v51
	v_cvt_pk_bf16_f32 v51, v48, v49
	ds_bpermute_b32 v236, v244, v152
	ds_bpermute_b32 v237, v244, v153
	ds_bpermute_b32 v238, v244, v50
	ds_bpermute_b32 v239, v244, v51
	s_waitcnt lgkmcnt(0)
	global_store_dwordx2 v[236:237], v[238:239], off offset:8
	s_and_saveexec_b64 s[6:7], s[96:97]
	s_cbranch_execz .LBB0_1803
	v_mov_b64_e32 v[48:49], s[24:25]
	v_mad_i64_i32 v[48:49], s[58:59], v154, s76, v[48:49]
	v_lshl_add_u64 v[48:49], v[196:197], 2, v[48:49]
	global_store_dwordx4 v[48:49], v[44:47], off offset:16
	s_nop 1
	v_add_co_u32_e32 v44, vcc, 0x2000, v48
	s_nop 1
	v_addc_co_u32_e32 v45, vcc, 0, v49, vcc
	global_store_dwordx4 v[44:45], v[40:43], off offset:3088

; __device__ __forceinline__ unsigned pk2(float lo, float hi) { const f32x2 v = {lo, hi}; const bf16x2_t b = __builtin_convertvector(v, bf16x2_t); return __builtin_bit_cast(unsigned, b); }
; __device__ __forceinline__ f32x4 gelu_mul4(f32x4 x, f32x4 v) {
;     const f32x4 t = x * x;
;     const f32x4 u = t * (-2.0f * 0.7978845608028654f * 0.044715f * 1.4426950408889634f) + (-2.0f * 0.7978845608028654f * 1.4426950408889634f);
;     const f32x4 z = x * u;
;     f32x4 d; d[0] = __builtin_amdgcn_exp2f(z[0]); d[1] = __builtin_amdgcn_exp2f(z[1]); d[2] = __builtin_amdgcn_exp2f(z[2]); d[3] = __builtin_amdgcn_exp2f(z[3]);
;     d = d + 1.0f;
;     f32x4 r; r[0] = __builtin_amdgcn_rcpf(d[0]); r[1] = __builtin_amdgcn_rcpf(d[1]); r[2] = __builtin_amdgcn_rcpf(d[2]); r[3] = __builtin_amdgcn_rcpf(d[3]);
;     return (x * v) * r;
; }
;     __device__ __forceinline__ void operator()(const f32x4 (&acc)[2][2][4][2], const pg8::Unit& u, int wr, int wc, int fr, int fq, PG8_LAS unsigned char* xl) const {
;     ...
;                         cc[bj] = bb[bj] + w0[bj] * p2 + w1[bj] * p1 + w2[bj] * cur;
;                     }
;                     const f32x4 gv = gelu_mul4(cc[0], cc[1]);
;                     u32x2 w; w.x = pk2(gv[0], gv[1]); w.y = pk2(gv[2], gv[3]);
;                     *(u32x2*)(G + (size_t)row * FF + jc0 + 4 * n) = w;
;                     if (!sample && ai == 0 && wr == 0 && m == 0 && fr < 2 && (pm & 7) != 0) {
; #pragma unroll
;                         for (int bj = 0; bj < 2; ++bj) *(f32x4*)(PH + (size_t)(pm * 2 + fr) * FF2 + bj * FF + jc0 + 4 * n) = cc[bj];
;                     }
;                     if (sample && (fr & 3) >= 2) { const int b = (row - MP) >> 2, t = fr & 3;
; #pragma unroll
;                         for (int bj = 0; bj < 2; ++bj) *(f32x4*)(nf_s + (size_t)(b * 2 + t - 2) * FF2 + bj * FF + jc0 + 4 * n) = acc[ai][bj][m][n];
;                     }
.LBB0_1813:
	s_waitcnt lgkmcnt(0)
	v_pk_fma_f32 v[40:41], v[98:99], v[50:51], v[102:103]
	v_pk_fma_f32 v[42:43], v[96:97], v[48:49], v[100:101]
	v_pk_fma_f32 v[40:41], v[90:91], v[46:47], v[40:41]
	v_pk_fma_f32 v[42:43], v[88:89], v[44:45], v[42:43]
	v_pk_fma_f32 v[40:41], v[38:39], v[82:83], v[40:41]
	v_pk_fma_f32 v[42:43], v[36:37], v[80:81], v[42:43]
	v_pk_fma_f32 v[46:47], v[84:85], v[56:57], v[92:93]
	v_pk_mul_f32 v[48:49], v[40:41], v[40:41]
	v_pk_fma_f32 v[46:47], v[76:77], v[52:53], v[46:47]
	v_pk_mul_f32 v[50:51], v[42:43], v[42:43]
	v_pk_fma_f32 v[48:49], v[48:49], s[82:83], v[246:247] op_sel_hi:[1,0,0]
	v_pk_fma_f32 v[50:51], v[50:51], s[82:83], v[246:247] op_sel_hi:[1,0,0]
	v_pk_mul_f32 v[48:49], v[40:41], v[48:49]
	v_pk_mul_f32 v[50:51], v[42:43], v[50:51]
	v_exp_f32_e32 v48, v48
	v_exp_f32_e32 v50, v50
	v_exp_f32_e32 v49, v49
	v_exp_f32_e32 v51, v51
	v_pk_fma_f32 v[44:45], v[86:87], v[58:59], v[94:95]
	v_pk_fma_f32 v[46:47], v[32:33], v[72:73], v[46:47]
	v_pk_add_f32 v[48:49], v[48:49], 1.0 op_sel_hi:[1,0]
	v_pk_add_f32 v[50:51], v[50:51], 1.0 op_sel_hi:[1,0]
	v_rcp_f32_e32 v48, v48
	v_rcp_f32_e32 v50, v50
	v_rcp_f32_e32 v49, v49
	v_rcp_f32_e32 v51, v51
	v_pk_fma_f32 v[44:45], v[78:79], v[54:55], v[44:45]
	v_pk_mul_f32 v[42:43], v[42:43], v[46:47]
	v_pk_fma_f32 v[44:45], v[34:35], v[74:75], v[44:45]
	v_pk_mul_f32 v[42:43], v[42:43], v[50:51]
	v_pk_mul_f32 v[40:41], v[40:41], v[44:45]
	v_cvt_pk_bf16_f32 v42, v42, v43
	v_pk_mul_f32 v[40:41], v[40:41], v[48:49]
	s_nop 0
	v_cvt_pk_bf16_f32 v43, v40, v41
	ds_bpermute_b32 v236, v244, v144
	ds_bpermute_b32 v237, v244, v145
	ds_bpermute_b32 v238, v244, v42
	ds_bpermute_b32 v239, v244, v43
	s_waitcnt lgkmcnt(0)
	global_store_dwordx2 v[236:237], v[238:239], off offset:8
	s_and_saveexec_b64 s[6:7], s[96:97]
	s_cbranch_execz .LBB0_1815
	v_mov_b64_e32 v[40:41], s[24:25]
	v_mad_i64_i32 v[40:41], s[8:9], v146, s76, v[40:41]
	v_lshl_add_u64 v[40:41], v[196:197], 2, v[40:41]
	global_store_dwordx4 v[40:41], v[36:39], off offset:16
	v_add_co_u32_e32 v40, vcc, 0x2000, v40
	s_nop 1
	v_addc_co_u32_e32 v41, vcc, 0, v41, vcc
	global_store_dwordx4 v[40:41], v[32:35], off offset:3088

; __device__ __forceinline__ unsigned pk2(float lo, float hi) { const f32x2 v = {lo, hi}; const bf16x2_t b = __builtin_convertvector(v, bf16x2_t); return __builtin_bit_cast(unsigned, b); }
; __device__ __forceinline__ f32x4 gelu_mul4(f32x4 x, f32x4 v) {
;     const f32x4 t = x * x;
;     const f32x4 u = t * (-2.0f * 0.7978845608028654f * 0.044715f * 1.4426950408889634f) + (-2.0f * 0.7978845608028654f * 1.4426950408889634f);
;     const f32x4 z = x * u;
;     f32x4 d; d[0] = __builtin_amdgcn_exp2f(z[0]); d[1] = __builtin_amdgcn_exp2f(z[1]); d[2] = __builtin_amdgcn_exp2f(z[2]); d[3] = __builtin_amdgcn_exp2f(z[3]);
;     d = d + 1.0f;
;     f32x4 r; r[0] = __builtin_amdgcn_rcpf(d[0]); r[1] = __builtin_amdgcn_rcpf(d[1]); r[2] = __builtin_amdgcn_rcpf(d[2]); r[3] = __builtin_amdgcn_rcpf(d[3]);
;     return (x * v) * r;
; }
;     __device__ __forceinline__ void operator()(const f32x4 (&acc)[2][2][4][2], const pg8::Unit& u, int wr, int wc, int fr, int fq, PG8_LAS unsigned char* xl) const {
;     ...
;                         cc[bj] = bb[bj] + w0[bj] * p2 + w1[bj] * p1 + w2[bj] * cur;
;                     }
;                     const f32x4 gv = gelu_mul4(cc[0], cc[1]);
;                     u32x2 w; w.x = pk2(gv[0], gv[1]); w.y = pk2(gv[2], gv[3]);
;                     *(u32x2*)(G + (size_t)row * FF + jc0 + 4 * n) = w;
;                     if (!sample && ai == 0 && wr == 0 && m == 0 && fr < 2 && (pm & 7) != 0) {
; #pragma unroll
;                         for (int bj = 0; bj < 2; ++bj) *(f32x4*)(PH + (size_t)(pm * 2 + fr) * FF2 + bj * FF + jc0 + 4 * n) = cc[bj];
;                     }
;                     if (sample && (fr & 3) >= 2) { const int b = (row - MP) >> 2, t = fr & 3;
; #pragma unroll
;                         for (int bj = 0; bj < 2; ++bj) *(f32x4*)(nf_s + (size_t)(b * 2 + t - 2) * FF2 + bj * FF + jc0 + 4 * n) = acc[ai][bj][m][n];
;                     }
.LBB0_1823:
	v_pk_fma_f32 v[32:33], v[98:99], v[46:47], v[102:103]
	v_pk_fma_f32 v[34:35], v[96:97], v[44:45], v[100:101]
	v_pk_fma_f32 v[32:33], v[90:91], v[42:43], v[32:33]
	v_pk_fma_f32 v[34:35], v[88:89], v[40:41], v[34:35]
	v_pk_fma_f32 v[32:33], v[30:31], v[82:83], v[32:33]
	v_pk_fma_f32 v[34:35], v[28:29], v[80:81], v[34:35]
	v_pk_fma_f32 v[40:41], v[86:87], v[50:51], v[94:95]
	v_pk_fma_f32 v[42:43], v[84:85], v[48:49], v[92:93]
	v_pk_fma_f32 v[38:39], v[78:79], v[38:39], v[40:41]
	v_pk_fma_f32 v[36:37], v[76:77], v[36:37], v[42:43]
	v_pk_mul_f32 v[40:41], v[32:33], v[32:33]
	v_pk_mul_f32 v[42:43], v[34:35], v[34:35]
	v_pk_fma_f32 v[40:41], v[40:41], s[82:83], v[246:247] op_sel_hi:[1,0,0]
	v_pk_fma_f32 v[42:43], v[42:43], s[82:83], v[246:247] op_sel_hi:[1,0,0]
	v_pk_mul_f32 v[40:41], v[32:33], v[40:41]
	v_pk_mul_f32 v[42:43], v[34:35], v[42:43]
	v_exp_f32_e32 v40, v40
	v_exp_f32_e32 v42, v42
	v_exp_f32_e32 v41, v41
	v_exp_f32_e32 v43, v43
	v_pk_fma_f32 v[38:39], v[26:27], v[74:75], v[38:39]
	v_pk_fma_f32 v[36:37], v[24:25], v[72:73], v[36:37]
	v_pk_add_f32 v[40:41], v[40:41], 1.0 op_sel_hi:[1,0]
	v_pk_add_f32 v[42:43], v[42:43], 1.0 op_sel_hi:[1,0]
	v_rcp_f32_e32 v40, v40
	v_rcp_f32_e32 v42, v42
	v_rcp_f32_e32 v41, v41
	v_rcp_f32_e32 v43, v43
	v_pk_mul_f32 v[32:33], v[32:33], v[38:39]
	v_pk_mul_f32 v[34:35], v[34:35], v[36:37]
	v_pk_mul_f32 v[32:33], v[32:33], v[40:41]
	v_pk_mul_f32 v[34:35], v[34:35], v[42:43]
	s_nop 0
	v_cvt_pk_bf16_f32 v34, v34, v35
	v_cvt_pk_bf16_f32 v35, v32, v33
	ds_bpermute_b32 v236, v244, v136
	ds_bpermute_b32 v237, v244, v137
	ds_bpermute_b32 v238, v244, v34
	ds_bpermute_b32 v239, v244, v35
	s_waitcnt lgkmcnt(0)
	global_store_dwordx2 v[236:237], v[238:239], off offset:8
	s_and_saveexec_b64 s[6:7], s[96:97]
	s_cbranch_execz .LBB0_1825
	v_mov_b64_e32 v[32:33], s[24:25]
	v_mad_i64_i32 v[32:33], s[8:9], v138, s76, v[32:33]
	v_lshl_add_u64 v[32:33], v[196:197], 2, v[32:33]
	global_store_dwordx4 v[32:33], v[28:31], off offset:16
	v_add_co_u32_e32 v32, vcc, 0x2000, v32
	s_nop 1
	v_addc_co_u32_e32 v33, vcc, 0, v33, vcc
	global_store_dwordx4 v[32:33], v[24:27], off offset:3088

; __device__ __forceinline__ unsigned pk2(float lo, float hi) { const f32x2 v = {lo, hi}; const bf16x2_t b = __builtin_convertvector(v, bf16x2_t); return __builtin_bit_cast(unsigned, b); }
; __device__ __forceinline__ f32x4 gelu_mul4(f32x4 x, f32x4 v) {
;     const f32x4 t = x * x;
;     const f32x4 u = t * (-2.0f * 0.7978845608028654f * 0.044715f * 1.4426950408889634f) + (-2.0f * 0.7978845608028654f * 1.4426950408889634f);
;     const f32x4 z = x * u;
;     f32x4 d; d[0] = __builtin_amdgcn_exp2f(z[0]); d[1] = __builtin_amdgcn_exp2f(z[1]); d[2] = __builtin_amdgcn_exp2f(z[2]); d[3] = __builtin_amdgcn_exp2f(z[3]);
;     d = d + 1.0f;
;     f32x4 r; r[0] = __builtin_amdgcn_rcpf(d[0]); r[1] = __builtin_amdgcn_rcpf(d[1]); r[2] = __builtin_amdgcn_rcpf(d[2]); r[3] = __builtin_amdgcn_rcpf(d[3]);
;     return (x * v) * r;
; }
;     __device__ __forceinline__ void operator()(const f32x4 (&acc)[2][2][4][2], const pg8::Unit& u, int wr, int wc, int fr, int fq, PG8_LAS unsigned char* xl) const {
;     ...
;                         cc[bj] = bb[bj] + w0[bj] * p2 + w1[bj] * p1 + w2[bj] * cur;
;                     }
;                     const f32x4 gv = gelu_mul4(cc[0], cc[1]);
;                     u32x2 w; w.x = pk2(gv[0], gv[1]); w.y = pk2(gv[2], gv[3]);
;                     *(u32x2*)(G + (size_t)row * FF + jc0 + 4 * n) = w;
;                     if (!sample && ai == 0 && wr == 0 && m == 0 && fr < 2 && (pm & 7) != 0) {
; #pragma unroll
;                         for (int bj = 0; bj < 2; ++bj) *(f32x4*)(PH + (size_t)(pm * 2 + fr) * FF2 + bj * FF + jc0 + 4 * n) = cc[bj];
;                     }
;                     if (sample && (fr & 3) >= 2) { const int b = (row - MP) >> 2, t = fr & 3;
; #pragma unroll
;                         for (int bj = 0; bj < 2; ++bj) *(f32x4*)(nf_s + (size_t)(b * 2 + t - 2) * FF2 + bj * FF + jc0 + 4 * n) = acc[ai][bj][m][n];
;                     }
.LBB0_1833:
	v_pk_fma_f32 v[24:25], v[98:99], v[38:39], v[102:103]
	v_pk_fma_f32 v[26:27], v[96:97], v[36:37], v[100:101]
	v_pk_fma_f32 v[24:25], v[90:91], v[34:35], v[24:25]
	v_pk_fma_f32 v[26:27], v[88:89], v[32:33], v[26:27]
	v_pk_fma_f32 v[24:25], v[22:23], v[82:83], v[24:25]
	v_pk_fma_f32 v[26:27], v[20:21], v[80:81], v[26:27]
	v_pk_fma_f32 v[32:33], v[86:87], v[42:43], v[94:95]
	v_pk_fma_f32 v[34:35], v[84:85], v[40:41], v[92:93]
	v_pk_fma_f32 v[30:31], v[78:79], v[30:31], v[32:33]
	v_pk_fma_f32 v[28:29], v[76:77], v[28:29], v[34:35]
	v_pk_mul_f32 v[32:33], v[24:25], v[24:25]
	v_pk_mul_f32 v[34:35], v[26:27], v[26:27]
	v_pk_fma_f32 v[32:33], v[32:33], s[82:83], v[246:247] op_sel_hi:[1,0,0]
	v_pk_fma_f32 v[34:35], v[34:35], s[82:83], v[246:247] op_sel_hi:[1,0,0]
	v_pk_mul_f32 v[32:33], v[24:25], v[32:33]
	v_pk_mul_f32 v[34:35], v[26:27], v[34:35]
	v_exp_f32_e32 v32, v32
	v_exp_f32_e32 v34, v34
	v_exp_f32_e32 v33, v33
	v_exp_f32_e32 v35, v35
	v_pk_fma_f32 v[30:31], v[18:19], v[74:75], v[30:31]
	v_pk_fma_f32 v[28:29], v[16:17], v[72:73], v[28:29]
	v_pk_add_f32 v[32:33], v[32:33], 1.0 op_sel_hi:[1,0]
	v_pk_add_f32 v[34:35], v[34:35], 1.0 op_sel_hi:[1,0]
	v_rcp_f32_e32 v32, v32
	v_rcp_f32_e32 v34, v34
	v_rcp_f32_e32 v33, v33
	v_rcp_f32_e32 v35, v35
	v_pk_mul_f32 v[24:25], v[24:25], v[30:31]
	v_pk_mul_f32 v[26:27], v[26:27], v[28:29]
	v_pk_mul_f32 v[24:25], v[24:25], v[32:33]
	v_pk_mul_f32 v[26:27], v[26:27], v[34:35]
	s_nop 0
	v_cvt_pk_bf16_f32 v26, v26, v27
	v_cvt_pk_bf16_f32 v27, v24, v25
	ds_bpermute_b32 v236, v244, v128
	ds_bpermute_b32 v237, v244, v129
	ds_bpermute_b32 v238, v244, v26
	ds_bpermute_b32 v239, v244, v27
	s_waitcnt lgkmcnt(0)
	global_store_dwordx2 v[236:237], v[238:239], off offset:8
	s_and_saveexec_b64 s[6:7], s[96:97]
	s_cbranch_execz .LBB0_1835
	v_mov_b64_e32 v[24:25], s[24:25]
	v_mad_i64_i32 v[24:25], s[8:9], v139, s76, v[24:25]
	v_lshl_add_u64 v[24:25], v[196:197], 2, v[24:25]
	global_store_dwordx4 v[24:25], v[20:23], off offset:16
	v_add_co_u32_e32 v24, vcc, 0x2000, v24
	s_nop 1
	v_addc_co_u32_e32 v25, vcc, 0, v25, vcc
	global_store_dwordx4 v[24:25], v[16:19], off offset:3088

; __device__ __forceinline__ unsigned pk2(float lo, float hi) { const f32x2 v = {lo, hi}; const bf16x2_t b = __builtin_convertvector(v, bf16x2_t); return __builtin_bit_cast(unsigned, b); }
; __device__ __forceinline__ f32x4 gelu_mul4(f32x4 x, f32x4 v) {
;     const f32x4 t = x * x;
;     const f32x4 u = t * (-2.0f * 0.7978845608028654f * 0.044715f * 1.4426950408889634f) + (-2.0f * 0.7978845608028654f * 1.4426950408889634f);
;     const f32x4 z = x * u;
;     f32x4 d; d[0] = __builtin_amdgcn_exp2f(z[0]); d[1] = __builtin_amdgcn_exp2f(z[1]); d[2] = __builtin_amdgcn_exp2f(z[2]); d[3] = __builtin_amdgcn_exp2f(z[3]);
;     d = d + 1.0f;
;     f32x4 r; r[0] = __builtin_amdgcn_rcpf(d[0]); r[1] = __builtin_amdgcn_rcpf(d[1]); r[2] = __builtin_amdgcn_rcpf(d[2]); r[3] = __builtin_amdgcn_rcpf(d[3]);
;     return (x * v) * r;
; }
;     __device__ __forceinline__ void operator()(const f32x4 (&acc)[2][2][4][2], const pg8::Unit& u, int wr, int wc, int fr, int fq, PG8_LAS unsigned char* xl) const {
;     ...
;                         cc[bj] = bb[bj] + w0[bj] * p2 + w1[bj] * p1 + w2[bj] * cur;
;                     }
;                     const f32x4 gv = gelu_mul4(cc[0], cc[1]);
;                     u32x2 w; w.x = pk2(gv[0], gv[1]); w.y = pk2(gv[2], gv[3]);
;                     *(u32x2*)(G + (size_t)row * FF + jc0 + 4 * n) = w;
;                     if (!sample && ai == 0 && wr == 0 && m == 0 && fr < 2 && (pm & 7) != 0) {
; #pragma unroll
;                         for (int bj = 0; bj < 2; ++bj) *(f32x4*)(PH + (size_t)(pm * 2 + fr) * FF2 + bj * FF + jc0 + 4 * n) = cc[bj];
;                     }
;                     if (sample && (fr & 3) >= 2) { const int b = (row - MP) >> 2, t = fr & 3;
; #pragma unroll
;                         for (int bj = 0; bj < 2; ++bj) *(f32x4*)(nf_s + (size_t)(b * 2 + t - 2) * FF2 + bj * FF + jc0 + 4 * n) = acc[ai][bj][m][n];
;                     }
.LBB0_1843:
	v_pk_fma_f32 v[16:17], v[98:99], v[30:31], v[102:103]
	v_pk_fma_f32 v[18:19], v[96:97], v[28:29], v[100:101]
	v_pk_fma_f32 v[16:17], v[90:91], v[26:27], v[16:17]
	v_pk_fma_f32 v[18:19], v[88:89], v[24:25], v[18:19]
	v_pk_fma_f32 v[16:17], v[10:11], v[82:83], v[16:17]
	v_pk_fma_f32 v[18:19], v[8:9], v[80:81], v[18:19]
	v_pk_fma_f32 v[24:25], v[86:87], v[34:35], v[94:95]
	v_pk_fma_f32 v[26:27], v[84:85], v[32:33], v[92:93]
	v_pk_fma_f32 v[22:23], v[78:79], v[22:23], v[24:25]
	v_pk_fma_f32 v[20:21], v[76:77], v[20:21], v[26:27]
	v_pk_mul_f32 v[24:25], v[16:17], v[16:17]
	v_pk_mul_f32 v[26:27], v[18:19], v[18:19]
	v_pk_fma_f32 v[24:25], v[24:25], s[82:83], v[246:247] op_sel_hi:[1,0,0]
	v_pk_fma_f32 v[26:27], v[26:27], s[82:83], v[246:247] op_sel_hi:[1,0,0]
	v_pk_mul_f32 v[24:25], v[16:17], v[24:25]
	v_pk_mul_f32 v[26:27], v[18:19], v[26:27]
	v_exp_f32_e32 v24, v24
	v_exp_f32_e32 v26, v26
	v_exp_f32_e32 v25, v25
	v_exp_f32_e32 v27, v27
	v_pk_fma_f32 v[22:23], v[2:3], v[74:75], v[22:23]
	v_pk_fma_f32 v[20:21], v[0:1], v[72:73], v[20:21]
	v_pk_add_f32 v[24:25], v[24:25], 1.0 op_sel_hi:[1,0]
	v_pk_add_f32 v[26:27], v[26:27], 1.0 op_sel_hi:[1,0]
	v_rcp_f32_e32 v24, v24
	v_rcp_f32_e32 v26, v26
	v_rcp_f32_e32 v25, v25
	v_rcp_f32_e32 v27, v27
	v_pk_mul_f32 v[16:17], v[16:17], v[22:23]
	v_pk_mul_f32 v[18:19], v[18:19], v[20:21]
	v_pk_mul_f32 v[16:17], v[16:17], v[24:25]
	v_pk_mul_f32 v[18:19], v[18:19], v[26:27]
	s_nop 0
	v_cvt_pk_bf16_f32 v18, v18, v19
	v_cvt_pk_bf16_f32 v19, v16, v17
	ds_bpermute_b32 v236, v244, v130
	ds_bpermute_b32 v237, v244, v131
	ds_bpermute_b32 v238, v244, v18
	ds_bpermute_b32 v239, v244, v19
	s_waitcnt lgkmcnt(0)
	global_store_dwordx2 v[236:237], v[238:239], off offset:8
	s_and_saveexec_b64 s[6:7], s[96:97]
	s_cbranch_execz .LBB0_1845
	v_mov_b64_e32 v[16:17], s[24:25]
	v_mad_i64_i32 v[16:17], s[8:9], v147, s76, v[16:17]
	v_lshl_add_u64 v[16:17], v[196:197], 2, v[16:17]
	global_store_dwordx4 v[16:17], v[8:11], off offset:16
	v_add_co_u32_e32 v16, vcc, 0x2000, v16
	s_nop 1
	v_addc_co_u32_e32 v17, vcc, 0, v17, vcc
	global_store_dwordx4 v[16:17], v[0:3], off offset:3088

; __global__ void __launch_bounds__(512, 2) fwd_megakernel(Args a_unused) {
	.amdhsa_kernel _Z14fwd_megakernel4Args
		.amdhsa_group_segment_fixed_size 0
		.amdhsa_private_segment_fixed_size 0
		.amdhsa_kernarg_size 432
		.amdhsa_user_sgpr_count 2
		.amdhsa_user_sgpr_dispatch_ptr 0
		.amdhsa_user_sgpr_queue_ptr 0
		.amdhsa_user_sgpr_kernarg_segment_ptr 1
		.amdhsa_user_sgpr_dispatch_id 0
		.amdhsa_user_sgpr_kernarg_preload_length 0
		.amdhsa_user_sgpr_kernarg_preload_offset 0
		.amdhsa_user_sgpr_private_segment_size 0
		.amdhsa_uses_dynamic_stack 0
		.amdhsa_enable_private_segment 0
		.amdhsa_system_sgpr_workgroup_id_x 1
		.amdhsa_system_sgpr_workgroup_id_y 0
		.amdhsa_system_sgpr_workgroup_id_z 0
		.amdhsa_system_sgpr_workgroup_info 0
		.amdhsa_system_vgpr_workitem_id 2
		.amdhsa_next_free_vgpr 248
		.amdhsa_next_free_sgpr 102
		.amdhsa_accum_offset 248
		.amdhsa_reserve_vcc 1
		.amdhsa_float_round_mode_32 0
		.amdhsa_float_round_mode_16_64 0
		.amdhsa_float_denorm_mode_32 3
		.amdhsa_float_denorm_mode_16_64 3
		.amdhsa_dx10_clamp 1
		.amdhsa_ieee_mode 1
		.amdhsa_fp16_overflow 0
		.amdhsa_tg_split 0
		.amdhsa_exception_fp_ieee_invalid_op 0
		.amdhsa_exception_fp_denorm_src 0
		.amdhsa_exception_fp_ieee_div_zero 0
		.amdhsa_exception_fp_ieee_overflow 0
		.amdhsa_exception_fp_ieee_underflow 0
		.amdhsa_exception_fp_ieee_inexact 0
		.amdhsa_exception_int_div_zero 0
	.end_amdhsa_kernel

; __global__ void __launch_bounds__(512, 2) fwd_megakernel(Args a_unused) {
amdhsa.kernels:
  - .agpr_count:     0
    .args:
      - .offset:         0
        .size:           176
        .value_kind:     by_value
      - .offset:         176
        .size:           4
        .value_kind:     hidden_block_count_x
      - .offset:         180
        .size:           4
        .value_kind:     hidden_block_count_y
      - .offset:         184
        .size:           4
        .value_kind:     hidden_block_count_z
      - .offset:         188
        .size:           2
        .value_kind:     hidden_group_size_x
      - .offset:         190
        .size:           2
        .value_kind:     hidden_group_size_y
      - .offset:         192
        .size:           2
        .value_kind:     hidden_group_size_z
      - .offset:         194
        .size:           2
        .value_kind:     hidden_remainder_x
      - .offset:         196
        .size:           2
        .value_kind:     hidden_remainder_y
      - .offset:         198
        .size:           2
        .value_kind:     hidden_remainder_z
      - .offset:         216
        .size:           8
        .value_kind:     hidden_global_offset_x
      - .offset:         224
        .size:           8
        .value_kind:     hidden_global_offset_y
      - .offset:         232
        .size:           8
        .value_kind:     hidden_global_offset_z
      - .offset:         240
        .size:           2
        .value_kind:     hidden_grid_dims
      - .offset:         264
        .size:           8
        .value_kind:     hidden_multigrid_sync_arg
      - .offset:         296
        .size:           4
        .value_kind:     hidden_dynamic_lds_size
    .group_segment_fixed_size: 0
    .kernarg_segment_align: 8
    .kernarg_segment_size: 432
    .language:       OpenCL C
    .language_version:
      - 2
      - 0
    .max_flat_workgroup_size: 512
    .name:           _Z14fwd_megakernel4Args
    .private_segment_fixed_size: 0
    .sgpr_count:     108
    .sgpr_spill_count: 80
    .symbol:         _Z14fwd_megakernel4Args.kd
    .uniform_work_group_size: 1
    .uses_dynamic_stack: false
    .vgpr_count:     248
    .vgpr_spill_count: 0
    .wavefront_size: 64
